# K-loops: the m0-write -> LDS-DMA wait state is filled by the address add instead of s_nop (99 sites)
# baseline (speedup 1.0000x reference)
.LBB0_111:
	s_add_u32 s28, s26, 0xfffc0080
	s_addc_u32 s29, s27, -1
	s_add_i32 s57, 0, 0x10000
	s_cmp_eq_u32 s56, 12
	s_cselect_b32 s31, s19, s29
	s_cselect_b32 s30, s52, s28
	v_add_u32_e32 v150, s57, v1
	s_cselect_b32 s29, s17, s55
	s_cselect_b32 s28, s53, s54
	s_add_i32 s60, 0, 0x14000
	ds_read_b128 v[142:145], v150
	ds_read_b128 v[146:149], v150 offset:1024
	ds_read_b128 v[154:157], v150 offset:2048
	ds_read_b128 v[158:161], v150 offset:3072
	v_add_u32_e32 v150, s60, v1
	s_nop 0
	ds_read_b128 v[162:165], v150
	ds_read_b128 v[166:169], v150 offset:1024
	ds_read_b128 v[170:173], v150 offset:2048
	ds_read_b128 v[174:177], v150 offset:3072
	v_lshl_add_u64 v[150:151], s[26:27], 0, v[138:139]
	s_add_i32 m0, s43, 0xc000
	ds_read_b128 v[178:181], v152
	ds_read_b128 v[182:185], v152 offset:1024
	ds_read_b128 v[186:189], v152 offset:2048
	ds_read_b128 v[190:193], v152 offset:3072
	ds_read_b128 v[204:207], v152 offset:4096
	ds_read_b128 v[208:211], v152 offset:5120
	ds_read_b128 v[212:215], v152 offset:6144
	ds_read_b128 v[228:231], v152 offset:7168
	global_load_lds_dwordx4 v[150:151], off
	s_add_i32 m0, s43, 0xe000
	v_lshl_add_u64 v[150:151], s[26:27], 0, v[140:141]
	global_load_lds_dwordx4 v[150:151], off
	s_waitcnt vmcnt(8)
	s_waitcnt lgkmcnt(0)
	s_barrier
	s_setprio 1
	s_waitcnt lgkmcnt(0)
	v_mfma_f32_16x16x32_bf16 v[126:129], v[142:145], v[178:181], v[126:129]
	v_mfma_f32_16x16x32_bf16 v[122:125], v[154:157], v[178:181], v[122:125]
	v_mfma_f32_16x16x32_bf16 v[110:113], v[142:145], v[186:189], v[110:113]
	v_mfma_f32_16x16x32_bf16 v[106:109], v[154:157], v[186:189], v[106:109]
	v_mfma_f32_16x16x32_bf16 v[94:97], v[142:145], v[204:207], v[94:97]
	v_mfma_f32_16x16x32_bf16 v[90:93], v[154:157], v[204:207], v[90:93]
	v_mfma_f32_16x16x32_bf16 v[78:81], v[142:145], v[212:215], v[78:81]
	v_mfma_f32_16x16x32_bf16 v[74:77], v[154:157], v[212:215], v[74:77]
	v_mfma_f32_16x16x32_bf16 v[126:129], v[146:149], v[182:185], v[126:129]
	v_mfma_f32_16x16x32_bf16 v[122:125], v[158:161], v[182:185], v[122:125]
	v_mfma_f32_16x16x32_bf16 v[110:113], v[146:149], v[190:193], v[110:113]
	v_mfma_f32_16x16x32_bf16 v[106:109], v[158:161], v[190:193], v[106:109]
	v_mfma_f32_16x16x32_bf16 v[94:97], v[146:149], v[208:211], v[94:97]
	v_mfma_f32_16x16x32_bf16 v[90:93], v[158:161], v[208:211], v[90:93]
	v_mfma_f32_16x16x32_bf16 v[78:81], v[146:149], v[228:231], v[78:81]
	v_mfma_f32_16x16x32_bf16 v[74:77], v[158:161], v[228:231], v[74:77]
	v_mfma_f32_16x16x32_bf16 v[118:121], v[162:165], v[178:181], v[118:121]
	v_mfma_f32_16x16x32_bf16 v[114:117], v[170:173], v[178:181], v[114:117]
	v_mfma_f32_16x16x32_bf16 v[102:105], v[162:165], v[186:189], v[102:105]
	v_mfma_f32_16x16x32_bf16 v[98:101], v[170:173], v[186:189], v[98:101]
	v_mfma_f32_16x16x32_bf16 v[86:89], v[162:165], v[204:207], v[86:89]
	v_mfma_f32_16x16x32_bf16 v[82:85], v[170:173], v[204:207], v[82:85]
	v_mfma_f32_16x16x32_bf16 v[70:73], v[162:165], v[212:215], v[70:73]
	v_mfma_f32_16x16x32_bf16 v[66:69], v[170:173], v[212:215], v[66:69]
	v_mfma_f32_16x16x32_bf16 v[118:121], v[166:169], v[182:185], v[118:121]
	v_mfma_f32_16x16x32_bf16 v[114:117], v[174:177], v[182:185], v[114:117]
	v_mfma_f32_16x16x32_bf16 v[102:105], v[166:169], v[190:193], v[102:105]
	v_mfma_f32_16x16x32_bf16 v[98:101], v[174:177], v[190:193], v[98:101]
	v_mfma_f32_16x16x32_bf16 v[86:89], v[166:169], v[208:211], v[86:89]
	v_mfma_f32_16x16x32_bf16 v[82:85], v[174:177], v[208:211], v[82:85]
	v_mfma_f32_16x16x32_bf16 v[70:73], v[166:169], v[228:231], v[70:73]
	v_mfma_f32_16x16x32_bf16 v[66:69], v[174:177], v[228:231], v[66:69]
	s_setprio 0
	s_barrier
	s_add_i32 s57, s57, s42
	v_lshl_add_u64 v[150:151], s[28:29], 0, v[134:135]
	s_mov_b32 m0, s57
	ds_read_b128 v[178:181], v152 offset:16384
	ds_read_b128 v[182:185], v152 offset:17408
	ds_read_b128 v[186:189], v152 offset:18432
	ds_read_b128 v[190:193], v152 offset:19456
	ds_read_b128 v[204:207], v152 offset:20480
	ds_read_b128 v[208:211], v152 offset:21504
	ds_read_b128 v[212:215], v152 offset:22528
	ds_read_b128 v[228:231], v152 offset:23552
	global_load_lds_dwordx4 v[150:151], off
	s_add_i32 m0, s57, 0x2000
	s_add_u32 s58, s28, 0x40000
	v_lshl_add_u64 v[194:195], s[28:29], 0, v[130:131]
	s_addc_u32 s59, s29, 0
	s_add_i32 s57, s60, s42
	global_load_lds_dwordx4 v[194:195], off
	v_lshl_add_u64 v[216:217], s[58:59], 0, v[134:135]
	s_mov_b32 m0, s57
	v_lshl_add_u64 v[232:233], s[30:31], 0, v[132:133]
	global_load_lds_dwordx4 v[216:217], off
	s_add_i32 m0, s57, 0x2000
	v_lshl_add_u64 v[216:217], s[58:59], 0, v[130:131]
	global_load_lds_dwordx4 v[216:217], off
	s_mov_b32 m0, s43
	v_lshl_add_u64 v[216:217], s[30:31], 0, v[136:137]
	global_load_lds_dwordx4 v[216:217], off
	s_mov_b32 m0, s44
	s_nop 0
	global_load_lds_dwordx4 v[232:233], off
	s_waitcnt vmcnt(8)
	s_waitcnt lgkmcnt(0)
	s_barrier
	s_setprio 1
	s_waitcnt lgkmcnt(0)
	v_mfma_f32_16x16x32_bf16 v[62:65], v[142:145], v[178:181], v[62:65]
	v_mfma_f32_16x16x32_bf16 v[58:61], v[154:157], v[178:181], v[58:61]
	v_mfma_f32_16x16x32_bf16 v[46:49], v[142:145], v[186:189], v[46:49]
	v_mfma_f32_16x16x32_bf16 v[42:45], v[154:157], v[186:189], v[42:45]
	v_mfma_f32_16x16x32_bf16 v[30:33], v[142:145], v[204:207], v[30:33]
	v_mfma_f32_16x16x32_bf16 v[26:29], v[154:157], v[204:207], v[26:29]
	v_mfma_f32_16x16x32_bf16 v[14:17], v[142:145], v[212:215], v[14:17]
	v_mfma_f32_16x16x32_bf16 v[10:13], v[154:157], v[212:215], v[10:13]
	v_mfma_f32_16x16x32_bf16 v[62:65], v[146:149], v[182:185], v[62:65]
	v_mfma_f32_16x16x32_bf16 v[58:61], v[158:161], v[182:185], v[58:61]
	v_mfma_f32_16x16x32_bf16 v[46:49], v[146:149], v[190:193], v[46:49]
	v_mfma_f32_16x16x32_bf16 v[42:45], v[158:161], v[190:193], v[42:45]
	v_mfma_f32_16x16x32_bf16 v[30:33], v[146:149], v[208:211], v[30:33]
	v_mfma_f32_16x16x32_bf16 v[26:29], v[158:161], v[208:211], v[26:29]
	v_mfma_f32_16x16x32_bf16 v[14:17], v[146:149], v[228:231], v[14:17]
	v_mfma_f32_16x16x32_bf16 v[10:13], v[158:161], v[228:231], v[10:13]
	v_mfma_f32_16x16x32_bf16 v[54:57], v[162:165], v[178:181], v[54:57]
	v_mfma_f32_16x16x32_bf16 v[50:53], v[170:173], v[178:181], v[50:53]
	v_mfma_f32_16x16x32_bf16 v[38:41], v[162:165], v[186:189], v[38:41]
	v_mfma_f32_16x16x32_bf16 v[34:37], v[170:173], v[186:189], v[34:37]
	v_mfma_f32_16x16x32_bf16 v[22:25], v[162:165], v[204:207], v[22:25]
	v_mfma_f32_16x16x32_bf16 v[18:21], v[170:173], v[204:207], v[18:21]
	v_mfma_f32_16x16x32_bf16 v[6:9], v[162:165], v[212:215], v[6:9]
	v_mfma_f32_16x16x32_bf16 v[2:5], v[170:173], v[212:215], v[2:5]
	v_mfma_f32_16x16x32_bf16 v[54:57], v[166:169], v[182:185], v[54:57]
	v_mfma_f32_16x16x32_bf16 v[50:53], v[174:177], v[182:185], v[50:53]
	v_mfma_f32_16x16x32_bf16 v[38:41], v[166:169], v[190:193], v[38:41]
	v_mfma_f32_16x16x32_bf16 v[34:37], v[174:177], v[190:193], v[34:37]
	v_mfma_f32_16x16x32_bf16 v[22:25], v[166:169], v[208:211], v[22:25]
	v_mfma_f32_16x16x32_bf16 v[18:21], v[174:177], v[208:211], v[18:21]
	v_mfma_f32_16x16x32_bf16 v[6:9], v[166:169], v[228:231], v[6:9]
	v_mfma_f32_16x16x32_bf16 v[2:5], v[174:177], v[228:231], v[2:5]
	s_setprio 0
	s_barrier
	s_add_i32 s57, 0, 0x18000
	v_add_u32_e32 v153, s57, v1
	s_add_i32 s58, 0, 0x1c000
	ds_read_b128 v[142:145], v153
	ds_read_b128 v[146:149], v153 offset:1024
	ds_read_b128 v[154:157], v153 offset:2048
	ds_read_b128 v[158:161], v153 offset:3072
	v_add_u32_e32 v153, s58, v1
	ds_read_b128 v[162:165], v153
	ds_read_b128 v[166:169], v153 offset:1024
	ds_read_b128 v[170:173], v153 offset:2048
	ds_read_b128 v[174:177], v153 offset:3072
	s_add_u32 s30, s30, 0x40000
	s_addc_u32 s31, s31, 0
	s_mov_b32 m0, s45
	v_lshl_add_u64 v[234:235], s[30:31], 0, v[136:137]
	ds_read_b128 v[178:181], v152 offset:32768
	ds_read_b128 v[182:185], v152 offset:33792
	ds_read_b128 v[186:189], v152 offset:34816
	ds_read_b128 v[190:193], v152 offset:35840
	ds_read_b128 v[204:207], v152 offset:36864
	ds_read_b128 v[208:211], v152 offset:37888
	ds_read_b128 v[212:215], v152 offset:38912
	ds_read_b128 v[228:231], v152 offset:39936
	global_load_lds_dwordx4 v[234:235], off
	s_mov_b32 m0, s46
	v_lshl_add_u64 v[234:235], s[30:31], 0, v[132:133]
	global_load_lds_dwordx4 v[234:235], off
	s_waitcnt vmcnt(8)
	s_waitcnt lgkmcnt(0)
	s_barrier
	s_setprio 1
	s_waitcnt lgkmcnt(0)
	v_mfma_f32_16x16x32_bf16 v[126:129], v[142:145], v[178:181], v[126:129]
	v_mfma_f32_16x16x32_bf16 v[122:125], v[154:157], v[178:181], v[122:125]
	v_mfma_f32_16x16x32_bf16 v[110:113], v[142:145], v[186:189], v[110:113]
	v_mfma_f32_16x16x32_bf16 v[106:109], v[154:157], v[186:189], v[106:109]
	v_mfma_f32_16x16x32_bf16 v[94:97], v[142:145], v[204:207], v[94:97]
	v_mfma_f32_16x16x32_bf16 v[90:93], v[154:157], v[204:207], v[90:93]
	v_mfma_f32_16x16x32_bf16 v[78:81], v[142:145], v[212:215], v[78:81]
	v_mfma_f32_16x16x32_bf16 v[74:77], v[154:157], v[212:215], v[74:77]
	v_mfma_f32_16x16x32_bf16 v[126:129], v[146:149], v[182:185], v[126:129]
	v_mfma_f32_16x16x32_bf16 v[122:125], v[158:161], v[182:185], v[122:125]
	v_mfma_f32_16x16x32_bf16 v[110:113], v[146:149], v[190:193], v[110:113]
	v_mfma_f32_16x16x32_bf16 v[106:109], v[158:161], v[190:193], v[106:109]
	v_mfma_f32_16x16x32_bf16 v[94:97], v[146:149], v[208:211], v[94:97]
	v_mfma_f32_16x16x32_bf16 v[90:93], v[158:161], v[208:211], v[90:93]
	v_mfma_f32_16x16x32_bf16 v[78:81], v[146:149], v[228:231], v[78:81]
	v_mfma_f32_16x16x32_bf16 v[74:77], v[158:161], v[228:231], v[74:77]
	v_mfma_f32_16x16x32_bf16 v[118:121], v[162:165], v[178:181], v[118:121]
	v_mfma_f32_16x16x32_bf16 v[114:117], v[170:173], v[178:181], v[114:117]
	v_mfma_f32_16x16x32_bf16 v[102:105], v[162:165], v[186:189], v[102:105]
	v_mfma_f32_16x16x32_bf16 v[98:101], v[170:173], v[186:189], v[98:101]
	v_mfma_f32_16x16x32_bf16 v[86:89], v[162:165], v[204:207], v[86:89]
	v_mfma_f32_16x16x32_bf16 v[82:85], v[170:173], v[204:207], v[82:85]
	v_mfma_f32_16x16x32_bf16 v[70:73], v[162:165], v[212:215], v[70:73]
	v_mfma_f32_16x16x32_bf16 v[66:69], v[170:173], v[212:215], v[66:69]
	v_mfma_f32_16x16x32_bf16 v[118:121], v[166:169], v[182:185], v[118:121]
	v_mfma_f32_16x16x32_bf16 v[114:117], v[174:177], v[182:185], v[114:117]
	v_mfma_f32_16x16x32_bf16 v[102:105], v[166:169], v[190:193], v[102:105]
	v_mfma_f32_16x16x32_bf16 v[98:101], v[174:177], v[190:193], v[98:101]
	v_mfma_f32_16x16x32_bf16 v[86:89], v[166:169], v[208:211], v[86:89]
	v_mfma_f32_16x16x32_bf16 v[82:85], v[174:177], v[208:211], v[82:85]
	v_mfma_f32_16x16x32_bf16 v[70:73], v[166:169], v[228:231], v[70:73]
	v_mfma_f32_16x16x32_bf16 v[66:69], v[174:177], v[228:231], v[66:69]
	s_setprio 0
	s_barrier
	s_add_i32 s30, s57, s42
	v_lshl_add_u64 v[150:151], v[150:151], 0, s[94:95]
	s_mov_b32 m0, s30
	ds_read_b128 v[178:181], v152 offset:49152
	ds_read_b128 v[182:185], v152 offset:50176
	ds_read_b128 v[186:189], v152 offset:51200
	ds_read_b128 v[190:193], v152 offset:52224
	ds_read_b128 v[204:207], v152 offset:53248
	ds_read_b128 v[208:211], v152 offset:54272
	ds_read_b128 v[212:215], v152 offset:55296
	ds_read_b128 v[228:231], v152 offset:56320
	global_load_lds_dwordx4 v[150:151], off
	s_add_i32 m0, s30, 0x2000
	s_add_u32 s28, s28, 0x40080
	v_lshl_add_u64 v[150:151], v[194:195], 0, s[94:95]
	s_addc_u32 s29, s29, 0
	s_add_i32 s30, s58, s42
	global_load_lds_dwordx4 v[150:151], off
	s_mov_b32 m0, s30
	v_lshl_add_u64 v[150:151], s[28:29], 0, v[134:135]
	global_load_lds_dwordx4 v[150:151], off
	s_add_i32 m0, s30, 0x2000
	v_lshl_add_u64 v[150:151], s[28:29], 0, v[130:131]
	global_load_lds_dwordx4 v[150:151], off
	s_mov_b32 m0, s49
	v_lshl_add_u64 v[150:151], v[216:217], 0, s[94:95]
	global_load_lds_dwordx4 v[150:151], off
	s_mov_b32 m0, s50
	v_lshl_add_u64 v[150:151], v[232:233], 0, s[94:95]
	global_load_lds_dwordx4 v[150:151], off
	s_waitcnt vmcnt(8)
	s_waitcnt lgkmcnt(0)
	s_barrier
	s_setprio 1
	s_waitcnt lgkmcnt(0)
	v_mfma_f32_16x16x32_bf16 v[62:65], v[142:145], v[178:181], v[62:65]
	v_mfma_f32_16x16x32_bf16 v[58:61], v[154:157], v[178:181], v[58:61]
	v_mfma_f32_16x16x32_bf16 v[46:49], v[142:145], v[186:189], v[46:49]
	v_mfma_f32_16x16x32_bf16 v[42:45], v[154:157], v[186:189], v[42:45]
	v_mfma_f32_16x16x32_bf16 v[30:33], v[142:145], v[204:207], v[30:33]
	v_mfma_f32_16x16x32_bf16 v[26:29], v[154:157], v[204:207], v[26:29]
	v_mfma_f32_16x16x32_bf16 v[14:17], v[142:145], v[212:215], v[14:17]
	v_mfma_f32_16x16x32_bf16 v[10:13], v[154:157], v[212:215], v[10:13]
	v_mfma_f32_16x16x32_bf16 v[62:65], v[146:149], v[182:185], v[62:65]
	v_mfma_f32_16x16x32_bf16 v[58:61], v[158:161], v[182:185], v[58:61]
	v_mfma_f32_16x16x32_bf16 v[46:49], v[146:149], v[190:193], v[46:49]
	v_mfma_f32_16x16x32_bf16 v[42:45], v[158:161], v[190:193], v[42:45]
	v_mfma_f32_16x16x32_bf16 v[30:33], v[146:149], v[208:211], v[30:33]
	v_mfma_f32_16x16x32_bf16 v[26:29], v[158:161], v[208:211], v[26:29]
	v_mfma_f32_16x16x32_bf16 v[14:17], v[146:149], v[228:231], v[14:17]
	v_mfma_f32_16x16x32_bf16 v[10:13], v[158:161], v[228:231], v[10:13]
	v_mfma_f32_16x16x32_bf16 v[54:57], v[162:165], v[178:181], v[54:57]
	v_mfma_f32_16x16x32_bf16 v[50:53], v[170:173], v[178:181], v[50:53]
	v_mfma_f32_16x16x32_bf16 v[38:41], v[162:165], v[186:189], v[38:41]
	v_mfma_f32_16x16x32_bf16 v[34:37], v[170:173], v[186:189], v[34:37]
	v_mfma_f32_16x16x32_bf16 v[22:25], v[162:165], v[204:207], v[22:25]
	v_mfma_f32_16x16x32_bf16 v[18:21], v[170:173], v[204:207], v[18:21]
	v_mfma_f32_16x16x32_bf16 v[6:9], v[162:165], v[212:215], v[6:9]
	v_mfma_f32_16x16x32_bf16 v[2:5], v[170:173], v[212:215], v[2:5]
	v_mfma_f32_16x16x32_bf16 v[54:57], v[166:169], v[182:185], v[54:57]
	v_mfma_f32_16x16x32_bf16 v[50:53], v[174:177], v[182:185], v[50:53]
	v_mfma_f32_16x16x32_bf16 v[38:41], v[166:169], v[190:193], v[38:41]
	v_mfma_f32_16x16x32_bf16 v[34:37], v[174:177], v[190:193], v[34:37]
	v_mfma_f32_16x16x32_bf16 v[22:25], v[166:169], v[208:211], v[22:25]
	v_mfma_f32_16x16x32_bf16 v[18:21], v[174:177], v[208:211], v[18:21]
	v_mfma_f32_16x16x32_bf16 v[6:9], v[166:169], v[228:231], v[6:9]
	v_mfma_f32_16x16x32_bf16 v[2:5], v[174:177], v[228:231], v[2:5]
	s_setprio 0
	s_barrier
	s_add_i32 s56, s56, 2
	s_add_u32 s26, s26, 0x100
	s_addc_u32 s27, s27, 0
	s_add_u32 s54, s54, 0x100
	s_addc_u32 s55, s55, 0
	s_cmp_gt_u32 s56, 13
	s_cbranch_scc0 .LBB0_111
	s_and_b64 vcc, exec, s[14:15]
	s_cbranch_vccz .LBB0_114
	s_barrier

.LBB0_139:
	s_add_u32 s28, s26, 0xfffc0080
	s_addc_u32 s29, s27, -1
	s_add_i32 s64, 0, 0x10000
	s_cmp_eq_u32 s63, 12
	s_cselect_b32 s31, s21, s29
	s_cselect_b32 s30, s59, s28
	v_add_u32_e32 v143, s64, v1
	s_cselect_b32 s29, s19, s62
	s_cselect_b32 s28, s60, s61
	s_add_i32 s66, 0, 0x14000
	ds_read_b128 v[144:147], v143
	ds_read_b128 v[148:151], v143 offset:1024
	ds_read_b128 v[152:155], v143 offset:2048
	ds_read_b128 v[156:159], v143 offset:3072
	v_add_u32_e32 v143, s66, v1
	ds_read_b128 v[160:163], v143
	ds_read_b128 v[164:167], v143 offset:1024
	ds_read_b128 v[168:171], v143 offset:2048
	ds_read_b128 v[172:175], v143 offset:3072
	v_lshl_add_u64 v[216:217], s[26:27], 0, v[138:139]
	s_add_i32 m0, s50, 0xc000
	ds_read_b128 v[176:179], v142
	ds_read_b128 v[180:183], v142 offset:1024
	ds_read_b128 v[184:187], v142 offset:2048
	ds_read_b128 v[188:191], v142 offset:3072
	ds_read_b128 v[192:195], v142 offset:4096
	ds_read_b128 v[204:207], v142 offset:5120
	ds_read_b128 v[208:211], v142 offset:6144
	ds_read_b128 v[212:215], v142 offset:7168
	global_load_lds_dwordx4 v[216:217], off
	s_add_i32 m0, s50, 0xe000
	v_lshl_add_u64 v[216:217], s[26:27], 0, v[140:141]
	global_load_lds_dwordx4 v[216:217], off
	s_waitcnt vmcnt(8)
	s_waitcnt lgkmcnt(0)
	s_barrier
	s_setprio 1
	s_waitcnt lgkmcnt(0)
	v_mfma_f32_16x16x32_bf16 v[126:129], v[144:147], v[176:179], v[126:129]
	v_mfma_f32_16x16x32_bf16 v[122:125], v[152:155], v[176:179], v[122:125]
	v_mfma_f32_16x16x32_bf16 v[118:121], v[144:147], v[184:187], v[118:121]
	v_mfma_f32_16x16x32_bf16 v[114:117], v[152:155], v[184:187], v[114:117]
	v_mfma_f32_16x16x32_bf16 v[102:105], v[144:147], v[192:195], v[102:105]
	v_mfma_f32_16x16x32_bf16 v[98:101], v[152:155], v[192:195], v[98:101]
	v_mfma_f32_16x16x32_bf16 v[86:89], v[144:147], v[208:211], v[86:89]
	v_mfma_f32_16x16x32_bf16 v[82:85], v[152:155], v[208:211], v[82:85]
	v_mfma_f32_16x16x32_bf16 v[126:129], v[148:151], v[180:183], v[126:129]
	v_mfma_f32_16x16x32_bf16 v[122:125], v[156:159], v[180:183], v[122:125]
	v_mfma_f32_16x16x32_bf16 v[118:121], v[148:151], v[188:191], v[118:121]
	v_mfma_f32_16x16x32_bf16 v[114:117], v[156:159], v[188:191], v[114:117]
	v_mfma_f32_16x16x32_bf16 v[102:105], v[148:151], v[204:207], v[102:105]
	v_mfma_f32_16x16x32_bf16 v[98:101], v[156:159], v[204:207], v[98:101]
	v_mfma_f32_16x16x32_bf16 v[86:89], v[148:151], v[212:215], v[86:89]
	v_mfma_f32_16x16x32_bf16 v[82:85], v[156:159], v[212:215], v[82:85]
	v_mfma_f32_16x16x32_bf16 v[110:113], v[160:163], v[176:179], v[110:113]
	v_mfma_f32_16x16x32_bf16 v[106:109], v[168:171], v[176:179], v[106:109]
	v_mfma_f32_16x16x32_bf16 v[94:97], v[160:163], v[184:187], v[94:97]
	v_mfma_f32_16x16x32_bf16 v[90:93], v[168:171], v[184:187], v[90:93]
	v_mfma_f32_16x16x32_bf16 v[78:81], v[160:163], v[192:195], v[78:81]
	v_mfma_f32_16x16x32_bf16 v[74:77], v[168:171], v[192:195], v[74:77]
	v_mfma_f32_16x16x32_bf16 v[70:73], v[160:163], v[208:211], v[70:73]
	v_mfma_f32_16x16x32_bf16 v[66:69], v[168:171], v[208:211], v[66:69]
	v_mfma_f32_16x16x32_bf16 v[110:113], v[164:167], v[180:183], v[110:113]
	v_mfma_f32_16x16x32_bf16 v[106:109], v[172:175], v[180:183], v[106:109]
	v_mfma_f32_16x16x32_bf16 v[94:97], v[164:167], v[188:191], v[94:97]
	v_mfma_f32_16x16x32_bf16 v[90:93], v[172:175], v[188:191], v[90:93]
	v_mfma_f32_16x16x32_bf16 v[78:81], v[164:167], v[204:207], v[78:81]
	v_mfma_f32_16x16x32_bf16 v[74:77], v[172:175], v[204:207], v[74:77]
	v_mfma_f32_16x16x32_bf16 v[70:73], v[164:167], v[212:215], v[70:73]
	v_mfma_f32_16x16x32_bf16 v[66:69], v[172:175], v[212:215], v[66:69]
	s_setprio 0
	s_barrier
	s_add_i32 s64, s64, s49
	v_lshl_add_u64 v[216:217], s[28:29], 0, v[132:133]
	s_mov_b32 m0, s64
	ds_read_b128 v[176:179], v142 offset:16384
	ds_read_b128 v[180:183], v142 offset:17408
	ds_read_b128 v[184:187], v142 offset:18432
	ds_read_b128 v[188:191], v142 offset:19456
	ds_read_b128 v[192:195], v142 offset:20480
	ds_read_b128 v[204:207], v142 offset:21504
	ds_read_b128 v[208:211], v142 offset:22528
	ds_read_b128 v[212:215], v142 offset:23552
	global_load_lds_dwordx4 v[216:217], off
	s_add_i32 m0, s64, 0x2000
	s_add_u32 s64, s28, 0x40000
	v_lshl_add_u64 v[228:229], s[28:29], 0, v[136:137]
	s_addc_u32 s65, s29, 0
	s_add_i32 s66, s66, s49
	global_load_lds_dwordx4 v[228:229], off
	v_lshl_add_u64 v[230:231], s[64:65], 0, v[132:133]
	s_mov_b32 m0, s66
	v_lshl_add_u64 v[232:233], s[30:31], 0, v[134:135]
	global_load_lds_dwordx4 v[230:231], off
	s_add_i32 m0, s66, 0x2000
	v_lshl_add_u64 v[230:231], s[64:65], 0, v[136:137]
	global_load_lds_dwordx4 v[230:231], off
	s_mov_b32 m0, s50
	v_lshl_add_u64 v[230:231], s[30:31], 0, v[130:131]
	global_load_lds_dwordx4 v[230:231], off
	s_mov_b32 m0, s51
	s_nop 0
	global_load_lds_dwordx4 v[232:233], off
	s_waitcnt vmcnt(8)
	s_waitcnt lgkmcnt(0)
	s_barrier
	s_setprio 1
	s_waitcnt lgkmcnt(0)
	v_mfma_f32_16x16x32_bf16 v[62:65], v[144:147], v[176:179], v[62:65]
	v_mfma_f32_16x16x32_bf16 v[58:61], v[152:155], v[176:179], v[58:61]
	v_mfma_f32_16x16x32_bf16 v[54:57], v[144:147], v[184:187], v[54:57]
	v_mfma_f32_16x16x32_bf16 v[50:53], v[152:155], v[184:187], v[50:53]
	v_mfma_f32_16x16x32_bf16 v[38:41], v[144:147], v[192:195], v[38:41]
	v_mfma_f32_16x16x32_bf16 v[34:37], v[152:155], v[192:195], v[34:37]
	v_mfma_f32_16x16x32_bf16 v[22:25], v[144:147], v[208:211], v[22:25]
	v_mfma_f32_16x16x32_bf16 v[18:21], v[152:155], v[208:211], v[18:21]
	v_mfma_f32_16x16x32_bf16 v[62:65], v[148:151], v[180:183], v[62:65]
	v_mfma_f32_16x16x32_bf16 v[58:61], v[156:159], v[180:183], v[58:61]
	v_mfma_f32_16x16x32_bf16 v[54:57], v[148:151], v[188:191], v[54:57]
	v_mfma_f32_16x16x32_bf16 v[50:53], v[156:159], v[188:191], v[50:53]
	v_mfma_f32_16x16x32_bf16 v[38:41], v[148:151], v[204:207], v[38:41]
	v_mfma_f32_16x16x32_bf16 v[34:37], v[156:159], v[204:207], v[34:37]
	v_mfma_f32_16x16x32_bf16 v[22:25], v[148:151], v[212:215], v[22:25]
	v_mfma_f32_16x16x32_bf16 v[18:21], v[156:159], v[212:215], v[18:21]
	v_mfma_f32_16x16x32_bf16 v[46:49], v[160:163], v[176:179], v[46:49]
	v_mfma_f32_16x16x32_bf16 v[42:45], v[168:171], v[176:179], v[42:45]
	v_mfma_f32_16x16x32_bf16 v[30:33], v[160:163], v[184:187], v[30:33]
	v_mfma_f32_16x16x32_bf16 v[26:29], v[168:171], v[184:187], v[26:29]
	v_mfma_f32_16x16x32_bf16 v[14:17], v[160:163], v[192:195], v[14:17]
	v_mfma_f32_16x16x32_bf16 v[10:13], v[168:171], v[192:195], v[10:13]
	v_mfma_f32_16x16x32_bf16 v[6:9], v[160:163], v[208:211], v[6:9]
	v_mfma_f32_16x16x32_bf16 v[2:5], v[168:171], v[208:211], v[2:5]
	v_mfma_f32_16x16x32_bf16 v[46:49], v[164:167], v[180:183], v[46:49]
	v_mfma_f32_16x16x32_bf16 v[42:45], v[172:175], v[180:183], v[42:45]
	v_mfma_f32_16x16x32_bf16 v[30:33], v[164:167], v[188:191], v[30:33]
	v_mfma_f32_16x16x32_bf16 v[26:29], v[172:175], v[188:191], v[26:29]
	v_mfma_f32_16x16x32_bf16 v[14:17], v[164:167], v[204:207], v[14:17]
	v_mfma_f32_16x16x32_bf16 v[10:13], v[172:175], v[204:207], v[10:13]
	v_mfma_f32_16x16x32_bf16 v[6:9], v[164:167], v[212:215], v[6:9]
	v_mfma_f32_16x16x32_bf16 v[2:5], v[172:175], v[212:215], v[2:5]
	s_setprio 0
	s_barrier
	s_add_i32 s64, 0, 0x18000
	v_add_u32_e32 v143, s64, v1
	s_add_i32 s65, 0, 0x1c000
	ds_read_b128 v[144:147], v143
	ds_read_b128 v[148:151], v143 offset:1024
	ds_read_b128 v[152:155], v143 offset:2048
	ds_read_b128 v[156:159], v143 offset:3072
	v_add_u32_e32 v143, s65, v1
	ds_read_b128 v[160:163], v143
	ds_read_b128 v[164:167], v143 offset:1024
	ds_read_b128 v[168:171], v143 offset:2048
	ds_read_b128 v[172:175], v143 offset:3072
	s_add_u32 s30, s30, 0x40000
	s_addc_u32 s31, s31, 0
	s_mov_b32 m0, s52
	v_lshl_add_u64 v[234:235], s[30:31], 0, v[130:131]
	ds_read_b128 v[176:179], v142 offset:32768
	ds_read_b128 v[180:183], v142 offset:33792
	ds_read_b128 v[184:187], v142 offset:34816
	ds_read_b128 v[188:191], v142 offset:35840
	ds_read_b128 v[192:195], v142 offset:36864
	ds_read_b128 v[204:207], v142 offset:37888
	ds_read_b128 v[208:211], v142 offset:38912
	ds_read_b128 v[212:215], v142 offset:39936
	global_load_lds_dwordx4 v[234:235], off
	s_mov_b32 m0, s53
	v_lshl_add_u64 v[234:235], s[30:31], 0, v[134:135]
	global_load_lds_dwordx4 v[234:235], off
	s_waitcnt vmcnt(8)
	s_waitcnt lgkmcnt(0)
	s_barrier
	s_setprio 1
	s_waitcnt lgkmcnt(0)
	v_mfma_f32_16x16x32_bf16 v[126:129], v[144:147], v[176:179], v[126:129]
	v_mfma_f32_16x16x32_bf16 v[122:125], v[152:155], v[176:179], v[122:125]
	v_mfma_f32_16x16x32_bf16 v[118:121], v[144:147], v[184:187], v[118:121]
	v_mfma_f32_16x16x32_bf16 v[114:117], v[152:155], v[184:187], v[114:117]
	v_mfma_f32_16x16x32_bf16 v[102:105], v[144:147], v[192:195], v[102:105]
	v_mfma_f32_16x16x32_bf16 v[98:101], v[152:155], v[192:195], v[98:101]
	v_mfma_f32_16x16x32_bf16 v[86:89], v[144:147], v[208:211], v[86:89]
	v_mfma_f32_16x16x32_bf16 v[82:85], v[152:155], v[208:211], v[82:85]
	v_mfma_f32_16x16x32_bf16 v[126:129], v[148:151], v[180:183], v[126:129]
	v_mfma_f32_16x16x32_bf16 v[122:125], v[156:159], v[180:183], v[122:125]
	v_mfma_f32_16x16x32_bf16 v[118:121], v[148:151], v[188:191], v[118:121]
	v_mfma_f32_16x16x32_bf16 v[114:117], v[156:159], v[188:191], v[114:117]
	v_mfma_f32_16x16x32_bf16 v[102:105], v[148:151], v[204:207], v[102:105]
	v_mfma_f32_16x16x32_bf16 v[98:101], v[156:159], v[204:207], v[98:101]
	v_mfma_f32_16x16x32_bf16 v[86:89], v[148:151], v[212:215], v[86:89]
	v_mfma_f32_16x16x32_bf16 v[82:85], v[156:159], v[212:215], v[82:85]
	v_mfma_f32_16x16x32_bf16 v[110:113], v[160:163], v[176:179], v[110:113]
	v_mfma_f32_16x16x32_bf16 v[106:109], v[168:171], v[176:179], v[106:109]
	v_mfma_f32_16x16x32_bf16 v[94:97], v[160:163], v[184:187], v[94:97]
	v_mfma_f32_16x16x32_bf16 v[90:93], v[168:171], v[184:187], v[90:93]
	v_mfma_f32_16x16x32_bf16 v[78:81], v[160:163], v[192:195], v[78:81]
	v_mfma_f32_16x16x32_bf16 v[74:77], v[168:171], v[192:195], v[74:77]
	v_mfma_f32_16x16x32_bf16 v[70:73], v[160:163], v[208:211], v[70:73]
	v_mfma_f32_16x16x32_bf16 v[66:69], v[168:171], v[208:211], v[66:69]
	v_mfma_f32_16x16x32_bf16 v[110:113], v[164:167], v[180:183], v[110:113]
	v_mfma_f32_16x16x32_bf16 v[106:109], v[172:175], v[180:183], v[106:109]
	v_mfma_f32_16x16x32_bf16 v[94:97], v[164:167], v[188:191], v[94:97]
	v_mfma_f32_16x16x32_bf16 v[90:93], v[172:175], v[188:191], v[90:93]
	v_mfma_f32_16x16x32_bf16 v[78:81], v[164:167], v[204:207], v[78:81]
	v_mfma_f32_16x16x32_bf16 v[74:77], v[172:175], v[204:207], v[74:77]
	v_mfma_f32_16x16x32_bf16 v[70:73], v[164:167], v[212:215], v[70:73]
	v_mfma_f32_16x16x32_bf16 v[66:69], v[172:175], v[212:215], v[66:69]
	s_setprio 0
	s_barrier
	s_add_i32 s30, s64, s49
	v_lshl_add_u64 v[216:217], v[216:217], 0, s[94:95]
	s_mov_b32 m0, s30
	ds_read_b128 v[176:179], v142 offset:49152
	ds_read_b128 v[180:183], v142 offset:50176
	ds_read_b128 v[184:187], v142 offset:51200
	ds_read_b128 v[188:191], v142 offset:52224
	ds_read_b128 v[192:195], v142 offset:53248
	ds_read_b128 v[204:207], v142 offset:54272
	ds_read_b128 v[208:211], v142 offset:55296
	ds_read_b128 v[212:215], v142 offset:56320
	global_load_lds_dwordx4 v[216:217], off
	s_add_i32 m0, s30, 0x2000
	s_add_u32 s28, s28, 0x40080
	v_lshl_add_u64 v[216:217], v[228:229], 0, s[94:95]
	s_addc_u32 s29, s29, 0
	s_add_i32 s30, s65, s49
	global_load_lds_dwordx4 v[216:217], off
	s_mov_b32 m0, s30
	v_lshl_add_u64 v[216:217], s[28:29], 0, v[132:133]
	global_load_lds_dwordx4 v[216:217], off
	s_add_i32 m0, s30, 0x2000
	v_lshl_add_u64 v[216:217], s[28:29], 0, v[136:137]
	global_load_lds_dwordx4 v[216:217], off
	s_mov_b32 m0, s56
	v_lshl_add_u64 v[216:217], v[230:231], 0, s[94:95]
	global_load_lds_dwordx4 v[216:217], off
	s_mov_b32 m0, s57
	v_lshl_add_u64 v[216:217], v[232:233], 0, s[94:95]
	global_load_lds_dwordx4 v[216:217], off
	s_waitcnt vmcnt(8)
	s_waitcnt lgkmcnt(0)
	s_barrier
	s_setprio 1
	s_waitcnt lgkmcnt(0)
	v_mfma_f32_16x16x32_bf16 v[62:65], v[144:147], v[176:179], v[62:65]
	v_mfma_f32_16x16x32_bf16 v[58:61], v[152:155], v[176:179], v[58:61]
	v_mfma_f32_16x16x32_bf16 v[54:57], v[144:147], v[184:187], v[54:57]
	v_mfma_f32_16x16x32_bf16 v[50:53], v[152:155], v[184:187], v[50:53]
	v_mfma_f32_16x16x32_bf16 v[38:41], v[144:147], v[192:195], v[38:41]
	v_mfma_f32_16x16x32_bf16 v[34:37], v[152:155], v[192:195], v[34:37]
	v_mfma_f32_16x16x32_bf16 v[22:25], v[144:147], v[208:211], v[22:25]
	v_mfma_f32_16x16x32_bf16 v[18:21], v[152:155], v[208:211], v[18:21]
	v_mfma_f32_16x16x32_bf16 v[62:65], v[148:151], v[180:183], v[62:65]
	v_mfma_f32_16x16x32_bf16 v[58:61], v[156:159], v[180:183], v[58:61]
	v_mfma_f32_16x16x32_bf16 v[54:57], v[148:151], v[188:191], v[54:57]
	v_mfma_f32_16x16x32_bf16 v[50:53], v[156:159], v[188:191], v[50:53]
	v_mfma_f32_16x16x32_bf16 v[38:41], v[148:151], v[204:207], v[38:41]
	v_mfma_f32_16x16x32_bf16 v[34:37], v[156:159], v[204:207], v[34:37]
	v_mfma_f32_16x16x32_bf16 v[22:25], v[148:151], v[212:215], v[22:25]
	v_mfma_f32_16x16x32_bf16 v[18:21], v[156:159], v[212:215], v[18:21]
	v_mfma_f32_16x16x32_bf16 v[46:49], v[160:163], v[176:179], v[46:49]
	v_mfma_f32_16x16x32_bf16 v[42:45], v[168:171], v[176:179], v[42:45]
	v_mfma_f32_16x16x32_bf16 v[30:33], v[160:163], v[184:187], v[30:33]
	v_mfma_f32_16x16x32_bf16 v[26:29], v[168:171], v[184:187], v[26:29]
	v_mfma_f32_16x16x32_bf16 v[14:17], v[160:163], v[192:195], v[14:17]
	v_mfma_f32_16x16x32_bf16 v[10:13], v[168:171], v[192:195], v[10:13]
	v_mfma_f32_16x16x32_bf16 v[6:9], v[160:163], v[208:211], v[6:9]
	v_mfma_f32_16x16x32_bf16 v[2:5], v[168:171], v[208:211], v[2:5]
	v_mfma_f32_16x16x32_bf16 v[46:49], v[164:167], v[180:183], v[46:49]
	v_mfma_f32_16x16x32_bf16 v[42:45], v[172:175], v[180:183], v[42:45]
	v_mfma_f32_16x16x32_bf16 v[30:33], v[164:167], v[188:191], v[30:33]
	v_mfma_f32_16x16x32_bf16 v[26:29], v[172:175], v[188:191], v[26:29]
	v_mfma_f32_16x16x32_bf16 v[14:17], v[164:167], v[204:207], v[14:17]
	v_mfma_f32_16x16x32_bf16 v[10:13], v[172:175], v[204:207], v[10:13]
	v_mfma_f32_16x16x32_bf16 v[6:9], v[164:167], v[212:215], v[6:9]
	v_mfma_f32_16x16x32_bf16 v[2:5], v[172:175], v[212:215], v[2:5]
	s_setprio 0
	s_barrier
	s_add_i32 s63, s63, 2
	s_add_u32 s26, s26, 0x100
	s_addc_u32 s27, s27, 0
	s_add_u32 s61, s61, 0x100
	s_addc_u32 s62, s62, 0
	s_cmp_gt_u32 s63, 13
	s_cbranch_scc0 .LBB0_139
	s_and_b64 vcc, exec, s[10:11]
	s_cbranch_vccz .LBB0_142
	s_barrier

.LBB0_220:
	s_add_u32 s26, s24, 0x100
	s_addc_u32 s27, s25, 0
	s_add_i32 s59, 0, 0x10000
	s_cmp_eq_u32 s58, 40
	s_cselect_b32 s31, s7, s27
	s_cselect_b32 s30, s6, s26
	s_cselect_b32 s29, s23, s57
	s_cselect_b32 s28, s22, s56
	s_add_i32 s60, 0, 0x14000
	v_add_u32_e32 v134, s59, v1
	v_add_u32_e32 v154, s60, v1
	ds_read_b128 v[110:113], v134
	ds_read_b128 v[118:121], v134 offset:1024
	ds_read_b128 v[122:125], v134 offset:2048
	ds_read_b128 v[134:137], v134 offset:3072
	ds_read_b128 v[138:141], v154
	ds_read_b128 v[142:145], v154 offset:1024
	ds_read_b128 v[146:149], v154 offset:2048
	ds_read_b128 v[154:157], v154 offset:3072
	v_lshl_add_u64 v[216:217], s[24:25], 0, v[206:207]
	s_add_i32 m0, s41, 0xc000
	ds_read_b128 v[162:165], v214
	ds_read_b128 v[166:169], v214 offset:1024
	ds_read_b128 v[170:173], v214 offset:2048
	ds_read_b128 v[174:177], v214 offset:3072
	ds_read_b128 v[178:181], v214 offset:4096
	ds_read_b128 v[182:185], v214 offset:5120
	ds_read_b128 v[186:189], v214 offset:6144
	ds_read_b128 v[210:213], v214 offset:7168
	global_load_lds_dwordx4 v[216:217], off
	s_add_i32 m0, s41, 0xe000
	v_lshl_add_u64 v[216:217], s[24:25], 0, v[208:209]
	global_load_lds_dwordx4 v[216:217], off
	s_waitcnt vmcnt(8)
	s_waitcnt lgkmcnt(0)
	s_barrier
	s_setprio 1
	s_waitcnt lgkmcnt(0)
	v_mfma_f32_16x16x32_bf16 v[158:161], v[110:113], v[162:165], v[158:161]
	v_mfma_f32_16x16x32_bf16 v[150:153], v[122:125], v[162:165], v[150:153]
	v_mfma_f32_16x16x32_bf16 v[114:117], v[110:113], v[170:173], v[114:117]
	v_mfma_f32_16x16x32_bf16 v[106:109], v[122:125], v[170:173], v[106:109]
	v_mfma_f32_16x16x32_bf16 v[94:97], v[110:113], v[178:181], v[94:97]
	v_mfma_f32_16x16x32_bf16 v[90:93], v[122:125], v[178:181], v[90:93]
	v_mfma_f32_16x16x32_bf16 v[78:81], v[110:113], v[186:189], v[78:81]
	v_mfma_f32_16x16x32_bf16 v[74:77], v[122:125], v[186:189], v[74:77]
	v_mfma_f32_16x16x32_bf16 v[158:161], v[118:121], v[166:169], v[158:161]
	v_mfma_f32_16x16x32_bf16 v[150:153], v[134:137], v[166:169], v[150:153]
	v_mfma_f32_16x16x32_bf16 v[114:117], v[118:121], v[174:177], v[114:117]
	v_mfma_f32_16x16x32_bf16 v[106:109], v[134:137], v[174:177], v[106:109]
	v_mfma_f32_16x16x32_bf16 v[94:97], v[118:121], v[182:185], v[94:97]
	v_mfma_f32_16x16x32_bf16 v[90:93], v[134:137], v[182:185], v[90:93]
	v_mfma_f32_16x16x32_bf16 v[78:81], v[118:121], v[210:213], v[78:81]
	v_mfma_f32_16x16x32_bf16 v[74:77], v[134:137], v[210:213], v[74:77]
	v_mfma_f32_16x16x32_bf16 v[130:133], v[138:141], v[162:165], v[130:133]
	v_mfma_f32_16x16x32_bf16 v[126:129], v[146:149], v[162:165], v[126:129]
	v_mfma_f32_16x16x32_bf16 v[102:105], v[138:141], v[170:173], v[102:105]
	v_mfma_f32_16x16x32_bf16 v[98:101], v[146:149], v[170:173], v[98:101]
	v_mfma_f32_16x16x32_bf16 v[86:89], v[138:141], v[178:181], v[86:89]
	v_mfma_f32_16x16x32_bf16 v[82:85], v[146:149], v[178:181], v[82:85]
	v_mfma_f32_16x16x32_bf16 v[70:73], v[138:141], v[186:189], v[70:73]
	v_mfma_f32_16x16x32_bf16 v[66:69], v[146:149], v[186:189], v[66:69]
	v_mfma_f32_16x16x32_bf16 v[130:133], v[142:145], v[166:169], v[130:133]
	v_mfma_f32_16x16x32_bf16 v[126:129], v[154:157], v[166:169], v[126:129]
	v_mfma_f32_16x16x32_bf16 v[102:105], v[142:145], v[174:177], v[102:105]
	v_mfma_f32_16x16x32_bf16 v[98:101], v[154:157], v[174:177], v[98:101]
	v_mfma_f32_16x16x32_bf16 v[86:89], v[142:145], v[182:185], v[86:89]
	v_mfma_f32_16x16x32_bf16 v[82:85], v[154:157], v[182:185], v[82:85]
	v_mfma_f32_16x16x32_bf16 v[70:73], v[142:145], v[210:213], v[70:73]
	v_mfma_f32_16x16x32_bf16 v[66:69], v[154:157], v[210:213], v[66:69]
	s_setprio 0
	s_barrier
	s_add_i32 s24, s59, s40
	v_lshl_add_u64 v[216:217], s[28:29], 0, v[192:193]
	s_mov_b32 m0, s24
	ds_read_b128 v[162:165], v214 offset:16384
	ds_read_b128 v[166:169], v214 offset:17408
	ds_read_b128 v[170:173], v214 offset:18432
	ds_read_b128 v[174:177], v214 offset:19456
	ds_read_b128 v[178:181], v214 offset:20480
	ds_read_b128 v[182:185], v214 offset:21504
	ds_read_b128 v[186:189], v214 offset:22528
	ds_read_b128 v[210:213], v214 offset:23552
	global_load_lds_dwordx4 v[216:217], off
	s_add_i32 m0, s24, 0x2000
	s_add_u32 s24, s28, 0xb0000
	v_lshl_add_u64 v[228:229], s[28:29], 0, v[204:205]
	s_addc_u32 s25, s29, 0
	s_add_i32 s59, s60, s40
	global_load_lds_dwordx4 v[228:229], off
	v_lshl_add_u64 v[230:231], s[24:25], 0, v[192:193]
	s_mov_b32 m0, s59
	v_lshl_add_u64 v[232:233], s[30:31], 0, v[194:195]
	global_load_lds_dwordx4 v[230:231], off
	s_add_i32 m0, s59, 0x2000
	v_lshl_add_u64 v[230:231], s[24:25], 0, v[204:205]
	global_load_lds_dwordx4 v[230:231], off
	s_mov_b32 m0, s41
	v_lshl_add_u64 v[230:231], s[30:31], 0, v[190:191]
	global_load_lds_dwordx4 v[230:231], off
	s_mov_b32 m0, s42
	s_nop 0
	global_load_lds_dwordx4 v[232:233], off
	s_waitcnt vmcnt(8)
	s_waitcnt lgkmcnt(0)
	s_barrier
	s_setprio 1
	s_waitcnt lgkmcnt(0)
	v_mfma_f32_16x16x32_bf16 v[62:65], v[110:113], v[162:165], v[62:65]
	v_mfma_f32_16x16x32_bf16 v[58:61], v[122:125], v[162:165], v[58:61]
	v_mfma_f32_16x16x32_bf16 v[46:49], v[110:113], v[170:173], v[46:49]
	v_mfma_f32_16x16x32_bf16 v[42:45], v[122:125], v[170:173], v[42:45]
	v_mfma_f32_16x16x32_bf16 v[30:33], v[110:113], v[178:181], v[30:33]
	v_mfma_f32_16x16x32_bf16 v[26:29], v[122:125], v[178:181], v[26:29]
	v_mfma_f32_16x16x32_bf16 v[14:17], v[110:113], v[186:189], v[14:17]
	v_mfma_f32_16x16x32_bf16 v[10:13], v[122:125], v[186:189], v[10:13]
	v_mfma_f32_16x16x32_bf16 v[62:65], v[118:121], v[166:169], v[62:65]
	v_mfma_f32_16x16x32_bf16 v[58:61], v[134:137], v[166:169], v[58:61]
	v_mfma_f32_16x16x32_bf16 v[46:49], v[118:121], v[174:177], v[46:49]
	v_mfma_f32_16x16x32_bf16 v[42:45], v[134:137], v[174:177], v[42:45]
	v_mfma_f32_16x16x32_bf16 v[30:33], v[118:121], v[182:185], v[30:33]
	v_mfma_f32_16x16x32_bf16 v[26:29], v[134:137], v[182:185], v[26:29]
	v_mfma_f32_16x16x32_bf16 v[14:17], v[118:121], v[210:213], v[14:17]
	v_mfma_f32_16x16x32_bf16 v[10:13], v[134:137], v[210:213], v[10:13]
	v_mfma_f32_16x16x32_bf16 v[54:57], v[138:141], v[162:165], v[54:57]
	v_mfma_f32_16x16x32_bf16 v[50:53], v[146:149], v[162:165], v[50:53]
	v_mfma_f32_16x16x32_bf16 v[38:41], v[138:141], v[170:173], v[38:41]
	v_mfma_f32_16x16x32_bf16 v[34:37], v[146:149], v[170:173], v[34:37]
	v_mfma_f32_16x16x32_bf16 v[22:25], v[138:141], v[178:181], v[22:25]
	v_mfma_f32_16x16x32_bf16 v[18:21], v[146:149], v[178:181], v[18:21]
	v_mfma_f32_16x16x32_bf16 v[6:9], v[138:141], v[186:189], v[6:9]
	v_mfma_f32_16x16x32_bf16 v[2:5], v[146:149], v[186:189], v[2:5]
	v_mfma_f32_16x16x32_bf16 v[54:57], v[142:145], v[166:169], v[54:57]
	v_mfma_f32_16x16x32_bf16 v[50:53], v[154:157], v[166:169], v[50:53]
	v_mfma_f32_16x16x32_bf16 v[38:41], v[142:145], v[174:177], v[38:41]
	v_mfma_f32_16x16x32_bf16 v[34:37], v[154:157], v[174:177], v[34:37]
	v_mfma_f32_16x16x32_bf16 v[22:25], v[142:145], v[182:185], v[22:25]
	v_mfma_f32_16x16x32_bf16 v[18:21], v[154:157], v[182:185], v[18:21]
	v_mfma_f32_16x16x32_bf16 v[6:9], v[142:145], v[210:213], v[6:9]
	v_mfma_f32_16x16x32_bf16 v[2:5], v[154:157], v[210:213], v[2:5]
	s_setprio 0
	s_barrier
	s_add_i32 s59, 0, 0x18000
	s_add_i32 s60, 0, 0x1c000
	v_add_u32_e32 v134, s59, v1
	v_add_u32_e32 v154, s60, v1
	ds_read_b128 v[110:113], v134
	ds_read_b128 v[118:121], v134 offset:1024
	ds_read_b128 v[122:125], v134 offset:2048
	ds_read_b128 v[134:137], v134 offset:3072
	ds_read_b128 v[138:141], v154
	ds_read_b128 v[142:145], v154 offset:1024
	ds_read_b128 v[146:149], v154 offset:2048
	ds_read_b128 v[154:157], v154 offset:3072
	s_add_u32 s24, s30, 0xb0000
	s_addc_u32 s25, s31, 0
	s_mov_b32 m0, s43
	v_lshl_add_u64 v[234:235], s[24:25], 0, v[190:191]
	ds_read_b128 v[162:165], v214 offset:32768
	ds_read_b128 v[166:169], v214 offset:33792
	ds_read_b128 v[170:173], v214 offset:34816
	ds_read_b128 v[174:177], v214 offset:35840
	ds_read_b128 v[178:181], v214 offset:36864
	ds_read_b128 v[182:185], v214 offset:37888
	ds_read_b128 v[186:189], v214 offset:38912
	ds_read_b128 v[210:213], v214 offset:39936
	global_load_lds_dwordx4 v[234:235], off
	s_mov_b32 m0, s44
	v_lshl_add_u64 v[234:235], s[24:25], 0, v[194:195]
	global_load_lds_dwordx4 v[234:235], off
	s_waitcnt vmcnt(8)
	s_waitcnt lgkmcnt(0)
	s_barrier
	s_setprio 1
	s_waitcnt lgkmcnt(0)
	v_mfma_f32_16x16x32_bf16 v[158:161], v[110:113], v[162:165], v[158:161]
	v_mfma_f32_16x16x32_bf16 v[150:153], v[122:125], v[162:165], v[150:153]
	v_mfma_f32_16x16x32_bf16 v[114:117], v[110:113], v[170:173], v[114:117]
	v_mfma_f32_16x16x32_bf16 v[106:109], v[122:125], v[170:173], v[106:109]
	v_mfma_f32_16x16x32_bf16 v[94:97], v[110:113], v[178:181], v[94:97]
	v_mfma_f32_16x16x32_bf16 v[90:93], v[122:125], v[178:181], v[90:93]
	v_mfma_f32_16x16x32_bf16 v[78:81], v[110:113], v[186:189], v[78:81]
	v_mfma_f32_16x16x32_bf16 v[74:77], v[122:125], v[186:189], v[74:77]
	v_mfma_f32_16x16x32_bf16 v[158:161], v[118:121], v[166:169], v[158:161]
	v_mfma_f32_16x16x32_bf16 v[150:153], v[134:137], v[166:169], v[150:153]
	v_mfma_f32_16x16x32_bf16 v[114:117], v[118:121], v[174:177], v[114:117]
	v_mfma_f32_16x16x32_bf16 v[106:109], v[134:137], v[174:177], v[106:109]
	v_mfma_f32_16x16x32_bf16 v[94:97], v[118:121], v[182:185], v[94:97]
	v_mfma_f32_16x16x32_bf16 v[90:93], v[134:137], v[182:185], v[90:93]
	v_mfma_f32_16x16x32_bf16 v[78:81], v[118:121], v[210:213], v[78:81]
	v_mfma_f32_16x16x32_bf16 v[74:77], v[134:137], v[210:213], v[74:77]
	v_mfma_f32_16x16x32_bf16 v[130:133], v[138:141], v[162:165], v[130:133]
	v_mfma_f32_16x16x32_bf16 v[126:129], v[146:149], v[162:165], v[126:129]
	v_mfma_f32_16x16x32_bf16 v[102:105], v[138:141], v[170:173], v[102:105]
	v_mfma_f32_16x16x32_bf16 v[98:101], v[146:149], v[170:173], v[98:101]
	v_mfma_f32_16x16x32_bf16 v[86:89], v[138:141], v[178:181], v[86:89]
	v_mfma_f32_16x16x32_bf16 v[82:85], v[146:149], v[178:181], v[82:85]
	v_mfma_f32_16x16x32_bf16 v[70:73], v[138:141], v[186:189], v[70:73]
	v_mfma_f32_16x16x32_bf16 v[66:69], v[146:149], v[186:189], v[66:69]
	v_mfma_f32_16x16x32_bf16 v[130:133], v[142:145], v[166:169], v[130:133]
	v_mfma_f32_16x16x32_bf16 v[126:129], v[154:157], v[166:169], v[126:129]
	v_mfma_f32_16x16x32_bf16 v[102:105], v[142:145], v[174:177], v[102:105]
	v_mfma_f32_16x16x32_bf16 v[98:101], v[154:157], v[174:177], v[98:101]
	v_mfma_f32_16x16x32_bf16 v[86:89], v[142:145], v[182:185], v[86:89]
	v_mfma_f32_16x16x32_bf16 v[82:85], v[154:157], v[182:185], v[82:85]
	v_mfma_f32_16x16x32_bf16 v[70:73], v[142:145], v[210:213], v[70:73]
	v_mfma_f32_16x16x32_bf16 v[66:69], v[154:157], v[210:213], v[66:69]
	s_setprio 0
	s_barrier
	s_add_i32 s24, s59, s40
	v_lshl_add_u64 v[216:217], v[216:217], 0, s[94:95]
	s_mov_b32 m0, s24
	ds_read_b128 v[162:165], v214 offset:49152
	ds_read_b128 v[166:169], v214 offset:50176
	ds_read_b128 v[170:173], v214 offset:51200
	ds_read_b128 v[174:177], v214 offset:52224
	ds_read_b128 v[178:181], v214 offset:53248
	ds_read_b128 v[182:185], v214 offset:54272
	ds_read_b128 v[186:189], v214 offset:55296
	ds_read_b128 v[210:213], v214 offset:56320
	global_load_lds_dwordx4 v[216:217], off
	s_add_i32 m0, s24, 0x2000
	s_add_u32 s24, s28, 0xb0080
	v_lshl_add_u64 v[216:217], v[228:229], 0, s[94:95]
	s_addc_u32 s25, s29, 0
	s_add_i32 s28, s60, s40
	global_load_lds_dwordx4 v[216:217], off
	s_mov_b32 m0, s28
	v_lshl_add_u64 v[216:217], s[24:25], 0, v[192:193]
	global_load_lds_dwordx4 v[216:217], off
	s_add_i32 m0, s28, 0x2000
	v_lshl_add_u64 v[216:217], s[24:25], 0, v[204:205]
	global_load_lds_dwordx4 v[216:217], off
	s_mov_b32 m0, s47
	v_lshl_add_u64 v[216:217], v[230:231], 0, s[94:95]
	global_load_lds_dwordx4 v[216:217], off
	s_mov_b32 m0, s48
	v_lshl_add_u64 v[216:217], v[232:233], 0, s[94:95]
	global_load_lds_dwordx4 v[216:217], off
	s_waitcnt vmcnt(8)
	s_waitcnt lgkmcnt(0)
	s_barrier
	s_setprio 1
	s_waitcnt lgkmcnt(0)
	v_mfma_f32_16x16x32_bf16 v[62:65], v[110:113], v[162:165], v[62:65]
	v_mfma_f32_16x16x32_bf16 v[58:61], v[122:125], v[162:165], v[58:61]
	v_mfma_f32_16x16x32_bf16 v[46:49], v[110:113], v[170:173], v[46:49]
	v_mfma_f32_16x16x32_bf16 v[42:45], v[122:125], v[170:173], v[42:45]
	v_mfma_f32_16x16x32_bf16 v[30:33], v[110:113], v[178:181], v[30:33]
	v_mfma_f32_16x16x32_bf16 v[26:29], v[122:125], v[178:181], v[26:29]
	v_mfma_f32_16x16x32_bf16 v[14:17], v[110:113], v[186:189], v[14:17]
	v_mfma_f32_16x16x32_bf16 v[10:13], v[122:125], v[186:189], v[10:13]
	v_mfma_f32_16x16x32_bf16 v[62:65], v[118:121], v[166:169], v[62:65]
	v_mfma_f32_16x16x32_bf16 v[58:61], v[134:137], v[166:169], v[58:61]
	v_mfma_f32_16x16x32_bf16 v[46:49], v[118:121], v[174:177], v[46:49]
	v_mfma_f32_16x16x32_bf16 v[42:45], v[134:137], v[174:177], v[42:45]
	v_mfma_f32_16x16x32_bf16 v[30:33], v[118:121], v[182:185], v[30:33]
	v_mfma_f32_16x16x32_bf16 v[26:29], v[134:137], v[182:185], v[26:29]
	v_mfma_f32_16x16x32_bf16 v[14:17], v[118:121], v[210:213], v[14:17]
	v_mfma_f32_16x16x32_bf16 v[10:13], v[134:137], v[210:213], v[10:13]
	v_mfma_f32_16x16x32_bf16 v[54:57], v[138:141], v[162:165], v[54:57]
	v_mfma_f32_16x16x32_bf16 v[50:53], v[146:149], v[162:165], v[50:53]
	v_mfma_f32_16x16x32_bf16 v[38:41], v[138:141], v[170:173], v[38:41]
	v_mfma_f32_16x16x32_bf16 v[34:37], v[146:149], v[170:173], v[34:37]
	v_mfma_f32_16x16x32_bf16 v[22:25], v[138:141], v[178:181], v[22:25]
	v_mfma_f32_16x16x32_bf16 v[18:21], v[146:149], v[178:181], v[18:21]
	v_mfma_f32_16x16x32_bf16 v[6:9], v[138:141], v[186:189], v[6:9]
	v_mfma_f32_16x16x32_bf16 v[2:5], v[146:149], v[186:189], v[2:5]
	v_mfma_f32_16x16x32_bf16 v[54:57], v[142:145], v[166:169], v[54:57]
	v_mfma_f32_16x16x32_bf16 v[50:53], v[154:157], v[166:169], v[50:53]
	v_mfma_f32_16x16x32_bf16 v[38:41], v[142:145], v[174:177], v[38:41]
	v_mfma_f32_16x16x32_bf16 v[34:37], v[154:157], v[174:177], v[34:37]
	v_mfma_f32_16x16x32_bf16 v[22:25], v[142:145], v[182:185], v[22:25]
	v_mfma_f32_16x16x32_bf16 v[18:21], v[154:157], v[182:185], v[18:21]
	v_mfma_f32_16x16x32_bf16 v[6:9], v[142:145], v[210:213], v[6:9]
	v_mfma_f32_16x16x32_bf16 v[2:5], v[154:157], v[210:213], v[2:5]
	s_setprio 0
	s_barrier
	s_add_i32 s58, s58, 2
	s_add_u32 s56, s56, 0x100
	s_addc_u32 s57, s57, 0
	s_cmp_gt_u32 s58, 41
	s_mov_b64 s[24:25], s[26:27]
	s_cbranch_scc0 .LBB0_220
	s_and_b64 vcc, exec, s[20:21]
	s_cbranch_vccz .LBB0_223
	s_barrier

.LBB0_252:
	s_add_i32 s15, s14, 0x100
	s_and_b64 s[12:13], s[12:13], exec
	s_cselect_b32 s13, 0, s15
	s_cselect_b32 s12, 0, 0
	s_add_u32 s16, s4, s13
	s_addc_u32 s17, s5, s12
	s_add_i32 s61, 0, 0x10000
	s_add_u32 s18, s2, s13
	s_addc_u32 s19, s3, s12
	s_add_i32 s13, 0, 0x14000
	s_add_u32 s22, s6, s14
	s_addc_u32 s23, s7, 0
	s_add_i32 s60, s61, s43
	s_add_i32 m0, s44, 0xc000
	s_add_i32 s63, s44, 0xe000
	s_add_i32 s57, s60, 0x2000
	v_add_u32_e32 v139, s61, v1
	s_add_u32 s20, s18, 0x80800
	ds_read_b128 v[140:143], v139
	ds_read_b128 v[144:147], v139 offset:1024
	ds_read_b128 v[148:151], v139 offset:2048
	ds_read_b128 v[152:155], v139 offset:3072
	v_add_u32_e32 v139, s13, v1
	s_addc_u32 s21, s19, 0
	s_add_i32 s59, s13, s43
	ds_read_b128 v[156:159], v139
	ds_read_b128 v[160:163], v139 offset:1024
	ds_read_b128 v[164:167], v139 offset:2048
	ds_read_b128 v[168:171], v139 offset:3072
	s_add_i32 s58, s59, 0x2000
	s_add_i32 s56, 0, 0x18000
	s_add_i32 s55, 0, 0x1c000
	s_add_u32 s14, s16, 0x40000
	s_addc_u32 s15, s17, 0
	s_add_i32 s54, s56, s43
	s_add_i32 s53, s54, 0x2000
	s_add_u32 s12, s18, 0x80880
	s_addc_u32 s13, s19, 0
	s_add_i32 s62, s55, s43
	s_add_i32 s61, s62, 0x2000
	v_lshl_add_u64 v[212:213], s[22:23], 0, v[130:131]
	v_lshl_add_u64 v[212:213], v[212:213], 0, s[94:95]
	ds_read_b128 v[172:175], v138
	ds_read_b128 v[176:179], v138 offset:1024
	ds_read_b128 v[180:183], v138 offset:2048
	ds_read_b128 v[184:187], v138 offset:3072
	ds_read_b128 v[188:191], v138 offset:4096
	ds_read_b128 v[192:195], v138 offset:5120
	ds_read_b128 v[204:207], v138 offset:6144
	ds_read_b128 v[208:211], v138 offset:7168
	global_load_lds_dwordx4 v[212:213], off
	v_lshl_add_u64 v[212:213], s[22:23], 0, v[134:135]
	s_mov_b32 m0, s63
	v_lshl_add_u64 v[212:213], v[212:213], 0, s[94:95]
	global_load_lds_dwordx4 v[212:213], off
	s_waitcnt vmcnt(8)
	s_waitcnt lgkmcnt(0)
	s_barrier
	s_setprio 1
	s_waitcnt lgkmcnt(0)
	v_mfma_f32_16x16x32_bf16 v[126:129], v[140:143], v[172:175], v[126:129]
	v_mfma_f32_16x16x32_bf16 v[122:125], v[148:151], v[172:175], v[122:125]
	v_mfma_f32_16x16x32_bf16 v[118:121], v[140:143], v[180:183], v[118:121]
	v_mfma_f32_16x16x32_bf16 v[114:117], v[148:151], v[180:183], v[114:117]
	v_mfma_f32_16x16x32_bf16 v[102:105], v[140:143], v[188:191], v[102:105]
	v_mfma_f32_16x16x32_bf16 v[98:101], v[148:151], v[188:191], v[98:101]
	v_mfma_f32_16x16x32_bf16 v[86:89], v[140:143], v[204:207], v[86:89]
	v_mfma_f32_16x16x32_bf16 v[82:85], v[148:151], v[204:207], v[82:85]
	v_mfma_f32_16x16x32_bf16 v[126:129], v[144:147], v[176:179], v[126:129]
	v_mfma_f32_16x16x32_bf16 v[122:125], v[152:155], v[176:179], v[122:125]
	v_mfma_f32_16x16x32_bf16 v[118:121], v[144:147], v[184:187], v[118:121]
	v_mfma_f32_16x16x32_bf16 v[114:117], v[152:155], v[184:187], v[114:117]
	v_mfma_f32_16x16x32_bf16 v[102:105], v[144:147], v[192:195], v[102:105]
	v_mfma_f32_16x16x32_bf16 v[98:101], v[152:155], v[192:195], v[98:101]
	v_mfma_f32_16x16x32_bf16 v[86:89], v[144:147], v[208:211], v[86:89]
	v_mfma_f32_16x16x32_bf16 v[82:85], v[152:155], v[208:211], v[82:85]
	v_mfma_f32_16x16x32_bf16 v[110:113], v[156:159], v[172:175], v[110:113]
	v_mfma_f32_16x16x32_bf16 v[106:109], v[164:167], v[172:175], v[106:109]
	v_mfma_f32_16x16x32_bf16 v[94:97], v[156:159], v[180:183], v[94:97]
	v_mfma_f32_16x16x32_bf16 v[90:93], v[164:167], v[180:183], v[90:93]
	v_mfma_f32_16x16x32_bf16 v[78:81], v[156:159], v[188:191], v[78:81]
	v_mfma_f32_16x16x32_bf16 v[74:77], v[164:167], v[188:191], v[74:77]
	v_mfma_f32_16x16x32_bf16 v[70:73], v[156:159], v[204:207], v[70:73]
	v_mfma_f32_16x16x32_bf16 v[66:69], v[164:167], v[204:207], v[66:69]
	v_mfma_f32_16x16x32_bf16 v[110:113], v[160:163], v[176:179], v[110:113]
	v_mfma_f32_16x16x32_bf16 v[106:109], v[168:171], v[176:179], v[106:109]
	v_mfma_f32_16x16x32_bf16 v[94:97], v[160:163], v[184:187], v[94:97]
	v_mfma_f32_16x16x32_bf16 v[90:93], v[168:171], v[184:187], v[90:93]
	v_mfma_f32_16x16x32_bf16 v[78:81], v[160:163], v[192:195], v[78:81]
	v_mfma_f32_16x16x32_bf16 v[74:77], v[168:171], v[192:195], v[74:77]
	v_mfma_f32_16x16x32_bf16 v[70:73], v[160:163], v[208:211], v[70:73]
	v_mfma_f32_16x16x32_bf16 v[66:69], v[168:171], v[208:211], v[66:69]
	s_setprio 0
	s_barrier
	v_lshl_add_u64 v[212:213], s[18:19], 0, v[132:133]
	s_mov_b32 m0, s60
	v_lshl_add_u64 v[214:215], v[212:213], 0, s[90:91]
	ds_read_b128 v[172:175], v138 offset:16384
	ds_read_b128 v[176:179], v138 offset:17408
	ds_read_b128 v[180:183], v138 offset:18432
	ds_read_b128 v[184:187], v138 offset:19456
	ds_read_b128 v[188:191], v138 offset:20480
	ds_read_b128 v[192:195], v138 offset:21504
	ds_read_b128 v[204:207], v138 offset:22528
	ds_read_b128 v[208:211], v138 offset:23552
	global_load_lds_dwordx4 v[214:215], off
	v_lshl_add_u64 v[214:215], s[18:19], 0, v[136:137]
	v_lshl_add_u64 v[216:217], v[214:215], 0, s[90:91]
	s_mov_b32 m0, s57
	v_lshl_add_u64 v[228:229], s[16:17], 0, v[134:135]
	global_load_lds_dwordx4 v[216:217], off
	s_mov_b32 m0, s59
	v_lshl_add_u64 v[216:217], s[20:21], 0, v[132:133]
	global_load_lds_dwordx4 v[216:217], off
	s_mov_b32 m0, s58
	v_lshl_add_u64 v[216:217], s[20:21], 0, v[136:137]
	global_load_lds_dwordx4 v[216:217], off
	s_mov_b32 m0, s44
	v_lshl_add_u64 v[216:217], s[16:17], 0, v[130:131]
	global_load_lds_dwordx4 v[216:217], off
	s_mov_b32 m0, s45
	s_nop 0
	global_load_lds_dwordx4 v[228:229], off
	s_waitcnt vmcnt(8)
	s_waitcnt lgkmcnt(0)
	s_barrier
	s_setprio 1
	s_waitcnt lgkmcnt(0)
	v_mfma_f32_16x16x32_bf16 v[62:65], v[140:143], v[172:175], v[62:65]
	v_mfma_f32_16x16x32_bf16 v[58:61], v[148:151], v[172:175], v[58:61]
	v_mfma_f32_16x16x32_bf16 v[54:57], v[140:143], v[180:183], v[54:57]
	v_mfma_f32_16x16x32_bf16 v[50:53], v[148:151], v[180:183], v[50:53]
	v_mfma_f32_16x16x32_bf16 v[38:41], v[140:143], v[188:191], v[38:41]
	v_mfma_f32_16x16x32_bf16 v[34:37], v[148:151], v[188:191], v[34:37]
	v_mfma_f32_16x16x32_bf16 v[22:25], v[140:143], v[204:207], v[22:25]
	v_mfma_f32_16x16x32_bf16 v[18:21], v[148:151], v[204:207], v[18:21]
	v_mfma_f32_16x16x32_bf16 v[62:65], v[144:147], v[176:179], v[62:65]
	v_mfma_f32_16x16x32_bf16 v[58:61], v[152:155], v[176:179], v[58:61]
	v_mfma_f32_16x16x32_bf16 v[54:57], v[144:147], v[184:187], v[54:57]
	v_mfma_f32_16x16x32_bf16 v[50:53], v[152:155], v[184:187], v[50:53]
	v_mfma_f32_16x16x32_bf16 v[38:41], v[144:147], v[192:195], v[38:41]
	v_mfma_f32_16x16x32_bf16 v[34:37], v[152:155], v[192:195], v[34:37]
	v_mfma_f32_16x16x32_bf16 v[22:25], v[144:147], v[208:211], v[22:25]
	v_mfma_f32_16x16x32_bf16 v[18:21], v[152:155], v[208:211], v[18:21]
	v_mfma_f32_16x16x32_bf16 v[46:49], v[156:159], v[172:175], v[46:49]
	v_mfma_f32_16x16x32_bf16 v[42:45], v[164:167], v[172:175], v[42:45]
	v_mfma_f32_16x16x32_bf16 v[30:33], v[156:159], v[180:183], v[30:33]
	v_mfma_f32_16x16x32_bf16 v[26:29], v[164:167], v[180:183], v[26:29]
	v_mfma_f32_16x16x32_bf16 v[14:17], v[156:159], v[188:191], v[14:17]
	v_mfma_f32_16x16x32_bf16 v[10:13], v[164:167], v[188:191], v[10:13]
	v_mfma_f32_16x16x32_bf16 v[6:9], v[156:159], v[204:207], v[6:9]
	v_mfma_f32_16x16x32_bf16 v[2:5], v[164:167], v[204:207], v[2:5]
	v_mfma_f32_16x16x32_bf16 v[46:49], v[160:163], v[176:179], v[46:49]
	v_mfma_f32_16x16x32_bf16 v[42:45], v[168:171], v[176:179], v[42:45]
	v_mfma_f32_16x16x32_bf16 v[30:33], v[160:163], v[184:187], v[30:33]
	v_mfma_f32_16x16x32_bf16 v[26:29], v[168:171], v[184:187], v[26:29]
	v_mfma_f32_16x16x32_bf16 v[14:17], v[160:163], v[192:195], v[14:17]
	v_mfma_f32_16x16x32_bf16 v[10:13], v[168:171], v[192:195], v[10:13]
	v_mfma_f32_16x16x32_bf16 v[6:9], v[160:163], v[208:211], v[6:9]
	v_mfma_f32_16x16x32_bf16 v[2:5], v[168:171], v[208:211], v[2:5]
	s_setprio 0
	s_barrier
	v_add_u32_e32 v139, s56, v1
	ds_read_b128 v[140:143], v139
	ds_read_b128 v[144:147], v139 offset:1024
	ds_read_b128 v[148:151], v139 offset:2048
	ds_read_b128 v[152:155], v139 offset:3072
	v_add_u32_e32 v139, s55, v1
	ds_read_b128 v[156:159], v139
	ds_read_b128 v[160:163], v139 offset:1024
	ds_read_b128 v[164:167], v139 offset:2048
	ds_read_b128 v[168:171], v139 offset:3072
	s_mov_b32 m0, s46
	v_lshl_add_u64 v[230:231], s[14:15], 0, v[130:131]
	ds_read_b128 v[172:175], v138 offset:32768
	ds_read_b128 v[176:179], v138 offset:33792
	ds_read_b128 v[180:183], v138 offset:34816
	ds_read_b128 v[184:187], v138 offset:35840
	ds_read_b128 v[188:191], v138 offset:36864
	ds_read_b128 v[192:195], v138 offset:37888
	ds_read_b128 v[204:207], v138 offset:38912
	ds_read_b128 v[208:211], v138 offset:39936
	global_load_lds_dwordx4 v[230:231], off
	s_mov_b32 m0, s47
	v_lshl_add_u64 v[230:231], s[14:15], 0, v[134:135]
	global_load_lds_dwordx4 v[230:231], off
	s_waitcnt vmcnt(8)
	s_waitcnt lgkmcnt(0)
	s_barrier
	s_setprio 1
	s_waitcnt lgkmcnt(0)
	v_mfma_f32_16x16x32_bf16 v[126:129], v[140:143], v[172:175], v[126:129]
	v_mfma_f32_16x16x32_bf16 v[122:125], v[148:151], v[172:175], v[122:125]
	v_mfma_f32_16x16x32_bf16 v[118:121], v[140:143], v[180:183], v[118:121]
	v_mfma_f32_16x16x32_bf16 v[114:117], v[148:151], v[180:183], v[114:117]
	v_mfma_f32_16x16x32_bf16 v[102:105], v[140:143], v[188:191], v[102:105]
	v_mfma_f32_16x16x32_bf16 v[98:101], v[148:151], v[188:191], v[98:101]
	v_mfma_f32_16x16x32_bf16 v[86:89], v[140:143], v[204:207], v[86:89]
	v_mfma_f32_16x16x32_bf16 v[82:85], v[148:151], v[204:207], v[82:85]
	v_mfma_f32_16x16x32_bf16 v[126:129], v[144:147], v[176:179], v[126:129]
	v_mfma_f32_16x16x32_bf16 v[122:125], v[152:155], v[176:179], v[122:125]
	v_mfma_f32_16x16x32_bf16 v[118:121], v[144:147], v[184:187], v[118:121]
	v_mfma_f32_16x16x32_bf16 v[114:117], v[152:155], v[184:187], v[114:117]
	v_mfma_f32_16x16x32_bf16 v[102:105], v[144:147], v[192:195], v[102:105]
	v_mfma_f32_16x16x32_bf16 v[98:101], v[152:155], v[192:195], v[98:101]
	v_mfma_f32_16x16x32_bf16 v[86:89], v[144:147], v[208:211], v[86:89]
	v_mfma_f32_16x16x32_bf16 v[82:85], v[152:155], v[208:211], v[82:85]
	v_mfma_f32_16x16x32_bf16 v[110:113], v[156:159], v[172:175], v[110:113]
	v_mfma_f32_16x16x32_bf16 v[106:109], v[164:167], v[172:175], v[106:109]
	v_mfma_f32_16x16x32_bf16 v[94:97], v[156:159], v[180:183], v[94:97]
	v_mfma_f32_16x16x32_bf16 v[90:93], v[164:167], v[180:183], v[90:93]
	v_mfma_f32_16x16x32_bf16 v[78:81], v[156:159], v[188:191], v[78:81]
	v_mfma_f32_16x16x32_bf16 v[74:77], v[164:167], v[188:191], v[74:77]
	v_mfma_f32_16x16x32_bf16 v[70:73], v[156:159], v[204:207], v[70:73]
	v_mfma_f32_16x16x32_bf16 v[66:69], v[164:167], v[204:207], v[66:69]
	v_mfma_f32_16x16x32_bf16 v[110:113], v[160:163], v[176:179], v[110:113]
	v_mfma_f32_16x16x32_bf16 v[106:109], v[168:171], v[176:179], v[106:109]
	v_mfma_f32_16x16x32_bf16 v[94:97], v[160:163], v[184:187], v[94:97]
	v_mfma_f32_16x16x32_bf16 v[90:93], v[168:171], v[184:187], v[90:93]
	v_mfma_f32_16x16x32_bf16 v[78:81], v[160:163], v[192:195], v[78:81]
	v_mfma_f32_16x16x32_bf16 v[74:77], v[168:171], v[192:195], v[74:77]
	v_mfma_f32_16x16x32_bf16 v[70:73], v[160:163], v[208:211], v[70:73]
	v_mfma_f32_16x16x32_bf16 v[66:69], v[168:171], v[208:211], v[66:69]
	s_setprio 0
	s_barrier
	s_mov_b32 m0, s54
	v_lshl_add_u64 v[212:213], v[212:213], 0, s[64:65]
	ds_read_b128 v[172:175], v138 offset:49152
	ds_read_b128 v[176:179], v138 offset:50176
	ds_read_b128 v[180:183], v138 offset:51200
	ds_read_b128 v[184:187], v138 offset:52224
	ds_read_b128 v[188:191], v138 offset:53248
	ds_read_b128 v[192:195], v138 offset:54272
	ds_read_b128 v[204:207], v138 offset:55296
	ds_read_b128 v[208:211], v138 offset:56320
	global_load_lds_dwordx4 v[212:213], off
	s_mov_b32 m0, s53
	v_lshl_add_u64 v[212:213], v[214:215], 0, s[64:65]
	global_load_lds_dwordx4 v[212:213], off
	s_mov_b32 m0, s62
	v_lshl_add_u64 v[212:213], s[12:13], 0, v[132:133]
	global_load_lds_dwordx4 v[212:213], off
	s_mov_b32 m0, s61
	v_lshl_add_u64 v[212:213], s[12:13], 0, v[136:137]
	global_load_lds_dwordx4 v[212:213], off
	s_mov_b32 m0, s51
	v_lshl_add_u64 v[212:213], v[216:217], 0, s[94:95]
	global_load_lds_dwordx4 v[212:213], off
	s_mov_b32 m0, s52
	v_lshl_add_u64 v[212:213], v[228:229], 0, s[94:95]
	global_load_lds_dwordx4 v[212:213], off
	s_waitcnt vmcnt(8)
	s_waitcnt lgkmcnt(0)
	s_barrier
	s_setprio 1
	s_waitcnt lgkmcnt(0)
	v_mfma_f32_16x16x32_bf16 v[62:65], v[140:143], v[172:175], v[62:65]
	v_mfma_f32_16x16x32_bf16 v[58:61], v[148:151], v[172:175], v[58:61]
	v_mfma_f32_16x16x32_bf16 v[54:57], v[140:143], v[180:183], v[54:57]
	v_mfma_f32_16x16x32_bf16 v[50:53], v[148:151], v[180:183], v[50:53]
	v_mfma_f32_16x16x32_bf16 v[38:41], v[140:143], v[188:191], v[38:41]
	v_mfma_f32_16x16x32_bf16 v[34:37], v[148:151], v[188:191], v[34:37]
	v_mfma_f32_16x16x32_bf16 v[22:25], v[140:143], v[204:207], v[22:25]
	v_mfma_f32_16x16x32_bf16 v[18:21], v[148:151], v[204:207], v[18:21]
	v_mfma_f32_16x16x32_bf16 v[62:65], v[144:147], v[176:179], v[62:65]
	v_mfma_f32_16x16x32_bf16 v[58:61], v[152:155], v[176:179], v[58:61]
	v_mfma_f32_16x16x32_bf16 v[54:57], v[144:147], v[184:187], v[54:57]
	v_mfma_f32_16x16x32_bf16 v[50:53], v[152:155], v[184:187], v[50:53]
	v_mfma_f32_16x16x32_bf16 v[38:41], v[144:147], v[192:195], v[38:41]
	v_mfma_f32_16x16x32_bf16 v[34:37], v[152:155], v[192:195], v[34:37]
	v_mfma_f32_16x16x32_bf16 v[22:25], v[144:147], v[208:211], v[22:25]
	v_mfma_f32_16x16x32_bf16 v[18:21], v[152:155], v[208:211], v[18:21]
	v_mfma_f32_16x16x32_bf16 v[46:49], v[156:159], v[172:175], v[46:49]
	v_mfma_f32_16x16x32_bf16 v[42:45], v[164:167], v[172:175], v[42:45]
	v_mfma_f32_16x16x32_bf16 v[30:33], v[156:159], v[180:183], v[30:33]
	v_mfma_f32_16x16x32_bf16 v[26:29], v[164:167], v[180:183], v[26:29]
	v_mfma_f32_16x16x32_bf16 v[14:17], v[156:159], v[188:191], v[14:17]
	v_mfma_f32_16x16x32_bf16 v[10:13], v[164:167], v[188:191], v[10:13]
	v_mfma_f32_16x16x32_bf16 v[6:9], v[156:159], v[204:207], v[6:9]
	v_mfma_f32_16x16x32_bf16 v[2:5], v[164:167], v[204:207], v[2:5]
	v_mfma_f32_16x16x32_bf16 v[46:49], v[160:163], v[176:179], v[46:49]
	v_mfma_f32_16x16x32_bf16 v[42:45], v[168:171], v[176:179], v[42:45]
	v_mfma_f32_16x16x32_bf16 v[30:33], v[160:163], v[184:187], v[30:33]
	v_mfma_f32_16x16x32_bf16 v[26:29], v[168:171], v[184:187], v[26:29]
	v_mfma_f32_16x16x32_bf16 v[14:17], v[160:163], v[192:195], v[14:17]
	v_mfma_f32_16x16x32_bf16 v[10:13], v[168:171], v[192:195], v[10:13]
	v_mfma_f32_16x16x32_bf16 v[6:9], v[160:163], v[208:211], v[6:9]
	v_mfma_f32_16x16x32_bf16 v[2:5], v[168:171], v[208:211], v[2:5]
	s_setprio 0
	s_barrier
	s_andn2_b64 vcc, exec, s[8:9]
	s_mov_b64 s[12:13], -1
	s_mov_b64 s[8:9], 0
	s_movk_i32 s14, 0x100
	s_cbranch_vccz .LBB0_252
	s_cmpk_lt_u32 s42, 0x100
	s_cbranch_scc0 .LBB0_255
	s_barrier

.LBB0_260:
	s_add_i32 s15, s14, 0x100
	s_and_b64 s[12:13], s[12:13], exec
	s_cselect_b32 s13, 0, s15
	s_cselect_b32 s12, 0, 0
	s_add_u32 s16, s2, s13
	s_addc_u32 s17, s3, s12
	s_add_i32 s56, 0, 0x10000
	s_add_u32 s18, s4, s13
	s_addc_u32 s19, s5, s12
	s_add_i32 s13, 0, 0x14000
	s_add_u32 s22, s6, s14
	s_addc_u32 s23, s7, 0
	s_add_i32 s55, s56, s39
	s_add_i32 m0, s40, 0xc000
	s_add_i32 s58, s40, 0xe000
	s_add_i32 s52, s55, 0x2000
	v_add_u32_e32 v139, s56, v1
	s_add_u32 s20, s18, 0x40000
	ds_read_b128 v[140:143], v139
	ds_read_b128 v[144:147], v139 offset:1024
	ds_read_b128 v[148:151], v139 offset:2048
	ds_read_b128 v[152:155], v139 offset:3072
	v_add_u32_e32 v139, s13, v1
	s_addc_u32 s21, s19, 0
	s_add_i32 s54, s13, s39
	ds_read_b128 v[156:159], v139
	ds_read_b128 v[160:163], v139 offset:1024
	ds_read_b128 v[164:167], v139 offset:2048
	ds_read_b128 v[168:171], v139 offset:3072
	s_add_i32 s53, s54, 0x2000
	s_add_i32 s51, 0, 0x18000
	s_add_i32 s50, 0, 0x1c000
	s_add_u32 s14, s16, 0x80000
	s_addc_u32 s15, s17, 0
	s_add_i32 s49, s51, s39
	s_add_i32 s48, s49, 0x2000
	s_add_u32 s12, s18, 0x40080
	s_addc_u32 s13, s19, 0
	s_add_i32 s57, s50, s39
	s_add_i32 s56, s57, 0x2000
	v_lshl_add_u64 v[212:213], s[22:23], 0, v[130:131]
	v_lshl_add_u64 v[212:213], v[212:213], 0, s[94:95]
	ds_read_b128 v[172:175], v138
	ds_read_b128 v[176:179], v138 offset:1024
	ds_read_b128 v[180:183], v138 offset:2048
	ds_read_b128 v[184:187], v138 offset:3072
	ds_read_b128 v[188:191], v138 offset:4096
	ds_read_b128 v[192:195], v138 offset:5120
	ds_read_b128 v[204:207], v138 offset:6144
	ds_read_b128 v[208:211], v138 offset:7168
	global_load_lds_dwordx4 v[212:213], off
	v_lshl_add_u64 v[212:213], s[22:23], 0, v[134:135]
	s_mov_b32 m0, s58
	v_lshl_add_u64 v[212:213], v[212:213], 0, s[94:95]
	global_load_lds_dwordx4 v[212:213], off
	s_waitcnt vmcnt(8)
	s_waitcnt lgkmcnt(0)
	s_barrier
	s_setprio 1
	s_waitcnt lgkmcnt(0)
	v_mfma_f32_16x16x32_bf16 v[126:129], v[140:143], v[172:175], v[126:129]
	v_mfma_f32_16x16x32_bf16 v[122:125], v[148:151], v[172:175], v[122:125]
	v_mfma_f32_16x16x32_bf16 v[118:121], v[140:143], v[180:183], v[118:121]
	v_mfma_f32_16x16x32_bf16 v[114:117], v[148:151], v[180:183], v[114:117]
	v_mfma_f32_16x16x32_bf16 v[102:105], v[140:143], v[188:191], v[102:105]
	v_mfma_f32_16x16x32_bf16 v[98:101], v[148:151], v[188:191], v[98:101]
	v_mfma_f32_16x16x32_bf16 v[86:89], v[140:143], v[204:207], v[86:89]
	v_mfma_f32_16x16x32_bf16 v[82:85], v[148:151], v[204:207], v[82:85]
	v_mfma_f32_16x16x32_bf16 v[126:129], v[144:147], v[176:179], v[126:129]
	v_mfma_f32_16x16x32_bf16 v[122:125], v[152:155], v[176:179], v[122:125]
	v_mfma_f32_16x16x32_bf16 v[118:121], v[144:147], v[184:187], v[118:121]
	v_mfma_f32_16x16x32_bf16 v[114:117], v[152:155], v[184:187], v[114:117]
	v_mfma_f32_16x16x32_bf16 v[102:105], v[144:147], v[192:195], v[102:105]
	v_mfma_f32_16x16x32_bf16 v[98:101], v[152:155], v[192:195], v[98:101]
	v_mfma_f32_16x16x32_bf16 v[86:89], v[144:147], v[208:211], v[86:89]
	v_mfma_f32_16x16x32_bf16 v[82:85], v[152:155], v[208:211], v[82:85]
	v_mfma_f32_16x16x32_bf16 v[110:113], v[156:159], v[172:175], v[110:113]
	v_mfma_f32_16x16x32_bf16 v[106:109], v[164:167], v[172:175], v[106:109]
	v_mfma_f32_16x16x32_bf16 v[94:97], v[156:159], v[180:183], v[94:97]
	v_mfma_f32_16x16x32_bf16 v[90:93], v[164:167], v[180:183], v[90:93]
	v_mfma_f32_16x16x32_bf16 v[78:81], v[156:159], v[188:191], v[78:81]
	v_mfma_f32_16x16x32_bf16 v[74:77], v[164:167], v[188:191], v[74:77]
	v_mfma_f32_16x16x32_bf16 v[70:73], v[156:159], v[204:207], v[70:73]
	v_mfma_f32_16x16x32_bf16 v[66:69], v[164:167], v[204:207], v[66:69]
	v_mfma_f32_16x16x32_bf16 v[110:113], v[160:163], v[176:179], v[110:113]
	v_mfma_f32_16x16x32_bf16 v[106:109], v[168:171], v[176:179], v[106:109]
	v_mfma_f32_16x16x32_bf16 v[94:97], v[160:163], v[184:187], v[94:97]
	v_mfma_f32_16x16x32_bf16 v[90:93], v[168:171], v[184:187], v[90:93]
	v_mfma_f32_16x16x32_bf16 v[78:81], v[160:163], v[192:195], v[78:81]
	v_mfma_f32_16x16x32_bf16 v[74:77], v[168:171], v[192:195], v[74:77]
	v_mfma_f32_16x16x32_bf16 v[70:73], v[160:163], v[208:211], v[70:73]
	v_mfma_f32_16x16x32_bf16 v[66:69], v[168:171], v[208:211], v[66:69]
	s_setprio 0
	s_barrier
	s_mov_b32 m0, s55
	v_lshl_add_u64 v[212:213], s[18:19], 0, v[132:133]
	ds_read_b128 v[172:175], v138 offset:16384
	ds_read_b128 v[176:179], v138 offset:17408
	ds_read_b128 v[180:183], v138 offset:18432
	ds_read_b128 v[184:187], v138 offset:19456
	ds_read_b128 v[188:191], v138 offset:20480
	ds_read_b128 v[192:195], v138 offset:21504
	ds_read_b128 v[204:207], v138 offset:22528
	ds_read_b128 v[208:211], v138 offset:23552
	global_load_lds_dwordx4 v[212:213], off
	v_lshl_add_u64 v[214:215], s[18:19], 0, v[136:137]
	s_mov_b32 m0, s52
	v_lshl_add_u64 v[216:217], s[20:21], 0, v[132:133]
	global_load_lds_dwordx4 v[214:215], off
	s_mov_b32 m0, s54
	v_lshl_add_u64 v[228:229], s[16:17], 0, v[134:135]
	global_load_lds_dwordx4 v[216:217], off
	s_mov_b32 m0, s53
	v_lshl_add_u64 v[216:217], s[20:21], 0, v[136:137]
	global_load_lds_dwordx4 v[216:217], off
	s_mov_b32 m0, s40
	v_lshl_add_u64 v[216:217], s[16:17], 0, v[130:131]
	global_load_lds_dwordx4 v[216:217], off
	s_mov_b32 m0, s41
	s_nop 0
	global_load_lds_dwordx4 v[228:229], off
	s_waitcnt vmcnt(8)
	s_waitcnt lgkmcnt(0)
	s_barrier
	s_setprio 1
	s_waitcnt lgkmcnt(0)
	v_mfma_f32_16x16x32_bf16 v[62:65], v[140:143], v[172:175], v[62:65]
	v_mfma_f32_16x16x32_bf16 v[58:61], v[148:151], v[172:175], v[58:61]
	v_mfma_f32_16x16x32_bf16 v[54:57], v[140:143], v[180:183], v[54:57]
	v_mfma_f32_16x16x32_bf16 v[50:53], v[148:151], v[180:183], v[50:53]
	v_mfma_f32_16x16x32_bf16 v[38:41], v[140:143], v[188:191], v[38:41]
	v_mfma_f32_16x16x32_bf16 v[34:37], v[148:151], v[188:191], v[34:37]
	v_mfma_f32_16x16x32_bf16 v[22:25], v[140:143], v[204:207], v[22:25]
	v_mfma_f32_16x16x32_bf16 v[18:21], v[148:151], v[204:207], v[18:21]
	v_mfma_f32_16x16x32_bf16 v[62:65], v[144:147], v[176:179], v[62:65]
	v_mfma_f32_16x16x32_bf16 v[58:61], v[152:155], v[176:179], v[58:61]
	v_mfma_f32_16x16x32_bf16 v[54:57], v[144:147], v[184:187], v[54:57]
	v_mfma_f32_16x16x32_bf16 v[50:53], v[152:155], v[184:187], v[50:53]
	v_mfma_f32_16x16x32_bf16 v[38:41], v[144:147], v[192:195], v[38:41]
	v_mfma_f32_16x16x32_bf16 v[34:37], v[152:155], v[192:195], v[34:37]
	v_mfma_f32_16x16x32_bf16 v[22:25], v[144:147], v[208:211], v[22:25]
	v_mfma_f32_16x16x32_bf16 v[18:21], v[152:155], v[208:211], v[18:21]
	v_mfma_f32_16x16x32_bf16 v[46:49], v[156:159], v[172:175], v[46:49]
	v_mfma_f32_16x16x32_bf16 v[42:45], v[164:167], v[172:175], v[42:45]
	v_mfma_f32_16x16x32_bf16 v[30:33], v[156:159], v[180:183], v[30:33]
	v_mfma_f32_16x16x32_bf16 v[26:29], v[164:167], v[180:183], v[26:29]
	v_mfma_f32_16x16x32_bf16 v[14:17], v[156:159], v[188:191], v[14:17]
	v_mfma_f32_16x16x32_bf16 v[10:13], v[164:167], v[188:191], v[10:13]
	v_mfma_f32_16x16x32_bf16 v[6:9], v[156:159], v[204:207], v[6:9]
	v_mfma_f32_16x16x32_bf16 v[2:5], v[164:167], v[204:207], v[2:5]
	v_mfma_f32_16x16x32_bf16 v[46:49], v[160:163], v[176:179], v[46:49]
	v_mfma_f32_16x16x32_bf16 v[42:45], v[168:171], v[176:179], v[42:45]
	v_mfma_f32_16x16x32_bf16 v[30:33], v[160:163], v[184:187], v[30:33]
	v_mfma_f32_16x16x32_bf16 v[26:29], v[168:171], v[184:187], v[26:29]
	v_mfma_f32_16x16x32_bf16 v[14:17], v[160:163], v[192:195], v[14:17]
	v_mfma_f32_16x16x32_bf16 v[10:13], v[168:171], v[192:195], v[10:13]
	v_mfma_f32_16x16x32_bf16 v[6:9], v[160:163], v[208:211], v[6:9]
	v_mfma_f32_16x16x32_bf16 v[2:5], v[168:171], v[208:211], v[2:5]
	s_setprio 0
	s_barrier
	v_add_u32_e32 v139, s51, v1
	ds_read_b128 v[140:143], v139
	ds_read_b128 v[144:147], v139 offset:1024
	ds_read_b128 v[148:151], v139 offset:2048
	ds_read_b128 v[152:155], v139 offset:3072
	v_add_u32_e32 v139, s50, v1
	ds_read_b128 v[156:159], v139
	ds_read_b128 v[160:163], v139 offset:1024
	ds_read_b128 v[164:167], v139 offset:2048
	ds_read_b128 v[168:171], v139 offset:3072
	s_mov_b32 m0, s42
	v_lshl_add_u64 v[230:231], s[14:15], 0, v[130:131]
	ds_read_b128 v[172:175], v138 offset:32768
	ds_read_b128 v[176:179], v138 offset:33792
	ds_read_b128 v[180:183], v138 offset:34816
	ds_read_b128 v[184:187], v138 offset:35840
	ds_read_b128 v[188:191], v138 offset:36864
	ds_read_b128 v[192:195], v138 offset:37888
	ds_read_b128 v[204:207], v138 offset:38912
	ds_read_b128 v[208:211], v138 offset:39936
	global_load_lds_dwordx4 v[230:231], off
	s_mov_b32 m0, s43
	v_lshl_add_u64 v[230:231], s[14:15], 0, v[134:135]
	global_load_lds_dwordx4 v[230:231], off
	s_waitcnt vmcnt(8)
	s_waitcnt lgkmcnt(0)
	s_barrier
	s_setprio 1
	s_waitcnt lgkmcnt(0)
	v_mfma_f32_16x16x32_bf16 v[126:129], v[140:143], v[172:175], v[126:129]
	v_mfma_f32_16x16x32_bf16 v[122:125], v[148:151], v[172:175], v[122:125]
	v_mfma_f32_16x16x32_bf16 v[118:121], v[140:143], v[180:183], v[118:121]
	v_mfma_f32_16x16x32_bf16 v[114:117], v[148:151], v[180:183], v[114:117]
	v_mfma_f32_16x16x32_bf16 v[102:105], v[140:143], v[188:191], v[102:105]
	v_mfma_f32_16x16x32_bf16 v[98:101], v[148:151], v[188:191], v[98:101]
	v_mfma_f32_16x16x32_bf16 v[86:89], v[140:143], v[204:207], v[86:89]
	v_mfma_f32_16x16x32_bf16 v[82:85], v[148:151], v[204:207], v[82:85]
	v_mfma_f32_16x16x32_bf16 v[126:129], v[144:147], v[176:179], v[126:129]
	v_mfma_f32_16x16x32_bf16 v[122:125], v[152:155], v[176:179], v[122:125]
	v_mfma_f32_16x16x32_bf16 v[118:121], v[144:147], v[184:187], v[118:121]
	v_mfma_f32_16x16x32_bf16 v[114:117], v[152:155], v[184:187], v[114:117]
	v_mfma_f32_16x16x32_bf16 v[102:105], v[144:147], v[192:195], v[102:105]
	v_mfma_f32_16x16x32_bf16 v[98:101], v[152:155], v[192:195], v[98:101]
	v_mfma_f32_16x16x32_bf16 v[86:89], v[144:147], v[208:211], v[86:89]
	v_mfma_f32_16x16x32_bf16 v[82:85], v[152:155], v[208:211], v[82:85]
	v_mfma_f32_16x16x32_bf16 v[110:113], v[156:159], v[172:175], v[110:113]
	v_mfma_f32_16x16x32_bf16 v[106:109], v[164:167], v[172:175], v[106:109]
	v_mfma_f32_16x16x32_bf16 v[94:97], v[156:159], v[180:183], v[94:97]
	v_mfma_f32_16x16x32_bf16 v[90:93], v[164:167], v[180:183], v[90:93]
	v_mfma_f32_16x16x32_bf16 v[78:81], v[156:159], v[188:191], v[78:81]
	v_mfma_f32_16x16x32_bf16 v[74:77], v[164:167], v[188:191], v[74:77]
	v_mfma_f32_16x16x32_bf16 v[70:73], v[156:159], v[204:207], v[70:73]
	v_mfma_f32_16x16x32_bf16 v[66:69], v[164:167], v[204:207], v[66:69]
	v_mfma_f32_16x16x32_bf16 v[110:113], v[160:163], v[176:179], v[110:113]
	v_mfma_f32_16x16x32_bf16 v[106:109], v[168:171], v[176:179], v[106:109]
	v_mfma_f32_16x16x32_bf16 v[94:97], v[160:163], v[184:187], v[94:97]
	v_mfma_f32_16x16x32_bf16 v[90:93], v[168:171], v[184:187], v[90:93]
	v_mfma_f32_16x16x32_bf16 v[78:81], v[160:163], v[192:195], v[78:81]
	v_mfma_f32_16x16x32_bf16 v[74:77], v[168:171], v[192:195], v[74:77]
	v_mfma_f32_16x16x32_bf16 v[70:73], v[160:163], v[208:211], v[70:73]
	v_mfma_f32_16x16x32_bf16 v[66:69], v[168:171], v[208:211], v[66:69]
	s_setprio 0
	s_barrier
	s_mov_b32 m0, s49
	v_lshl_add_u64 v[212:213], v[212:213], 0, s[94:95]
	ds_read_b128 v[172:175], v138 offset:49152
	ds_read_b128 v[176:179], v138 offset:50176
	ds_read_b128 v[180:183], v138 offset:51200
	ds_read_b128 v[184:187], v138 offset:52224
	ds_read_b128 v[188:191], v138 offset:53248
	ds_read_b128 v[192:195], v138 offset:54272
	ds_read_b128 v[204:207], v138 offset:55296
	ds_read_b128 v[208:211], v138 offset:56320
	global_load_lds_dwordx4 v[212:213], off
	s_mov_b32 m0, s48
	v_lshl_add_u64 v[212:213], v[214:215], 0, s[94:95]
	global_load_lds_dwordx4 v[212:213], off
	s_mov_b32 m0, s57
	v_lshl_add_u64 v[212:213], s[12:13], 0, v[132:133]
	global_load_lds_dwordx4 v[212:213], off
	s_mov_b32 m0, s56
	v_lshl_add_u64 v[212:213], s[12:13], 0, v[136:137]
	global_load_lds_dwordx4 v[212:213], off
	s_mov_b32 m0, s46
	v_lshl_add_u64 v[212:213], v[216:217], 0, s[94:95]
	global_load_lds_dwordx4 v[212:213], off
	s_mov_b32 m0, s47
	v_lshl_add_u64 v[212:213], v[228:229], 0, s[94:95]
	global_load_lds_dwordx4 v[212:213], off
	s_waitcnt vmcnt(8)
	s_waitcnt lgkmcnt(0)
	s_barrier
	s_setprio 1
	s_waitcnt lgkmcnt(0)
	v_mfma_f32_16x16x32_bf16 v[62:65], v[140:143], v[172:175], v[62:65]
	v_mfma_f32_16x16x32_bf16 v[58:61], v[148:151], v[172:175], v[58:61]
	v_mfma_f32_16x16x32_bf16 v[54:57], v[140:143], v[180:183], v[54:57]
	v_mfma_f32_16x16x32_bf16 v[50:53], v[148:151], v[180:183], v[50:53]
	v_mfma_f32_16x16x32_bf16 v[38:41], v[140:143], v[188:191], v[38:41]
	v_mfma_f32_16x16x32_bf16 v[34:37], v[148:151], v[188:191], v[34:37]
	v_mfma_f32_16x16x32_bf16 v[22:25], v[140:143], v[204:207], v[22:25]
	v_mfma_f32_16x16x32_bf16 v[18:21], v[148:151], v[204:207], v[18:21]
	v_mfma_f32_16x16x32_bf16 v[62:65], v[144:147], v[176:179], v[62:65]
	v_mfma_f32_16x16x32_bf16 v[58:61], v[152:155], v[176:179], v[58:61]
	v_mfma_f32_16x16x32_bf16 v[54:57], v[144:147], v[184:187], v[54:57]
	v_mfma_f32_16x16x32_bf16 v[50:53], v[152:155], v[184:187], v[50:53]
	v_mfma_f32_16x16x32_bf16 v[38:41], v[144:147], v[192:195], v[38:41]
	v_mfma_f32_16x16x32_bf16 v[34:37], v[152:155], v[192:195], v[34:37]
	v_mfma_f32_16x16x32_bf16 v[22:25], v[144:147], v[208:211], v[22:25]
	v_mfma_f32_16x16x32_bf16 v[18:21], v[152:155], v[208:211], v[18:21]
	v_mfma_f32_16x16x32_bf16 v[46:49], v[156:159], v[172:175], v[46:49]
	v_mfma_f32_16x16x32_bf16 v[42:45], v[164:167], v[172:175], v[42:45]
	v_mfma_f32_16x16x32_bf16 v[30:33], v[156:159], v[180:183], v[30:33]
	v_mfma_f32_16x16x32_bf16 v[26:29], v[164:167], v[180:183], v[26:29]
	v_mfma_f32_16x16x32_bf16 v[14:17], v[156:159], v[188:191], v[14:17]
	v_mfma_f32_16x16x32_bf16 v[10:13], v[164:167], v[188:191], v[10:13]
	v_mfma_f32_16x16x32_bf16 v[6:9], v[156:159], v[204:207], v[6:9]
	v_mfma_f32_16x16x32_bf16 v[2:5], v[164:167], v[204:207], v[2:5]
	v_mfma_f32_16x16x32_bf16 v[46:49], v[160:163], v[176:179], v[46:49]
	v_mfma_f32_16x16x32_bf16 v[42:45], v[168:171], v[176:179], v[42:45]
	v_mfma_f32_16x16x32_bf16 v[30:33], v[160:163], v[184:187], v[30:33]
	v_mfma_f32_16x16x32_bf16 v[26:29], v[168:171], v[184:187], v[26:29]
	v_mfma_f32_16x16x32_bf16 v[14:17], v[160:163], v[192:195], v[14:17]
	v_mfma_f32_16x16x32_bf16 v[10:13], v[168:171], v[192:195], v[10:13]
	v_mfma_f32_16x16x32_bf16 v[6:9], v[160:163], v[208:211], v[6:9]
	v_mfma_f32_16x16x32_bf16 v[2:5], v[168:171], v[208:211], v[2:5]
	s_setprio 0
	s_barrier
	s_andn2_b64 vcc, exec, s[8:9]
	s_mov_b64 s[12:13], -1
	s_mov_b64 s[8:9], 0
	s_movk_i32 s14, 0x100
	s_cbranch_vccz .LBB0_260
	s_cmpk_lt_u32 s38, 0x100
	s_cbranch_scc0 .LBB0_246
	s_barrier
	s_branch .LBB0_246

.LBB0_326:
	s_add_u32 s30, s28, 0xfffc0080
	s_addc_u32 s31, s29, -1
	s_add_i32 s72, 0, 0x10000
	s_cmp_eq_u32 s71, 12
	s_cselect_b32 s35, s5, s31
	s_cselect_b32 s34, s21, s30
	s_cselect_b32 s31, s19, s70
	s_cselect_b32 s30, s36, s37
	s_add_i32 s74, 0, 0x14000
	v_add_u32_e32 v154, s72, v1
	v_add_u32_e32 v167, s74, v1
	ds_read_b128 v[142:145], v154
	ds_read_b128 v[146:149], v154 offset:1024
	ds_read_b128 v[150:153], v154 offset:2048
	ds_read_b128 v[154:157], v154 offset:3072
	ds_read_b128 v[158:161], v167
	ds_read_b128 v[162:165], v167 offset:1024
	ds_read_b128 v[168:171], v167 offset:2048
	ds_read_b128 v[172:175], v167 offset:3072
	v_lshl_add_u64 v[216:217], s[28:29], 0, v[138:139]
	s_add_i32 m0, s27, 0xc000
	ds_read_b128 v[176:179], v166
	ds_read_b128 v[180:183], v166 offset:1024
	ds_read_b128 v[184:187], v166 offset:2048
	ds_read_b128 v[188:191], v166 offset:3072
	ds_read_b128 v[192:195], v166 offset:4096
	ds_read_b128 v[204:207], v166 offset:5120
	ds_read_b128 v[208:211], v166 offset:6144
	ds_read_b128 v[212:215], v166 offset:7168
	global_load_lds_dwordx4 v[216:217], off
	s_add_i32 m0, s27, 0xe000
	v_lshl_add_u64 v[216:217], s[28:29], 0, v[140:141]
	global_load_lds_dwordx4 v[216:217], off
	s_waitcnt vmcnt(8)
	s_waitcnt lgkmcnt(0)
	s_barrier
	s_setprio 1
	s_waitcnt lgkmcnt(0)
	v_mfma_f32_16x16x32_bf16 v[126:129], v[142:145], v[176:179], v[126:129]
	v_mfma_f32_16x16x32_bf16 v[122:125], v[150:153], v[176:179], v[122:125]
	v_mfma_f32_16x16x32_bf16 v[110:113], v[142:145], v[184:187], v[110:113]
	v_mfma_f32_16x16x32_bf16 v[106:109], v[150:153], v[184:187], v[106:109]
	v_mfma_f32_16x16x32_bf16 v[94:97], v[142:145], v[192:195], v[94:97]
	v_mfma_f32_16x16x32_bf16 v[90:93], v[150:153], v[192:195], v[90:93]
	v_mfma_f32_16x16x32_bf16 v[78:81], v[142:145], v[208:211], v[78:81]
	v_mfma_f32_16x16x32_bf16 v[74:77], v[150:153], v[208:211], v[74:77]
	v_mfma_f32_16x16x32_bf16 v[126:129], v[146:149], v[180:183], v[126:129]
	v_mfma_f32_16x16x32_bf16 v[122:125], v[154:157], v[180:183], v[122:125]
	v_mfma_f32_16x16x32_bf16 v[110:113], v[146:149], v[188:191], v[110:113]
	v_mfma_f32_16x16x32_bf16 v[106:109], v[154:157], v[188:191], v[106:109]
	v_mfma_f32_16x16x32_bf16 v[94:97], v[146:149], v[204:207], v[94:97]
	v_mfma_f32_16x16x32_bf16 v[90:93], v[154:157], v[204:207], v[90:93]
	v_mfma_f32_16x16x32_bf16 v[78:81], v[146:149], v[212:215], v[78:81]
	v_mfma_f32_16x16x32_bf16 v[74:77], v[154:157], v[212:215], v[74:77]
	v_mfma_f32_16x16x32_bf16 v[118:121], v[158:161], v[176:179], v[118:121]
	v_mfma_f32_16x16x32_bf16 v[114:117], v[168:171], v[176:179], v[114:117]
	v_mfma_f32_16x16x32_bf16 v[102:105], v[158:161], v[184:187], v[102:105]
	v_mfma_f32_16x16x32_bf16 v[98:101], v[168:171], v[184:187], v[98:101]
	v_mfma_f32_16x16x32_bf16 v[86:89], v[158:161], v[192:195], v[86:89]
	v_mfma_f32_16x16x32_bf16 v[82:85], v[168:171], v[192:195], v[82:85]
	v_mfma_f32_16x16x32_bf16 v[70:73], v[158:161], v[208:211], v[70:73]
	v_mfma_f32_16x16x32_bf16 v[66:69], v[168:171], v[208:211], v[66:69]
	v_mfma_f32_16x16x32_bf16 v[118:121], v[162:165], v[180:183], v[118:121]
	v_mfma_f32_16x16x32_bf16 v[114:117], v[172:175], v[180:183], v[114:117]
	v_mfma_f32_16x16x32_bf16 v[102:105], v[162:165], v[188:191], v[102:105]
	v_mfma_f32_16x16x32_bf16 v[98:101], v[172:175], v[188:191], v[98:101]
	v_mfma_f32_16x16x32_bf16 v[86:89], v[162:165], v[204:207], v[86:89]
	v_mfma_f32_16x16x32_bf16 v[82:85], v[172:175], v[204:207], v[82:85]
	v_mfma_f32_16x16x32_bf16 v[70:73], v[162:165], v[212:215], v[70:73]
	v_mfma_f32_16x16x32_bf16 v[66:69], v[172:175], v[212:215], v[66:69]
	s_setprio 0
	s_barrier
	s_add_i32 s72, s72, s44
	v_lshl_add_u64 v[216:217], s[30:31], 0, v[132:133]
	s_mov_b32 m0, s72
	ds_read_b128 v[176:179], v166 offset:16384
	ds_read_b128 v[180:183], v166 offset:17408
	ds_read_b128 v[184:187], v166 offset:18432
	ds_read_b128 v[188:191], v166 offset:19456
	ds_read_b128 v[192:195], v166 offset:20480
	ds_read_b128 v[204:207], v166 offset:21504
	ds_read_b128 v[208:211], v166 offset:22528
	ds_read_b128 v[212:215], v166 offset:23552
	global_load_lds_dwordx4 v[216:217], off
	s_add_i32 m0, s72, 0x2000
	s_add_u32 s72, s30, 0x40000
	v_lshl_add_u64 v[228:229], s[30:31], 0, v[136:137]
	s_addc_u32 s73, s31, 0
	s_add_i32 s74, s74, s44
	global_load_lds_dwordx4 v[228:229], off
	v_lshl_add_u64 v[230:231], s[72:73], 0, v[132:133]
	s_mov_b32 m0, s74
	v_lshl_add_u64 v[232:233], s[34:35], 0, v[134:135]
	global_load_lds_dwordx4 v[230:231], off
	s_add_i32 m0, s74, 0x2000
	v_lshl_add_u64 v[230:231], s[72:73], 0, v[136:137]
	global_load_lds_dwordx4 v[230:231], off
	s_mov_b32 m0, s27
	v_lshl_add_u64 v[230:231], s[34:35], 0, v[130:131]
	global_load_lds_dwordx4 v[230:231], off
	s_mov_b32 m0, s45
	s_nop 0
	global_load_lds_dwordx4 v[232:233], off
	s_waitcnt vmcnt(8)
	s_waitcnt lgkmcnt(0)
	s_barrier
	s_setprio 1
	s_waitcnt lgkmcnt(0)
	v_mfma_f32_16x16x32_bf16 v[62:65], v[142:145], v[176:179], v[62:65]
	v_mfma_f32_16x16x32_bf16 v[58:61], v[150:153], v[176:179], v[58:61]
	v_mfma_f32_16x16x32_bf16 v[46:49], v[142:145], v[184:187], v[46:49]
	v_mfma_f32_16x16x32_bf16 v[42:45], v[150:153], v[184:187], v[42:45]
	v_mfma_f32_16x16x32_bf16 v[30:33], v[142:145], v[192:195], v[30:33]
	v_mfma_f32_16x16x32_bf16 v[26:29], v[150:153], v[192:195], v[26:29]
	v_mfma_f32_16x16x32_bf16 v[14:17], v[142:145], v[208:211], v[14:17]
	v_mfma_f32_16x16x32_bf16 v[10:13], v[150:153], v[208:211], v[10:13]
	v_mfma_f32_16x16x32_bf16 v[62:65], v[146:149], v[180:183], v[62:65]
	v_mfma_f32_16x16x32_bf16 v[58:61], v[154:157], v[180:183], v[58:61]
	v_mfma_f32_16x16x32_bf16 v[46:49], v[146:149], v[188:191], v[46:49]
	v_mfma_f32_16x16x32_bf16 v[42:45], v[154:157], v[188:191], v[42:45]
	v_mfma_f32_16x16x32_bf16 v[30:33], v[146:149], v[204:207], v[30:33]
	v_mfma_f32_16x16x32_bf16 v[26:29], v[154:157], v[204:207], v[26:29]
	v_mfma_f32_16x16x32_bf16 v[14:17], v[146:149], v[212:215], v[14:17]
	v_mfma_f32_16x16x32_bf16 v[10:13], v[154:157], v[212:215], v[10:13]
	v_mfma_f32_16x16x32_bf16 v[54:57], v[158:161], v[176:179], v[54:57]
	v_mfma_f32_16x16x32_bf16 v[50:53], v[168:171], v[176:179], v[50:53]
	v_mfma_f32_16x16x32_bf16 v[38:41], v[158:161], v[184:187], v[38:41]
	v_mfma_f32_16x16x32_bf16 v[34:37], v[168:171], v[184:187], v[34:37]
	v_mfma_f32_16x16x32_bf16 v[22:25], v[158:161], v[192:195], v[22:25]
	v_mfma_f32_16x16x32_bf16 v[18:21], v[168:171], v[192:195], v[18:21]
	v_mfma_f32_16x16x32_bf16 v[6:9], v[158:161], v[208:211], v[6:9]
	v_mfma_f32_16x16x32_bf16 v[2:5], v[168:171], v[208:211], v[2:5]
	v_mfma_f32_16x16x32_bf16 v[54:57], v[162:165], v[180:183], v[54:57]
	v_mfma_f32_16x16x32_bf16 v[50:53], v[172:175], v[180:183], v[50:53]
	v_mfma_f32_16x16x32_bf16 v[38:41], v[162:165], v[188:191], v[38:41]
	v_mfma_f32_16x16x32_bf16 v[34:37], v[172:175], v[188:191], v[34:37]
	v_mfma_f32_16x16x32_bf16 v[22:25], v[162:165], v[204:207], v[22:25]
	v_mfma_f32_16x16x32_bf16 v[18:21], v[172:175], v[204:207], v[18:21]
	v_mfma_f32_16x16x32_bf16 v[6:9], v[162:165], v[212:215], v[6:9]
	v_mfma_f32_16x16x32_bf16 v[2:5], v[172:175], v[212:215], v[2:5]
	s_setprio 0
	s_barrier
	s_add_i32 s72, 0, 0x18000
	s_add_i32 s73, 0, 0x1c000
	v_add_u32_e32 v154, s72, v1
	v_add_u32_e32 v167, s73, v1
	ds_read_b128 v[142:145], v154
	ds_read_b128 v[146:149], v154 offset:1024
	ds_read_b128 v[150:153], v154 offset:2048
	ds_read_b128 v[154:157], v154 offset:3072
	ds_read_b128 v[158:161], v167
	ds_read_b128 v[162:165], v167 offset:1024
	ds_read_b128 v[168:171], v167 offset:2048
	ds_read_b128 v[172:175], v167 offset:3072
	s_add_u32 s34, s34, 0x40000
	s_addc_u32 s35, s35, 0
	s_mov_b32 m0, s46
	v_lshl_add_u64 v[234:235], s[34:35], 0, v[130:131]
	ds_read_b128 v[176:179], v166 offset:32768
	ds_read_b128 v[180:183], v166 offset:33792
	ds_read_b128 v[184:187], v166 offset:34816
	ds_read_b128 v[188:191], v166 offset:35840
	ds_read_b128 v[192:195], v166 offset:36864
	ds_read_b128 v[204:207], v166 offset:37888
	ds_read_b128 v[208:211], v166 offset:38912
	ds_read_b128 v[212:215], v166 offset:39936
	global_load_lds_dwordx4 v[234:235], off
	s_mov_b32 m0, s47
	v_lshl_add_u64 v[234:235], s[34:35], 0, v[134:135]
	global_load_lds_dwordx4 v[234:235], off
	s_waitcnt vmcnt(8)
	s_waitcnt lgkmcnt(0)
	s_barrier
	s_setprio 1
	s_waitcnt lgkmcnt(0)
	v_mfma_f32_16x16x32_bf16 v[126:129], v[142:145], v[176:179], v[126:129]
	v_mfma_f32_16x16x32_bf16 v[122:125], v[150:153], v[176:179], v[122:125]
	v_mfma_f32_16x16x32_bf16 v[110:113], v[142:145], v[184:187], v[110:113]
	v_mfma_f32_16x16x32_bf16 v[106:109], v[150:153], v[184:187], v[106:109]
	v_mfma_f32_16x16x32_bf16 v[94:97], v[142:145], v[192:195], v[94:97]
	v_mfma_f32_16x16x32_bf16 v[90:93], v[150:153], v[192:195], v[90:93]
	v_mfma_f32_16x16x32_bf16 v[78:81], v[142:145], v[208:211], v[78:81]
	v_mfma_f32_16x16x32_bf16 v[74:77], v[150:153], v[208:211], v[74:77]
	v_mfma_f32_16x16x32_bf16 v[126:129], v[146:149], v[180:183], v[126:129]
	v_mfma_f32_16x16x32_bf16 v[122:125], v[154:157], v[180:183], v[122:125]
	v_mfma_f32_16x16x32_bf16 v[110:113], v[146:149], v[188:191], v[110:113]
	v_mfma_f32_16x16x32_bf16 v[106:109], v[154:157], v[188:191], v[106:109]
	v_mfma_f32_16x16x32_bf16 v[94:97], v[146:149], v[204:207], v[94:97]
	v_mfma_f32_16x16x32_bf16 v[90:93], v[154:157], v[204:207], v[90:93]
	v_mfma_f32_16x16x32_bf16 v[78:81], v[146:149], v[212:215], v[78:81]
	v_mfma_f32_16x16x32_bf16 v[74:77], v[154:157], v[212:215], v[74:77]
	v_mfma_f32_16x16x32_bf16 v[118:121], v[158:161], v[176:179], v[118:121]
	v_mfma_f32_16x16x32_bf16 v[114:117], v[168:171], v[176:179], v[114:117]
	v_mfma_f32_16x16x32_bf16 v[102:105], v[158:161], v[184:187], v[102:105]
	v_mfma_f32_16x16x32_bf16 v[98:101], v[168:171], v[184:187], v[98:101]
	v_mfma_f32_16x16x32_bf16 v[86:89], v[158:161], v[192:195], v[86:89]
	v_mfma_f32_16x16x32_bf16 v[82:85], v[168:171], v[192:195], v[82:85]
	v_mfma_f32_16x16x32_bf16 v[70:73], v[158:161], v[208:211], v[70:73]
	v_mfma_f32_16x16x32_bf16 v[66:69], v[168:171], v[208:211], v[66:69]
	v_mfma_f32_16x16x32_bf16 v[118:121], v[162:165], v[180:183], v[118:121]
	v_mfma_f32_16x16x32_bf16 v[114:117], v[172:175], v[180:183], v[114:117]
	v_mfma_f32_16x16x32_bf16 v[102:105], v[162:165], v[188:191], v[102:105]
	v_mfma_f32_16x16x32_bf16 v[98:101], v[172:175], v[188:191], v[98:101]
	v_mfma_f32_16x16x32_bf16 v[86:89], v[162:165], v[204:207], v[86:89]
	v_mfma_f32_16x16x32_bf16 v[82:85], v[172:175], v[204:207], v[82:85]
	v_mfma_f32_16x16x32_bf16 v[70:73], v[162:165], v[212:215], v[70:73]
	v_mfma_f32_16x16x32_bf16 v[66:69], v[172:175], v[212:215], v[66:69]
	s_setprio 0
	s_barrier
	s_add_i32 s34, s72, s44
	v_lshl_add_u64 v[216:217], v[216:217], 0, s[94:95]
	s_mov_b32 m0, s34
	ds_read_b128 v[176:179], v166 offset:49152
	ds_read_b128 v[180:183], v166 offset:50176
	ds_read_b128 v[184:187], v166 offset:51200
	ds_read_b128 v[188:191], v166 offset:52224
	ds_read_b128 v[192:195], v166 offset:53248
	ds_read_b128 v[204:207], v166 offset:54272
	ds_read_b128 v[208:211], v166 offset:55296
	ds_read_b128 v[212:215], v166 offset:56320
	global_load_lds_dwordx4 v[216:217], off
	s_add_i32 m0, s34, 0x2000
	s_add_u32 s30, s30, 0x40080
	v_lshl_add_u64 v[216:217], v[228:229], 0, s[94:95]
	s_addc_u32 s31, s31, 0
	s_add_i32 s34, s73, s44
	global_load_lds_dwordx4 v[216:217], off
	s_mov_b32 m0, s34
	v_lshl_add_u64 v[216:217], s[30:31], 0, v[132:133]
	global_load_lds_dwordx4 v[216:217], off
	s_add_i32 m0, s34, 0x2000
	v_lshl_add_u64 v[216:217], s[30:31], 0, v[136:137]
	global_load_lds_dwordx4 v[216:217], off
	s_mov_b32 m0, s60
	v_lshl_add_u64 v[216:217], v[230:231], 0, s[94:95]
	global_load_lds_dwordx4 v[216:217], off
	s_mov_b32 m0, s61
	v_lshl_add_u64 v[216:217], v[232:233], 0, s[94:95]
	global_load_lds_dwordx4 v[216:217], off
	s_waitcnt vmcnt(8)
	s_waitcnt lgkmcnt(0)
	s_barrier
	s_setprio 1
	s_waitcnt lgkmcnt(0)
	v_mfma_f32_16x16x32_bf16 v[62:65], v[142:145], v[176:179], v[62:65]
	v_mfma_f32_16x16x32_bf16 v[58:61], v[150:153], v[176:179], v[58:61]
	v_mfma_f32_16x16x32_bf16 v[46:49], v[142:145], v[184:187], v[46:49]
	v_mfma_f32_16x16x32_bf16 v[42:45], v[150:153], v[184:187], v[42:45]
	v_mfma_f32_16x16x32_bf16 v[30:33], v[142:145], v[192:195], v[30:33]
	v_mfma_f32_16x16x32_bf16 v[26:29], v[150:153], v[192:195], v[26:29]
	v_mfma_f32_16x16x32_bf16 v[14:17], v[142:145], v[208:211], v[14:17]
	v_mfma_f32_16x16x32_bf16 v[10:13], v[150:153], v[208:211], v[10:13]
	v_mfma_f32_16x16x32_bf16 v[62:65], v[146:149], v[180:183], v[62:65]
	v_mfma_f32_16x16x32_bf16 v[58:61], v[154:157], v[180:183], v[58:61]
	v_mfma_f32_16x16x32_bf16 v[46:49], v[146:149], v[188:191], v[46:49]
	v_mfma_f32_16x16x32_bf16 v[42:45], v[154:157], v[188:191], v[42:45]
	v_mfma_f32_16x16x32_bf16 v[30:33], v[146:149], v[204:207], v[30:33]
	v_mfma_f32_16x16x32_bf16 v[26:29], v[154:157], v[204:207], v[26:29]
	v_mfma_f32_16x16x32_bf16 v[14:17], v[146:149], v[212:215], v[14:17]
	v_mfma_f32_16x16x32_bf16 v[10:13], v[154:157], v[212:215], v[10:13]
	v_mfma_f32_16x16x32_bf16 v[54:57], v[158:161], v[176:179], v[54:57]
	v_mfma_f32_16x16x32_bf16 v[50:53], v[168:171], v[176:179], v[50:53]
	v_mfma_f32_16x16x32_bf16 v[38:41], v[158:161], v[184:187], v[38:41]
	v_mfma_f32_16x16x32_bf16 v[34:37], v[168:171], v[184:187], v[34:37]
	v_mfma_f32_16x16x32_bf16 v[22:25], v[158:161], v[192:195], v[22:25]
	v_mfma_f32_16x16x32_bf16 v[18:21], v[168:171], v[192:195], v[18:21]
	v_mfma_f32_16x16x32_bf16 v[6:9], v[158:161], v[208:211], v[6:9]
	v_mfma_f32_16x16x32_bf16 v[2:5], v[168:171], v[208:211], v[2:5]
	v_mfma_f32_16x16x32_bf16 v[54:57], v[162:165], v[180:183], v[54:57]
	v_mfma_f32_16x16x32_bf16 v[50:53], v[172:175], v[180:183], v[50:53]
	v_mfma_f32_16x16x32_bf16 v[38:41], v[162:165], v[188:191], v[38:41]
	v_mfma_f32_16x16x32_bf16 v[34:37], v[172:175], v[188:191], v[34:37]
	v_mfma_f32_16x16x32_bf16 v[22:25], v[162:165], v[204:207], v[22:25]
	v_mfma_f32_16x16x32_bf16 v[18:21], v[172:175], v[204:207], v[18:21]
	v_mfma_f32_16x16x32_bf16 v[6:9], v[162:165], v[212:215], v[6:9]
	v_mfma_f32_16x16x32_bf16 v[2:5], v[172:175], v[212:215], v[2:5]
	s_setprio 0
	s_barrier
	s_add_i32 s71, s71, 2
	s_add_u32 s28, s28, 0x100
	s_addc_u32 s29, s29, 0
	s_add_u32 s37, s37, 0x100
	s_addc_u32 s70, s70, 0
	s_cmp_gt_u32 s71, 13
	s_cbranch_scc0 .LBB0_326
	s_and_b64 vcc, exec, s[14:15]
	s_cbranch_vccz .LBB0_329
	s_barrier

.LBB0_807:
	s_add_u32 s36, s26, s34
	s_addc_u32 s37, s27, s35
	s_add_u32 s36, s36, 0x100
	s_addc_u32 s37, s37, 0
	s_add_u32 s65, s62, s34
	s_addc_u32 s66, s63, s35
	s_add_i32 s67, 0, 0x10000
	s_cmpk_eq_i32 s34, 0x700
	s_cselect_b32 s39, s19, s37
	s_cselect_b32 s38, s25, s36
	s_cselect_b32 s37, s17, s66
	s_cselect_b32 s36, s60, s65
	s_add_i32 s65, 0, 0x14000
	v_add_u32_e32 v142, s67, v1
	v_add_u32_e32 v158, s65, v1
	ds_read_b128 v[130:133], v142
	ds_read_b128 v[134:137], v142 offset:1024
	ds_read_b128 v[138:141], v142 offset:2048
	ds_read_b128 v[142:145], v142 offset:3072
	ds_read_b128 v[146:149], v158
	ds_read_b128 v[150:153], v158 offset:1024
	ds_read_b128 v[154:157], v158 offset:2048
	ds_read_b128 v[158:161], v158 offset:3072
	v_lshl_add_u64 v[196:197], v[206:207], 0, s[34:35]
	s_add_i32 m0, s46, 0xc000
	ds_read_b128 v[162:165], v228
	ds_read_b128 v[166:169], v228 offset:1024
	ds_read_b128 v[170:173], v228 offset:2048
	ds_read_b128 v[174:177], v228 offset:3072
	ds_read_b128 v[178:181], v228 offset:4096
	ds_read_b128 v[182:185], v228 offset:5120
	ds_read_b128 v[210:213], v228 offset:6144
	ds_read_b128 v[214:217], v228 offset:7168
	global_load_lds_dwordx4 v[196:197], off
	s_add_i32 m0, s46, 0xe000
	v_lshl_add_u64 v[196:197], v[208:209], 0, s[34:35]
	global_load_lds_dwordx4 v[196:197], off
	s_waitcnt vmcnt(8)
	s_waitcnt lgkmcnt(0)
	s_barrier
	s_setprio 1
	s_waitcnt lgkmcnt(0)
	v_mfma_f32_16x16x32_bf16 v[126:129], v[130:133], v[162:165], v[126:129]
	v_mfma_f32_16x16x32_bf16 v[122:125], v[138:141], v[162:165], v[122:125]
	v_mfma_f32_16x16x32_bf16 v[110:113], v[130:133], v[170:173], v[110:113]
	v_mfma_f32_16x16x32_bf16 v[106:109], v[138:141], v[170:173], v[106:109]
	v_mfma_f32_16x16x32_bf16 v[94:97], v[130:133], v[178:181], v[94:97]
	v_mfma_f32_16x16x32_bf16 v[90:93], v[138:141], v[178:181], v[90:93]
	v_mfma_f32_16x16x32_bf16 v[78:81], v[130:133], v[210:213], v[78:81]
	v_mfma_f32_16x16x32_bf16 v[74:77], v[138:141], v[210:213], v[74:77]
	v_mfma_f32_16x16x32_bf16 v[126:129], v[134:137], v[166:169], v[126:129]
	v_mfma_f32_16x16x32_bf16 v[122:125], v[142:145], v[166:169], v[122:125]
	v_mfma_f32_16x16x32_bf16 v[110:113], v[134:137], v[174:177], v[110:113]
	v_mfma_f32_16x16x32_bf16 v[106:109], v[142:145], v[174:177], v[106:109]
	v_mfma_f32_16x16x32_bf16 v[94:97], v[134:137], v[182:185], v[94:97]
	v_mfma_f32_16x16x32_bf16 v[90:93], v[142:145], v[182:185], v[90:93]
	v_mfma_f32_16x16x32_bf16 v[78:81], v[134:137], v[214:217], v[78:81]
	v_mfma_f32_16x16x32_bf16 v[74:77], v[142:145], v[214:217], v[74:77]
	v_mfma_f32_16x16x32_bf16 v[118:121], v[146:149], v[162:165], v[118:121]
	v_mfma_f32_16x16x32_bf16 v[114:117], v[154:157], v[162:165], v[114:117]
	v_mfma_f32_16x16x32_bf16 v[102:105], v[146:149], v[170:173], v[102:105]
	v_mfma_f32_16x16x32_bf16 v[98:101], v[154:157], v[170:173], v[98:101]
	v_mfma_f32_16x16x32_bf16 v[86:89], v[146:149], v[178:181], v[86:89]
	v_mfma_f32_16x16x32_bf16 v[82:85], v[154:157], v[178:181], v[82:85]
	v_mfma_f32_16x16x32_bf16 v[70:73], v[146:149], v[210:213], v[70:73]
	v_mfma_f32_16x16x32_bf16 v[66:69], v[154:157], v[210:213], v[66:69]
	v_mfma_f32_16x16x32_bf16 v[118:121], v[150:153], v[166:169], v[118:121]
	v_mfma_f32_16x16x32_bf16 v[114:117], v[158:161], v[166:169], v[114:117]
	v_mfma_f32_16x16x32_bf16 v[102:105], v[150:153], v[174:177], v[102:105]
	v_mfma_f32_16x16x32_bf16 v[98:101], v[158:161], v[174:177], v[98:101]
	v_mfma_f32_16x16x32_bf16 v[86:89], v[150:153], v[182:185], v[86:89]
	v_mfma_f32_16x16x32_bf16 v[82:85], v[158:161], v[182:185], v[82:85]
	v_mfma_f32_16x16x32_bf16 v[70:73], v[150:153], v[214:217], v[70:73]
	v_mfma_f32_16x16x32_bf16 v[66:69], v[158:161], v[214:217], v[66:69]
	s_setprio 0
	s_barrier
	s_add_i32 s66, s67, s45
	v_lshl_add_u64 v[196:197], s[36:37], 0, v[190:191]
	s_mov_b32 m0, s66
	ds_read_b128 v[162:165], v228 offset:16384
	ds_read_b128 v[166:169], v228 offset:17408
	ds_read_b128 v[170:173], v228 offset:18432
	ds_read_b128 v[174:177], v228 offset:19456
	ds_read_b128 v[178:181], v228 offset:20480
	ds_read_b128 v[182:185], v228 offset:21504
	ds_read_b128 v[210:213], v228 offset:22528
	ds_read_b128 v[214:217], v228 offset:23552
	global_load_lds_dwordx4 v[196:197], off
	s_add_i32 m0, s66, 0x2000
	s_add_u32 s66, s36, 0x40000
	v_lshl_add_u64 v[198:199], s[36:37], 0, v[186:187]
	s_addc_u32 s67, s37, 0
	s_add_i32 s65, s65, s45
	global_load_lds_dwordx4 v[198:199], off
	v_lshl_add_u64 v[220:221], s[66:67], 0, v[190:191]
	s_mov_b32 m0, s65
	v_lshl_add_u64 v[222:223], s[38:39], 0, v[188:189]
	global_load_lds_dwordx4 v[220:221], off
	s_add_i32 m0, s65, 0x2000
	v_lshl_add_u64 v[220:221], s[66:67], 0, v[186:187]
	global_load_lds_dwordx4 v[220:221], off
	s_mov_b32 m0, s46
	v_lshl_add_u64 v[220:221], s[38:39], 0, v[192:193]
	global_load_lds_dwordx4 v[220:221], off
	s_mov_b32 m0, s47
	s_nop 0
	global_load_lds_dwordx4 v[222:223], off
	s_waitcnt vmcnt(8)
	s_waitcnt lgkmcnt(0)
	s_barrier
	s_setprio 1
	s_waitcnt lgkmcnt(0)
	v_mfma_f32_16x16x32_bf16 v[62:65], v[130:133], v[162:165], v[62:65]
	v_mfma_f32_16x16x32_bf16 v[58:61], v[138:141], v[162:165], v[58:61]
	v_mfma_f32_16x16x32_bf16 v[46:49], v[130:133], v[170:173], v[46:49]
	v_mfma_f32_16x16x32_bf16 v[42:45], v[138:141], v[170:173], v[42:45]
	v_mfma_f32_16x16x32_bf16 v[30:33], v[130:133], v[178:181], v[30:33]
	v_mfma_f32_16x16x32_bf16 v[26:29], v[138:141], v[178:181], v[26:29]
	v_mfma_f32_16x16x32_bf16 v[14:17], v[130:133], v[210:213], v[14:17]
	v_mfma_f32_16x16x32_bf16 v[10:13], v[138:141], v[210:213], v[10:13]
	v_mfma_f32_16x16x32_bf16 v[62:65], v[134:137], v[166:169], v[62:65]
	v_mfma_f32_16x16x32_bf16 v[58:61], v[142:145], v[166:169], v[58:61]
	v_mfma_f32_16x16x32_bf16 v[46:49], v[134:137], v[174:177], v[46:49]
	v_mfma_f32_16x16x32_bf16 v[42:45], v[142:145], v[174:177], v[42:45]
	v_mfma_f32_16x16x32_bf16 v[30:33], v[134:137], v[182:185], v[30:33]
	v_mfma_f32_16x16x32_bf16 v[26:29], v[142:145], v[182:185], v[26:29]
	v_mfma_f32_16x16x32_bf16 v[14:17], v[134:137], v[214:217], v[14:17]
	v_mfma_f32_16x16x32_bf16 v[10:13], v[142:145], v[214:217], v[10:13]
	v_mfma_f32_16x16x32_bf16 v[54:57], v[146:149], v[162:165], v[54:57]
	v_mfma_f32_16x16x32_bf16 v[50:53], v[154:157], v[162:165], v[50:53]
	v_mfma_f32_16x16x32_bf16 v[38:41], v[146:149], v[170:173], v[38:41]
	v_mfma_f32_16x16x32_bf16 v[34:37], v[154:157], v[170:173], v[34:37]
	v_mfma_f32_16x16x32_bf16 v[22:25], v[146:149], v[178:181], v[22:25]
	v_mfma_f32_16x16x32_bf16 v[18:21], v[154:157], v[178:181], v[18:21]
	v_mfma_f32_16x16x32_bf16 v[6:9], v[146:149], v[210:213], v[6:9]
	v_mfma_f32_16x16x32_bf16 v[2:5], v[154:157], v[210:213], v[2:5]
	v_mfma_f32_16x16x32_bf16 v[54:57], v[150:153], v[166:169], v[54:57]
	v_mfma_f32_16x16x32_bf16 v[50:53], v[158:161], v[166:169], v[50:53]
	v_mfma_f32_16x16x32_bf16 v[38:41], v[150:153], v[174:177], v[38:41]
	v_mfma_f32_16x16x32_bf16 v[34:37], v[158:161], v[174:177], v[34:37]
	v_mfma_f32_16x16x32_bf16 v[22:25], v[150:153], v[182:185], v[22:25]
	v_mfma_f32_16x16x32_bf16 v[18:21], v[158:161], v[182:185], v[18:21]
	v_mfma_f32_16x16x32_bf16 v[6:9], v[150:153], v[214:217], v[6:9]
	v_mfma_f32_16x16x32_bf16 v[2:5], v[158:161], v[214:217], v[2:5]
	s_setprio 0
	s_barrier
	s_add_i32 s65, 0, 0x18000
	s_add_i32 s66, 0, 0x1c000
	v_add_u32_e32 v142, s65, v1
	v_add_u32_e32 v158, s66, v1
	ds_read_b128 v[130:133], v142
	ds_read_b128 v[134:137], v142 offset:1024
	ds_read_b128 v[138:141], v142 offset:2048
	ds_read_b128 v[142:145], v142 offset:3072
	ds_read_b128 v[146:149], v158
	ds_read_b128 v[150:153], v158 offset:1024
	ds_read_b128 v[154:157], v158 offset:2048
	ds_read_b128 v[158:161], v158 offset:3072
	s_add_u32 s38, s38, 0x40000
	s_addc_u32 s39, s39, 0
	s_mov_b32 m0, s48
	v_lshl_add_u64 v[230:231], s[38:39], 0, v[192:193]
	ds_read_b128 v[162:165], v228 offset:32768
	ds_read_b128 v[166:169], v228 offset:33792
	ds_read_b128 v[170:173], v228 offset:34816
	ds_read_b128 v[174:177], v228 offset:35840
	ds_read_b128 v[178:181], v228 offset:36864
	ds_read_b128 v[182:185], v228 offset:37888
	ds_read_b128 v[210:213], v228 offset:38912
	ds_read_b128 v[214:217], v228 offset:39936
	global_load_lds_dwordx4 v[230:231], off
	s_mov_b32 m0, s49
	v_lshl_add_u64 v[230:231], s[38:39], 0, v[188:189]
	global_load_lds_dwordx4 v[230:231], off
	s_waitcnt vmcnt(8)
	s_waitcnt lgkmcnt(0)
	s_barrier
	s_setprio 1
	s_waitcnt lgkmcnt(0)
	v_mfma_f32_16x16x32_bf16 v[126:129], v[130:133], v[162:165], v[126:129]
	v_mfma_f32_16x16x32_bf16 v[122:125], v[138:141], v[162:165], v[122:125]
	v_mfma_f32_16x16x32_bf16 v[110:113], v[130:133], v[170:173], v[110:113]
	v_mfma_f32_16x16x32_bf16 v[106:109], v[138:141], v[170:173], v[106:109]
	v_mfma_f32_16x16x32_bf16 v[94:97], v[130:133], v[178:181], v[94:97]
	v_mfma_f32_16x16x32_bf16 v[90:93], v[138:141], v[178:181], v[90:93]
	v_mfma_f32_16x16x32_bf16 v[78:81], v[130:133], v[210:213], v[78:81]
	v_mfma_f32_16x16x32_bf16 v[74:77], v[138:141], v[210:213], v[74:77]
	v_mfma_f32_16x16x32_bf16 v[126:129], v[134:137], v[166:169], v[126:129]
	v_mfma_f32_16x16x32_bf16 v[122:125], v[142:145], v[166:169], v[122:125]
	v_mfma_f32_16x16x32_bf16 v[110:113], v[134:137], v[174:177], v[110:113]
	v_mfma_f32_16x16x32_bf16 v[106:109], v[142:145], v[174:177], v[106:109]
	v_mfma_f32_16x16x32_bf16 v[94:97], v[134:137], v[182:185], v[94:97]
	v_mfma_f32_16x16x32_bf16 v[90:93], v[142:145], v[182:185], v[90:93]
	v_mfma_f32_16x16x32_bf16 v[78:81], v[134:137], v[214:217], v[78:81]
	v_mfma_f32_16x16x32_bf16 v[74:77], v[142:145], v[214:217], v[74:77]
	v_mfma_f32_16x16x32_bf16 v[118:121], v[146:149], v[162:165], v[118:121]
	v_mfma_f32_16x16x32_bf16 v[114:117], v[154:157], v[162:165], v[114:117]
	v_mfma_f32_16x16x32_bf16 v[102:105], v[146:149], v[170:173], v[102:105]
	v_mfma_f32_16x16x32_bf16 v[98:101], v[154:157], v[170:173], v[98:101]
	v_mfma_f32_16x16x32_bf16 v[86:89], v[146:149], v[178:181], v[86:89]
	v_mfma_f32_16x16x32_bf16 v[82:85], v[154:157], v[178:181], v[82:85]
	v_mfma_f32_16x16x32_bf16 v[70:73], v[146:149], v[210:213], v[70:73]
	v_mfma_f32_16x16x32_bf16 v[66:69], v[154:157], v[210:213], v[66:69]
	v_mfma_f32_16x16x32_bf16 v[118:121], v[150:153], v[166:169], v[118:121]
	v_mfma_f32_16x16x32_bf16 v[114:117], v[158:161], v[166:169], v[114:117]
	v_mfma_f32_16x16x32_bf16 v[102:105], v[150:153], v[174:177], v[102:105]
	v_mfma_f32_16x16x32_bf16 v[98:101], v[158:161], v[174:177], v[98:101]
	v_mfma_f32_16x16x32_bf16 v[86:89], v[150:153], v[182:185], v[86:89]
	v_mfma_f32_16x16x32_bf16 v[82:85], v[158:161], v[182:185], v[82:85]
	v_mfma_f32_16x16x32_bf16 v[70:73], v[150:153], v[214:217], v[70:73]
	v_mfma_f32_16x16x32_bf16 v[66:69], v[158:161], v[214:217], v[66:69]
	s_setprio 0
	s_barrier
	s_add_i32 s38, s65, s45
	v_lshl_add_u64 v[196:197], v[196:197], 0, s[94:95]
	s_mov_b32 m0, s38
	ds_read_b128 v[162:165], v228 offset:49152
	ds_read_b128 v[166:169], v228 offset:50176
	ds_read_b128 v[170:173], v228 offset:51200
	ds_read_b128 v[174:177], v228 offset:52224
	ds_read_b128 v[178:181], v228 offset:53248
	ds_read_b128 v[182:185], v228 offset:54272
	ds_read_b128 v[210:213], v228 offset:55296
	ds_read_b128 v[214:217], v228 offset:56320
	global_load_lds_dwordx4 v[196:197], off
	s_add_i32 m0, s38, 0x2000
	s_add_u32 s36, s36, 0x40080
	v_lshl_add_u64 v[196:197], v[198:199], 0, s[94:95]
	s_addc_u32 s37, s37, 0
	s_add_i32 s38, s66, s45
	global_load_lds_dwordx4 v[196:197], off
	s_mov_b32 m0, s38
	v_lshl_add_u64 v[196:197], s[36:37], 0, v[190:191]
	global_load_lds_dwordx4 v[196:197], off
	s_add_i32 m0, s38, 0x2000
	v_lshl_add_u64 v[196:197], s[36:37], 0, v[186:187]
	global_load_lds_dwordx4 v[196:197], off
	s_mov_b32 m0, s55
	v_lshl_add_u64 v[196:197], v[220:221], 0, s[94:95]
	global_load_lds_dwordx4 v[196:197], off
	s_mov_b32 m0, s56
	v_lshl_add_u64 v[196:197], v[222:223], 0, s[94:95]
	global_load_lds_dwordx4 v[196:197], off
	s_waitcnt vmcnt(8)
	s_waitcnt lgkmcnt(0)
	s_barrier
	s_setprio 1
	s_waitcnt lgkmcnt(0)
	v_mfma_f32_16x16x32_bf16 v[62:65], v[130:133], v[162:165], v[62:65]
	v_mfma_f32_16x16x32_bf16 v[58:61], v[138:141], v[162:165], v[58:61]
	v_mfma_f32_16x16x32_bf16 v[46:49], v[130:133], v[170:173], v[46:49]
	v_mfma_f32_16x16x32_bf16 v[42:45], v[138:141], v[170:173], v[42:45]
	v_mfma_f32_16x16x32_bf16 v[30:33], v[130:133], v[178:181], v[30:33]
	v_mfma_f32_16x16x32_bf16 v[26:29], v[138:141], v[178:181], v[26:29]
	v_mfma_f32_16x16x32_bf16 v[14:17], v[130:133], v[210:213], v[14:17]
	v_mfma_f32_16x16x32_bf16 v[10:13], v[138:141], v[210:213], v[10:13]
	v_mfma_f32_16x16x32_bf16 v[62:65], v[134:137], v[166:169], v[62:65]
	v_mfma_f32_16x16x32_bf16 v[58:61], v[142:145], v[166:169], v[58:61]
	v_mfma_f32_16x16x32_bf16 v[46:49], v[134:137], v[174:177], v[46:49]
	v_mfma_f32_16x16x32_bf16 v[42:45], v[142:145], v[174:177], v[42:45]
	v_mfma_f32_16x16x32_bf16 v[30:33], v[134:137], v[182:185], v[30:33]
	v_mfma_f32_16x16x32_bf16 v[26:29], v[142:145], v[182:185], v[26:29]
	v_mfma_f32_16x16x32_bf16 v[14:17], v[134:137], v[214:217], v[14:17]
	v_mfma_f32_16x16x32_bf16 v[10:13], v[142:145], v[214:217], v[10:13]
	v_mfma_f32_16x16x32_bf16 v[54:57], v[146:149], v[162:165], v[54:57]
	v_mfma_f32_16x16x32_bf16 v[50:53], v[154:157], v[162:165], v[50:53]
	v_mfma_f32_16x16x32_bf16 v[38:41], v[146:149], v[170:173], v[38:41]
	v_mfma_f32_16x16x32_bf16 v[34:37], v[154:157], v[170:173], v[34:37]
	v_mfma_f32_16x16x32_bf16 v[22:25], v[146:149], v[178:181], v[22:25]
	v_mfma_f32_16x16x32_bf16 v[18:21], v[154:157], v[178:181], v[18:21]
	v_mfma_f32_16x16x32_bf16 v[6:9], v[146:149], v[210:213], v[6:9]
	v_mfma_f32_16x16x32_bf16 v[2:5], v[154:157], v[210:213], v[2:5]
	v_mfma_f32_16x16x32_bf16 v[54:57], v[150:153], v[166:169], v[54:57]
	v_mfma_f32_16x16x32_bf16 v[50:53], v[158:161], v[166:169], v[50:53]
	v_mfma_f32_16x16x32_bf16 v[38:41], v[150:153], v[174:177], v[38:41]
	v_mfma_f32_16x16x32_bf16 v[34:37], v[158:161], v[174:177], v[34:37]
	v_mfma_f32_16x16x32_bf16 v[22:25], v[150:153], v[182:185], v[22:25]
	v_mfma_f32_16x16x32_bf16 v[18:21], v[158:161], v[182:185], v[18:21]
	v_mfma_f32_16x16x32_bf16 v[6:9], v[150:153], v[214:217], v[6:9]
	v_mfma_f32_16x16x32_bf16 v[2:5], v[158:161], v[214:217], v[2:5]
	s_setprio 0
	s_barrier
	s_add_i32 s36, s64, 2
	s_add_u32 s34, s34, 0x100
	s_addc_u32 s35, s35, 0
	s_cmp_gt_u32 s64, 13
	s_mov_b32 s64, s36
	s_cbranch_scc1 .LBB0_812

.LBB0_890:
	s_add_u32 s28, s26, 0xfffc0080
	s_addc_u32 s29, s27, -1
	s_add_i32 s55, 0, 0x10000
	s_cmp_eq_u32 s54, 12
	s_cselect_b32 s31, s17, s29
	s_cselect_b32 s30, s23, s28
	s_cselect_b32 s29, s15, s53
	s_cselect_b32 s28, s51, s52
	s_add_i32 s58, 0, 0x14000
	v_add_u32_e32 v134, s55, v1
	v_add_u32_e32 v154, s58, v1
	ds_read_b128 v[110:113], v134
	ds_read_b128 v[118:121], v134 offset:1024
	ds_read_b128 v[122:125], v134 offset:2048
	ds_read_b128 v[134:137], v134 offset:3072
	ds_read_b128 v[138:141], v154
	ds_read_b128 v[142:145], v154 offset:1024
	ds_read_b128 v[146:149], v154 offset:2048
	ds_read_b128 v[154:157], v154 offset:3072
	v_lshl_add_u64 v[196:197], s[26:27], 0, v[206:207]
	s_add_i32 m0, s25, 0xc000
	ds_read_b128 v[162:165], v214
	ds_read_b128 v[166:169], v214 offset:1024
	ds_read_b128 v[170:173], v214 offset:2048
	ds_read_b128 v[174:177], v214 offset:3072
	ds_read_b128 v[178:181], v214 offset:4096
	ds_read_b128 v[182:185], v214 offset:5120
	ds_read_b128 v[186:189], v214 offset:6144
	ds_read_b128 v[210:213], v214 offset:7168
	global_load_lds_dwordx4 v[196:197], off
	s_add_i32 m0, s25, 0xe000
	v_lshl_add_u64 v[196:197], s[26:27], 0, v[208:209]
	global_load_lds_dwordx4 v[196:197], off
	s_waitcnt vmcnt(8)
	s_waitcnt lgkmcnt(0)
	s_barrier
	s_setprio 1
	s_waitcnt lgkmcnt(0)
	v_mfma_f32_16x16x32_bf16 v[158:161], v[110:113], v[162:165], v[158:161]
	v_mfma_f32_16x16x32_bf16 v[150:153], v[122:125], v[162:165], v[150:153]
	v_mfma_f32_16x16x32_bf16 v[114:117], v[110:113], v[170:173], v[114:117]
	v_mfma_f32_16x16x32_bf16 v[106:109], v[122:125], v[170:173], v[106:109]
	v_mfma_f32_16x16x32_bf16 v[94:97], v[110:113], v[178:181], v[94:97]
	v_mfma_f32_16x16x32_bf16 v[90:93], v[122:125], v[178:181], v[90:93]
	v_mfma_f32_16x16x32_bf16 v[78:81], v[110:113], v[186:189], v[78:81]
	v_mfma_f32_16x16x32_bf16 v[74:77], v[122:125], v[186:189], v[74:77]
	v_mfma_f32_16x16x32_bf16 v[158:161], v[118:121], v[166:169], v[158:161]
	v_mfma_f32_16x16x32_bf16 v[150:153], v[134:137], v[166:169], v[150:153]
	v_mfma_f32_16x16x32_bf16 v[114:117], v[118:121], v[174:177], v[114:117]
	v_mfma_f32_16x16x32_bf16 v[106:109], v[134:137], v[174:177], v[106:109]
	v_mfma_f32_16x16x32_bf16 v[94:97], v[118:121], v[182:185], v[94:97]
	v_mfma_f32_16x16x32_bf16 v[90:93], v[134:137], v[182:185], v[90:93]
	v_mfma_f32_16x16x32_bf16 v[78:81], v[118:121], v[210:213], v[78:81]
	v_mfma_f32_16x16x32_bf16 v[74:77], v[134:137], v[210:213], v[74:77]
	v_mfma_f32_16x16x32_bf16 v[130:133], v[138:141], v[162:165], v[130:133]
	v_mfma_f32_16x16x32_bf16 v[126:129], v[146:149], v[162:165], v[126:129]
	v_mfma_f32_16x16x32_bf16 v[102:105], v[138:141], v[170:173], v[102:105]
	v_mfma_f32_16x16x32_bf16 v[98:101], v[146:149], v[170:173], v[98:101]
	v_mfma_f32_16x16x32_bf16 v[86:89], v[138:141], v[178:181], v[86:89]
	v_mfma_f32_16x16x32_bf16 v[82:85], v[146:149], v[178:181], v[82:85]
	v_mfma_f32_16x16x32_bf16 v[70:73], v[138:141], v[186:189], v[70:73]
	v_mfma_f32_16x16x32_bf16 v[66:69], v[146:149], v[186:189], v[66:69]
	v_mfma_f32_16x16x32_bf16 v[130:133], v[142:145], v[166:169], v[130:133]
	v_mfma_f32_16x16x32_bf16 v[126:129], v[154:157], v[166:169], v[126:129]
	v_mfma_f32_16x16x32_bf16 v[102:105], v[142:145], v[174:177], v[102:105]
	v_mfma_f32_16x16x32_bf16 v[98:101], v[154:157], v[174:177], v[98:101]
	v_mfma_f32_16x16x32_bf16 v[86:89], v[142:145], v[182:185], v[86:89]
	v_mfma_f32_16x16x32_bf16 v[82:85], v[154:157], v[182:185], v[82:85]
	v_mfma_f32_16x16x32_bf16 v[70:73], v[142:145], v[210:213], v[70:73]
	v_mfma_f32_16x16x32_bf16 v[66:69], v[154:157], v[210:213], v[66:69]
	s_setprio 0
	s_barrier
	s_add_i32 s55, s55, s40
	v_lshl_add_u64 v[196:197], s[28:29], 0, v[192:193]
	s_mov_b32 m0, s55
	ds_read_b128 v[162:165], v214 offset:16384
	ds_read_b128 v[166:169], v214 offset:17408
	ds_read_b128 v[170:173], v214 offset:18432
	ds_read_b128 v[174:177], v214 offset:19456
	ds_read_b128 v[178:181], v214 offset:20480
	ds_read_b128 v[182:185], v214 offset:21504
	ds_read_b128 v[186:189], v214 offset:22528
	ds_read_b128 v[210:213], v214 offset:23552
	global_load_lds_dwordx4 v[196:197], off
	s_add_i32 m0, s55, 0x2000
	s_add_u32 s56, s28, 0x40000
	v_lshl_add_u64 v[198:199], s[28:29], 0, v[204:205]
	s_addc_u32 s57, s29, 0
	s_add_i32 s55, s58, s40
	global_load_lds_dwordx4 v[198:199], off
	v_lshl_add_u64 v[216:217], s[56:57], 0, v[192:193]
	s_mov_b32 m0, s55
	v_lshl_add_u64 v[220:221], s[30:31], 0, v[194:195]
	global_load_lds_dwordx4 v[216:217], off
	s_add_i32 m0, s55, 0x2000
	v_lshl_add_u64 v[216:217], s[56:57], 0, v[204:205]
	global_load_lds_dwordx4 v[216:217], off
	s_mov_b32 m0, s25
	v_lshl_add_u64 v[216:217], s[30:31], 0, v[190:191]
	global_load_lds_dwordx4 v[216:217], off
	s_mov_b32 m0, s41
	s_nop 0
	global_load_lds_dwordx4 v[220:221], off
	s_waitcnt vmcnt(8)
	s_waitcnt lgkmcnt(0)
	s_barrier
	s_setprio 1
	s_waitcnt lgkmcnt(0)
	v_mfma_f32_16x16x32_bf16 v[62:65], v[110:113], v[162:165], v[62:65]
	v_mfma_f32_16x16x32_bf16 v[58:61], v[122:125], v[162:165], v[58:61]
	v_mfma_f32_16x16x32_bf16 v[46:49], v[110:113], v[170:173], v[46:49]
	v_mfma_f32_16x16x32_bf16 v[42:45], v[122:125], v[170:173], v[42:45]
	v_mfma_f32_16x16x32_bf16 v[30:33], v[110:113], v[178:181], v[30:33]
	v_mfma_f32_16x16x32_bf16 v[26:29], v[122:125], v[178:181], v[26:29]
	v_mfma_f32_16x16x32_bf16 v[14:17], v[110:113], v[186:189], v[14:17]
	v_mfma_f32_16x16x32_bf16 v[10:13], v[122:125], v[186:189], v[10:13]
	v_mfma_f32_16x16x32_bf16 v[62:65], v[118:121], v[166:169], v[62:65]
	v_mfma_f32_16x16x32_bf16 v[58:61], v[134:137], v[166:169], v[58:61]
	v_mfma_f32_16x16x32_bf16 v[46:49], v[118:121], v[174:177], v[46:49]
	v_mfma_f32_16x16x32_bf16 v[42:45], v[134:137], v[174:177], v[42:45]
	v_mfma_f32_16x16x32_bf16 v[30:33], v[118:121], v[182:185], v[30:33]
	v_mfma_f32_16x16x32_bf16 v[26:29], v[134:137], v[182:185], v[26:29]
	v_mfma_f32_16x16x32_bf16 v[14:17], v[118:121], v[210:213], v[14:17]
	v_mfma_f32_16x16x32_bf16 v[10:13], v[134:137], v[210:213], v[10:13]
	v_mfma_f32_16x16x32_bf16 v[54:57], v[138:141], v[162:165], v[54:57]
	v_mfma_f32_16x16x32_bf16 v[50:53], v[146:149], v[162:165], v[50:53]
	v_mfma_f32_16x16x32_bf16 v[38:41], v[138:141], v[170:173], v[38:41]
	v_mfma_f32_16x16x32_bf16 v[34:37], v[146:149], v[170:173], v[34:37]
	v_mfma_f32_16x16x32_bf16 v[22:25], v[138:141], v[178:181], v[22:25]
	v_mfma_f32_16x16x32_bf16 v[18:21], v[146:149], v[178:181], v[18:21]
	v_mfma_f32_16x16x32_bf16 v[6:9], v[138:141], v[186:189], v[6:9]
	v_mfma_f32_16x16x32_bf16 v[2:5], v[146:149], v[186:189], v[2:5]
	v_mfma_f32_16x16x32_bf16 v[54:57], v[142:145], v[166:169], v[54:57]
	v_mfma_f32_16x16x32_bf16 v[50:53], v[154:157], v[166:169], v[50:53]
	v_mfma_f32_16x16x32_bf16 v[38:41], v[142:145], v[174:177], v[38:41]
	v_mfma_f32_16x16x32_bf16 v[34:37], v[154:157], v[174:177], v[34:37]
	v_mfma_f32_16x16x32_bf16 v[22:25], v[142:145], v[182:185], v[22:25]
	v_mfma_f32_16x16x32_bf16 v[18:21], v[154:157], v[182:185], v[18:21]
	v_mfma_f32_16x16x32_bf16 v[6:9], v[142:145], v[210:213], v[6:9]
	v_mfma_f32_16x16x32_bf16 v[2:5], v[154:157], v[210:213], v[2:5]
	s_setprio 0
	s_barrier
	s_add_i32 s55, 0, 0x18000
	s_add_i32 s56, 0, 0x1c000
	v_add_u32_e32 v134, s55, v1
	v_add_u32_e32 v154, s56, v1
	ds_read_b128 v[110:113], v134
	ds_read_b128 v[118:121], v134 offset:1024
	ds_read_b128 v[122:125], v134 offset:2048
	ds_read_b128 v[134:137], v134 offset:3072
	ds_read_b128 v[138:141], v154
	ds_read_b128 v[142:145], v154 offset:1024
	ds_read_b128 v[146:149], v154 offset:2048
	ds_read_b128 v[154:157], v154 offset:3072
	s_add_u32 s30, s30, 0x40000
	s_addc_u32 s31, s31, 0
	s_mov_b32 m0, s42
	v_lshl_add_u64 v[222:223], s[30:31], 0, v[190:191]
	ds_read_b128 v[162:165], v214 offset:32768
	ds_read_b128 v[166:169], v214 offset:33792
	ds_read_b128 v[170:173], v214 offset:34816
	ds_read_b128 v[174:177], v214 offset:35840
	ds_read_b128 v[178:181], v214 offset:36864
	ds_read_b128 v[182:185], v214 offset:37888
	ds_read_b128 v[186:189], v214 offset:38912
	ds_read_b128 v[210:213], v214 offset:39936
	global_load_lds_dwordx4 v[222:223], off
	s_mov_b32 m0, s43
	v_lshl_add_u64 v[222:223], s[30:31], 0, v[194:195]
	global_load_lds_dwordx4 v[222:223], off
	s_waitcnt vmcnt(8)
	s_waitcnt lgkmcnt(0)
	s_barrier
	s_setprio 1
	s_waitcnt lgkmcnt(0)
	v_mfma_f32_16x16x32_bf16 v[158:161], v[110:113], v[162:165], v[158:161]
	v_mfma_f32_16x16x32_bf16 v[150:153], v[122:125], v[162:165], v[150:153]
	v_mfma_f32_16x16x32_bf16 v[114:117], v[110:113], v[170:173], v[114:117]
	v_mfma_f32_16x16x32_bf16 v[106:109], v[122:125], v[170:173], v[106:109]
	v_mfma_f32_16x16x32_bf16 v[94:97], v[110:113], v[178:181], v[94:97]
	v_mfma_f32_16x16x32_bf16 v[90:93], v[122:125], v[178:181], v[90:93]
	v_mfma_f32_16x16x32_bf16 v[78:81], v[110:113], v[186:189], v[78:81]
	v_mfma_f32_16x16x32_bf16 v[74:77], v[122:125], v[186:189], v[74:77]
	v_mfma_f32_16x16x32_bf16 v[158:161], v[118:121], v[166:169], v[158:161]
	v_mfma_f32_16x16x32_bf16 v[150:153], v[134:137], v[166:169], v[150:153]
	v_mfma_f32_16x16x32_bf16 v[114:117], v[118:121], v[174:177], v[114:117]
	v_mfma_f32_16x16x32_bf16 v[106:109], v[134:137], v[174:177], v[106:109]
	v_mfma_f32_16x16x32_bf16 v[94:97], v[118:121], v[182:185], v[94:97]
	v_mfma_f32_16x16x32_bf16 v[90:93], v[134:137], v[182:185], v[90:93]
	v_mfma_f32_16x16x32_bf16 v[78:81], v[118:121], v[210:213], v[78:81]
	v_mfma_f32_16x16x32_bf16 v[74:77], v[134:137], v[210:213], v[74:77]
	v_mfma_f32_16x16x32_bf16 v[130:133], v[138:141], v[162:165], v[130:133]
	v_mfma_f32_16x16x32_bf16 v[126:129], v[146:149], v[162:165], v[126:129]
	v_mfma_f32_16x16x32_bf16 v[102:105], v[138:141], v[170:173], v[102:105]
	v_mfma_f32_16x16x32_bf16 v[98:101], v[146:149], v[170:173], v[98:101]
	v_mfma_f32_16x16x32_bf16 v[86:89], v[138:141], v[178:181], v[86:89]
	v_mfma_f32_16x16x32_bf16 v[82:85], v[146:149], v[178:181], v[82:85]
	v_mfma_f32_16x16x32_bf16 v[70:73], v[138:141], v[186:189], v[70:73]
	v_mfma_f32_16x16x32_bf16 v[66:69], v[146:149], v[186:189], v[66:69]
	v_mfma_f32_16x16x32_bf16 v[130:133], v[142:145], v[166:169], v[130:133]
	v_mfma_f32_16x16x32_bf16 v[126:129], v[154:157], v[166:169], v[126:129]
	v_mfma_f32_16x16x32_bf16 v[102:105], v[142:145], v[174:177], v[102:105]
	v_mfma_f32_16x16x32_bf16 v[98:101], v[154:157], v[174:177], v[98:101]
	v_mfma_f32_16x16x32_bf16 v[86:89], v[142:145], v[182:185], v[86:89]
	v_mfma_f32_16x16x32_bf16 v[82:85], v[154:157], v[182:185], v[82:85]
	v_mfma_f32_16x16x32_bf16 v[70:73], v[142:145], v[210:213], v[70:73]
	v_mfma_f32_16x16x32_bf16 v[66:69], v[154:157], v[210:213], v[66:69]
	s_setprio 0
	s_barrier
	s_add_i32 s30, s55, s40
	v_lshl_add_u64 v[196:197], v[196:197], 0, s[94:95]
	s_mov_b32 m0, s30
	ds_read_b128 v[162:165], v214 offset:49152
	ds_read_b128 v[166:169], v214 offset:50176
	ds_read_b128 v[170:173], v214 offset:51200
	ds_read_b128 v[174:177], v214 offset:52224
	ds_read_b128 v[178:181], v214 offset:53248
	ds_read_b128 v[182:185], v214 offset:54272
	ds_read_b128 v[186:189], v214 offset:55296
	ds_read_b128 v[210:213], v214 offset:56320
	global_load_lds_dwordx4 v[196:197], off
	s_add_i32 m0, s30, 0x2000
	s_add_u32 s28, s28, 0x40080
	v_lshl_add_u64 v[196:197], v[198:199], 0, s[94:95]
	s_addc_u32 s29, s29, 0
	s_add_i32 s30, s56, s40
	global_load_lds_dwordx4 v[196:197], off
	s_mov_b32 m0, s30
	v_lshl_add_u64 v[196:197], s[28:29], 0, v[192:193]
	global_load_lds_dwordx4 v[196:197], off
	s_add_i32 m0, s30, 0x2000
	v_lshl_add_u64 v[196:197], s[28:29], 0, v[204:205]
	global_load_lds_dwordx4 v[196:197], off
	s_mov_b32 m0, s46
	v_lshl_add_u64 v[196:197], v[216:217], 0, s[94:95]
	global_load_lds_dwordx4 v[196:197], off
	s_mov_b32 m0, s47
	v_lshl_add_u64 v[196:197], v[220:221], 0, s[94:95]
	global_load_lds_dwordx4 v[196:197], off
	s_waitcnt vmcnt(8)
	s_waitcnt lgkmcnt(0)
	s_barrier
	s_setprio 1
	s_waitcnt lgkmcnt(0)
	v_mfma_f32_16x16x32_bf16 v[62:65], v[110:113], v[162:165], v[62:65]
	v_mfma_f32_16x16x32_bf16 v[58:61], v[122:125], v[162:165], v[58:61]
	v_mfma_f32_16x16x32_bf16 v[46:49], v[110:113], v[170:173], v[46:49]
	v_mfma_f32_16x16x32_bf16 v[42:45], v[122:125], v[170:173], v[42:45]
	v_mfma_f32_16x16x32_bf16 v[30:33], v[110:113], v[178:181], v[30:33]
	v_mfma_f32_16x16x32_bf16 v[26:29], v[122:125], v[178:181], v[26:29]
	v_mfma_f32_16x16x32_bf16 v[14:17], v[110:113], v[186:189], v[14:17]
	v_mfma_f32_16x16x32_bf16 v[10:13], v[122:125], v[186:189], v[10:13]
	v_mfma_f32_16x16x32_bf16 v[62:65], v[118:121], v[166:169], v[62:65]
	v_mfma_f32_16x16x32_bf16 v[58:61], v[134:137], v[166:169], v[58:61]
	v_mfma_f32_16x16x32_bf16 v[46:49], v[118:121], v[174:177], v[46:49]
	v_mfma_f32_16x16x32_bf16 v[42:45], v[134:137], v[174:177], v[42:45]
	v_mfma_f32_16x16x32_bf16 v[30:33], v[118:121], v[182:185], v[30:33]
	v_mfma_f32_16x16x32_bf16 v[26:29], v[134:137], v[182:185], v[26:29]
	v_mfma_f32_16x16x32_bf16 v[14:17], v[118:121], v[210:213], v[14:17]
	v_mfma_f32_16x16x32_bf16 v[10:13], v[134:137], v[210:213], v[10:13]
	v_mfma_f32_16x16x32_bf16 v[54:57], v[138:141], v[162:165], v[54:57]
	v_mfma_f32_16x16x32_bf16 v[50:53], v[146:149], v[162:165], v[50:53]
	v_mfma_f32_16x16x32_bf16 v[38:41], v[138:141], v[170:173], v[38:41]
	v_mfma_f32_16x16x32_bf16 v[34:37], v[146:149], v[170:173], v[34:37]
	v_mfma_f32_16x16x32_bf16 v[22:25], v[138:141], v[178:181], v[22:25]
	v_mfma_f32_16x16x32_bf16 v[18:21], v[146:149], v[178:181], v[18:21]
	v_mfma_f32_16x16x32_bf16 v[6:9], v[138:141], v[186:189], v[6:9]
	v_mfma_f32_16x16x32_bf16 v[2:5], v[146:149], v[186:189], v[2:5]
	v_mfma_f32_16x16x32_bf16 v[54:57], v[142:145], v[166:169], v[54:57]
	v_mfma_f32_16x16x32_bf16 v[50:53], v[154:157], v[166:169], v[50:53]
	v_mfma_f32_16x16x32_bf16 v[38:41], v[142:145], v[174:177], v[38:41]
	v_mfma_f32_16x16x32_bf16 v[34:37], v[154:157], v[174:177], v[34:37]
	v_mfma_f32_16x16x32_bf16 v[22:25], v[142:145], v[182:185], v[22:25]
	v_mfma_f32_16x16x32_bf16 v[18:21], v[154:157], v[182:185], v[18:21]
	v_mfma_f32_16x16x32_bf16 v[6:9], v[142:145], v[210:213], v[6:9]
	v_mfma_f32_16x16x32_bf16 v[2:5], v[154:157], v[210:213], v[2:5]
	s_setprio 0
	s_barrier
	s_add_i32 s54, s54, 2
	s_add_u32 s26, s26, 0x100
	s_addc_u32 s27, s27, 0
	s_add_u32 s52, s52, 0x100
	s_addc_u32 s53, s53, 0
	s_cmp_gt_u32 s54, 13
	s_cbranch_scc0 .LBB0_890
	s_and_b64 vcc, exec, s[12:13]
	s_cbranch_vccz .LBB0_893
	s_barrier

.LBB0_984:
	s_add_u32 s28, s4, 0xfffc0080
	s_addc_u32 s29, s5, -1
	s_add_i32 s58, 0, 0x10000
	s_cmp_eq_u32 s57, 12
	s_cselect_b32 s31, s19, s29
	s_cselect_b32 s30, s53, s28
	s_cselect_b32 s29, s17, s56
	s_cselect_b32 s28, s54, s55
	s_add_i32 s60, 0, 0x14000
	v_add_u32_e32 v154, s58, v1
	v_add_u32_e32 v170, s60, v1
	ds_read_b128 v[142:145], v154
	ds_read_b128 v[146:149], v154 offset:1024
	ds_read_b128 v[150:153], v154 offset:2048
	ds_read_b128 v[154:157], v154 offset:3072
	ds_read_b128 v[158:161], v170
	ds_read_b128 v[162:165], v170 offset:1024
	ds_read_b128 v[166:169], v170 offset:2048
	ds_read_b128 v[170:173], v170 offset:3072
	v_lshl_add_u64 v[196:197], s[4:5], 0, v[138:139]
	s_add_i32 m0, s25, 0xc000
	ds_read_b128 v[174:177], v190
	ds_read_b128 v[178:181], v190 offset:1024
	ds_read_b128 v[182:185], v190 offset:2048
	ds_read_b128 v[186:189], v190 offset:3072
	ds_read_b128 v[192:195], v190 offset:4096
	ds_read_b128 v[204:207], v190 offset:5120
	ds_read_b128 v[208:211], v190 offset:6144
	ds_read_b128 v[212:215], v190 offset:7168
	global_load_lds_dwordx4 v[196:197], off
	s_add_i32 m0, s25, 0xe000
	v_lshl_add_u64 v[196:197], s[4:5], 0, v[140:141]
	global_load_lds_dwordx4 v[196:197], off
	s_waitcnt vmcnt(8)
	s_waitcnt lgkmcnt(0)
	s_barrier
	s_setprio 1
	s_waitcnt lgkmcnt(0)
	v_mfma_f32_16x16x32_bf16 v[126:129], v[142:145], v[174:177], v[126:129]
	v_mfma_f32_16x16x32_bf16 v[122:125], v[150:153], v[174:177], v[122:125]
	v_mfma_f32_16x16x32_bf16 v[110:113], v[142:145], v[182:185], v[110:113]
	v_mfma_f32_16x16x32_bf16 v[106:109], v[150:153], v[182:185], v[106:109]
	v_mfma_f32_16x16x32_bf16 v[94:97], v[142:145], v[192:195], v[94:97]
	v_mfma_f32_16x16x32_bf16 v[90:93], v[150:153], v[192:195], v[90:93]
	v_mfma_f32_16x16x32_bf16 v[78:81], v[142:145], v[208:211], v[78:81]
	v_mfma_f32_16x16x32_bf16 v[74:77], v[150:153], v[208:211], v[74:77]
	v_mfma_f32_16x16x32_bf16 v[126:129], v[146:149], v[178:181], v[126:129]
	v_mfma_f32_16x16x32_bf16 v[122:125], v[154:157], v[178:181], v[122:125]
	v_mfma_f32_16x16x32_bf16 v[110:113], v[146:149], v[186:189], v[110:113]
	v_mfma_f32_16x16x32_bf16 v[106:109], v[154:157], v[186:189], v[106:109]
	v_mfma_f32_16x16x32_bf16 v[94:97], v[146:149], v[204:207], v[94:97]
	v_mfma_f32_16x16x32_bf16 v[90:93], v[154:157], v[204:207], v[90:93]
	v_mfma_f32_16x16x32_bf16 v[78:81], v[146:149], v[212:215], v[78:81]
	v_mfma_f32_16x16x32_bf16 v[74:77], v[154:157], v[212:215], v[74:77]
	v_mfma_f32_16x16x32_bf16 v[118:121], v[158:161], v[174:177], v[118:121]
	v_mfma_f32_16x16x32_bf16 v[114:117], v[166:169], v[174:177], v[114:117]
	v_mfma_f32_16x16x32_bf16 v[102:105], v[158:161], v[182:185], v[102:105]
	v_mfma_f32_16x16x32_bf16 v[98:101], v[166:169], v[182:185], v[98:101]
	v_mfma_f32_16x16x32_bf16 v[86:89], v[158:161], v[192:195], v[86:89]
	v_mfma_f32_16x16x32_bf16 v[82:85], v[166:169], v[192:195], v[82:85]
	v_mfma_f32_16x16x32_bf16 v[70:73], v[158:161], v[208:211], v[70:73]
	v_mfma_f32_16x16x32_bf16 v[66:69], v[166:169], v[208:211], v[66:69]
	v_mfma_f32_16x16x32_bf16 v[118:121], v[162:165], v[178:181], v[118:121]
	v_mfma_f32_16x16x32_bf16 v[114:117], v[170:173], v[178:181], v[114:117]
	v_mfma_f32_16x16x32_bf16 v[102:105], v[162:165], v[186:189], v[102:105]
	v_mfma_f32_16x16x32_bf16 v[98:101], v[170:173], v[186:189], v[98:101]
	v_mfma_f32_16x16x32_bf16 v[86:89], v[162:165], v[204:207], v[86:89]
	v_mfma_f32_16x16x32_bf16 v[82:85], v[170:173], v[204:207], v[82:85]
	v_mfma_f32_16x16x32_bf16 v[70:73], v[162:165], v[212:215], v[70:73]
	v_mfma_f32_16x16x32_bf16 v[66:69], v[170:173], v[212:215], v[66:69]
	s_setprio 0
	s_barrier
	s_add_i32 s58, s58, s40
	v_lshl_add_u64 v[196:197], s[28:29], 0, v[132:133]
	s_mov_b32 m0, s58
	ds_read_b128 v[174:177], v190 offset:16384
	ds_read_b128 v[178:181], v190 offset:17408
	ds_read_b128 v[182:185], v190 offset:18432
	ds_read_b128 v[186:189], v190 offset:19456
	ds_read_b128 v[192:195], v190 offset:20480
	ds_read_b128 v[204:207], v190 offset:21504
	ds_read_b128 v[208:211], v190 offset:22528
	ds_read_b128 v[212:215], v190 offset:23552
	global_load_lds_dwordx4 v[196:197], off
	s_add_i32 m0, s58, 0x2000
	s_add_u32 s58, s28, 0x40000
	v_lshl_add_u64 v[198:199], s[28:29], 0, v[136:137]
	s_addc_u32 s59, s29, 0
	s_add_i32 s60, s60, s40
	global_load_lds_dwordx4 v[198:199], off
	v_lshl_add_u64 v[216:217], s[58:59], 0, v[132:133]
	s_mov_b32 m0, s60
	v_lshl_add_u64 v[220:221], s[30:31], 0, v[134:135]
	global_load_lds_dwordx4 v[216:217], off
	s_add_i32 m0, s60, 0x2000
	v_lshl_add_u64 v[216:217], s[58:59], 0, v[136:137]
	global_load_lds_dwordx4 v[216:217], off
	s_mov_b32 m0, s25
	v_lshl_add_u64 v[216:217], s[30:31], 0, v[130:131]
	global_load_lds_dwordx4 v[216:217], off
	s_mov_b32 m0, s27
	s_nop 0
	global_load_lds_dwordx4 v[220:221], off
	s_waitcnt vmcnt(8)
	s_waitcnt lgkmcnt(0)
	s_barrier
	s_setprio 1
	s_waitcnt lgkmcnt(0)
	v_mfma_f32_16x16x32_bf16 v[62:65], v[142:145], v[174:177], v[62:65]
	v_mfma_f32_16x16x32_bf16 v[58:61], v[150:153], v[174:177], v[58:61]
	v_mfma_f32_16x16x32_bf16 v[46:49], v[142:145], v[182:185], v[46:49]
	v_mfma_f32_16x16x32_bf16 v[42:45], v[150:153], v[182:185], v[42:45]
	v_mfma_f32_16x16x32_bf16 v[30:33], v[142:145], v[192:195], v[30:33]
	v_mfma_f32_16x16x32_bf16 v[26:29], v[150:153], v[192:195], v[26:29]
	v_mfma_f32_16x16x32_bf16 v[14:17], v[142:145], v[208:211], v[14:17]
	v_mfma_f32_16x16x32_bf16 v[10:13], v[150:153], v[208:211], v[10:13]
	v_mfma_f32_16x16x32_bf16 v[62:65], v[146:149], v[178:181], v[62:65]
	v_mfma_f32_16x16x32_bf16 v[58:61], v[154:157], v[178:181], v[58:61]
	v_mfma_f32_16x16x32_bf16 v[46:49], v[146:149], v[186:189], v[46:49]
	v_mfma_f32_16x16x32_bf16 v[42:45], v[154:157], v[186:189], v[42:45]
	v_mfma_f32_16x16x32_bf16 v[30:33], v[146:149], v[204:207], v[30:33]
	v_mfma_f32_16x16x32_bf16 v[26:29], v[154:157], v[204:207], v[26:29]
	v_mfma_f32_16x16x32_bf16 v[14:17], v[146:149], v[212:215], v[14:17]
	v_mfma_f32_16x16x32_bf16 v[10:13], v[154:157], v[212:215], v[10:13]
	v_mfma_f32_16x16x32_bf16 v[54:57], v[158:161], v[174:177], v[54:57]
	v_mfma_f32_16x16x32_bf16 v[50:53], v[166:169], v[174:177], v[50:53]
	v_mfma_f32_16x16x32_bf16 v[38:41], v[158:161], v[182:185], v[38:41]
	v_mfma_f32_16x16x32_bf16 v[34:37], v[166:169], v[182:185], v[34:37]
	v_mfma_f32_16x16x32_bf16 v[22:25], v[158:161], v[192:195], v[22:25]
	v_mfma_f32_16x16x32_bf16 v[18:21], v[166:169], v[192:195], v[18:21]
	v_mfma_f32_16x16x32_bf16 v[6:9], v[158:161], v[208:211], v[6:9]
	v_mfma_f32_16x16x32_bf16 v[2:5], v[166:169], v[208:211], v[2:5]
	v_mfma_f32_16x16x32_bf16 v[54:57], v[162:165], v[178:181], v[54:57]
	v_mfma_f32_16x16x32_bf16 v[50:53], v[170:173], v[178:181], v[50:53]
	v_mfma_f32_16x16x32_bf16 v[38:41], v[162:165], v[186:189], v[38:41]
	v_mfma_f32_16x16x32_bf16 v[34:37], v[170:173], v[186:189], v[34:37]
	v_mfma_f32_16x16x32_bf16 v[22:25], v[162:165], v[204:207], v[22:25]
	v_mfma_f32_16x16x32_bf16 v[18:21], v[170:173], v[204:207], v[18:21]
	v_mfma_f32_16x16x32_bf16 v[6:9], v[162:165], v[212:215], v[6:9]
	v_mfma_f32_16x16x32_bf16 v[2:5], v[170:173], v[212:215], v[2:5]
	s_setprio 0
	s_barrier
	s_add_i32 s58, 0, 0x18000
	s_add_i32 s59, 0, 0x1c000
	v_add_u32_e32 v154, s58, v1
	v_add_u32_e32 v170, s59, v1
	ds_read_b128 v[142:145], v154
	ds_read_b128 v[146:149], v154 offset:1024
	ds_read_b128 v[150:153], v154 offset:2048
	ds_read_b128 v[154:157], v154 offset:3072
	ds_read_b128 v[158:161], v170
	ds_read_b128 v[162:165], v170 offset:1024
	ds_read_b128 v[166:169], v170 offset:2048
	ds_read_b128 v[170:173], v170 offset:3072
	s_add_u32 s30, s30, 0x40000
	s_addc_u32 s31, s31, 0
	s_mov_b32 m0, s41
	v_lshl_add_u64 v[222:223], s[30:31], 0, v[130:131]
	ds_read_b128 v[174:177], v190 offset:32768
	ds_read_b128 v[178:181], v190 offset:33792
	ds_read_b128 v[182:185], v190 offset:34816
	ds_read_b128 v[186:189], v190 offset:35840
	ds_read_b128 v[192:195], v190 offset:36864
	ds_read_b128 v[204:207], v190 offset:37888
	ds_read_b128 v[208:211], v190 offset:38912
	ds_read_b128 v[212:215], v190 offset:39936
	global_load_lds_dwordx4 v[222:223], off
	s_mov_b32 m0, s42
	v_lshl_add_u64 v[222:223], s[30:31], 0, v[134:135]
	global_load_lds_dwordx4 v[222:223], off
	s_waitcnt vmcnt(8)
	s_waitcnt lgkmcnt(0)
	s_barrier
	s_setprio 1
	s_waitcnt lgkmcnt(0)
	v_mfma_f32_16x16x32_bf16 v[126:129], v[142:145], v[174:177], v[126:129]
	v_mfma_f32_16x16x32_bf16 v[122:125], v[150:153], v[174:177], v[122:125]
	v_mfma_f32_16x16x32_bf16 v[110:113], v[142:145], v[182:185], v[110:113]
	v_mfma_f32_16x16x32_bf16 v[106:109], v[150:153], v[182:185], v[106:109]
	v_mfma_f32_16x16x32_bf16 v[94:97], v[142:145], v[192:195], v[94:97]
	v_mfma_f32_16x16x32_bf16 v[90:93], v[150:153], v[192:195], v[90:93]
	v_mfma_f32_16x16x32_bf16 v[78:81], v[142:145], v[208:211], v[78:81]
	v_mfma_f32_16x16x32_bf16 v[74:77], v[150:153], v[208:211], v[74:77]
	v_mfma_f32_16x16x32_bf16 v[126:129], v[146:149], v[178:181], v[126:129]
	v_mfma_f32_16x16x32_bf16 v[122:125], v[154:157], v[178:181], v[122:125]
	v_mfma_f32_16x16x32_bf16 v[110:113], v[146:149], v[186:189], v[110:113]
	v_mfma_f32_16x16x32_bf16 v[106:109], v[154:157], v[186:189], v[106:109]
	v_mfma_f32_16x16x32_bf16 v[94:97], v[146:149], v[204:207], v[94:97]
	v_mfma_f32_16x16x32_bf16 v[90:93], v[154:157], v[204:207], v[90:93]
	v_mfma_f32_16x16x32_bf16 v[78:81], v[146:149], v[212:215], v[78:81]
	v_mfma_f32_16x16x32_bf16 v[74:77], v[154:157], v[212:215], v[74:77]
	v_mfma_f32_16x16x32_bf16 v[118:121], v[158:161], v[174:177], v[118:121]
	v_mfma_f32_16x16x32_bf16 v[114:117], v[166:169], v[174:177], v[114:117]
	v_mfma_f32_16x16x32_bf16 v[102:105], v[158:161], v[182:185], v[102:105]
	v_mfma_f32_16x16x32_bf16 v[98:101], v[166:169], v[182:185], v[98:101]
	v_mfma_f32_16x16x32_bf16 v[86:89], v[158:161], v[192:195], v[86:89]
	v_mfma_f32_16x16x32_bf16 v[82:85], v[166:169], v[192:195], v[82:85]
	v_mfma_f32_16x16x32_bf16 v[70:73], v[158:161], v[208:211], v[70:73]
	v_mfma_f32_16x16x32_bf16 v[66:69], v[166:169], v[208:211], v[66:69]
	v_mfma_f32_16x16x32_bf16 v[118:121], v[162:165], v[178:181], v[118:121]
	v_mfma_f32_16x16x32_bf16 v[114:117], v[170:173], v[178:181], v[114:117]
	v_mfma_f32_16x16x32_bf16 v[102:105], v[162:165], v[186:189], v[102:105]
	v_mfma_f32_16x16x32_bf16 v[98:101], v[170:173], v[186:189], v[98:101]
	v_mfma_f32_16x16x32_bf16 v[86:89], v[162:165], v[204:207], v[86:89]
	v_mfma_f32_16x16x32_bf16 v[82:85], v[170:173], v[204:207], v[82:85]
	v_mfma_f32_16x16x32_bf16 v[70:73], v[162:165], v[212:215], v[70:73]
	v_mfma_f32_16x16x32_bf16 v[66:69], v[170:173], v[212:215], v[66:69]
	s_setprio 0
	s_barrier
	s_add_i32 s30, s58, s40
	v_lshl_add_u64 v[196:197], v[196:197], 0, s[94:95]
	s_mov_b32 m0, s30
	ds_read_b128 v[174:177], v190 offset:49152
	ds_read_b128 v[178:181], v190 offset:50176
	ds_read_b128 v[182:185], v190 offset:51200
	ds_read_b128 v[186:189], v190 offset:52224
	ds_read_b128 v[192:195], v190 offset:53248
	ds_read_b128 v[204:207], v190 offset:54272
	ds_read_b128 v[208:211], v190 offset:55296
	ds_read_b128 v[212:215], v190 offset:56320
	global_load_lds_dwordx4 v[196:197], off
	s_add_i32 m0, s30, 0x2000
	s_add_u32 s28, s28, 0x40080
	v_lshl_add_u64 v[196:197], v[198:199], 0, s[94:95]
	s_addc_u32 s29, s29, 0
	s_add_i32 s30, s59, s40
	global_load_lds_dwordx4 v[196:197], off
	s_mov_b32 m0, s30
	v_lshl_add_u64 v[196:197], s[28:29], 0, v[132:133]
	global_load_lds_dwordx4 v[196:197], off
	s_add_i32 m0, s30, 0x2000
	v_lshl_add_u64 v[196:197], s[28:29], 0, v[136:137]
	global_load_lds_dwordx4 v[196:197], off
	s_mov_b32 m0, s45
	v_lshl_add_u64 v[196:197], v[216:217], 0, s[94:95]
	global_load_lds_dwordx4 v[196:197], off
	s_mov_b32 m0, s46
	v_lshl_add_u64 v[196:197], v[220:221], 0, s[94:95]
	global_load_lds_dwordx4 v[196:197], off
	s_waitcnt vmcnt(8)
	s_waitcnt lgkmcnt(0)
	s_barrier
	s_setprio 1
	s_waitcnt lgkmcnt(0)
	v_mfma_f32_16x16x32_bf16 v[62:65], v[142:145], v[174:177], v[62:65]
	v_mfma_f32_16x16x32_bf16 v[58:61], v[150:153], v[174:177], v[58:61]
	v_mfma_f32_16x16x32_bf16 v[46:49], v[142:145], v[182:185], v[46:49]
	v_mfma_f32_16x16x32_bf16 v[42:45], v[150:153], v[182:185], v[42:45]
	v_mfma_f32_16x16x32_bf16 v[30:33], v[142:145], v[192:195], v[30:33]
	v_mfma_f32_16x16x32_bf16 v[26:29], v[150:153], v[192:195], v[26:29]
	v_mfma_f32_16x16x32_bf16 v[14:17], v[142:145], v[208:211], v[14:17]
	v_mfma_f32_16x16x32_bf16 v[10:13], v[150:153], v[208:211], v[10:13]
	v_mfma_f32_16x16x32_bf16 v[62:65], v[146:149], v[178:181], v[62:65]
	v_mfma_f32_16x16x32_bf16 v[58:61], v[154:157], v[178:181], v[58:61]
	v_mfma_f32_16x16x32_bf16 v[46:49], v[146:149], v[186:189], v[46:49]
	v_mfma_f32_16x16x32_bf16 v[42:45], v[154:157], v[186:189], v[42:45]
	v_mfma_f32_16x16x32_bf16 v[30:33], v[146:149], v[204:207], v[30:33]
	v_mfma_f32_16x16x32_bf16 v[26:29], v[154:157], v[204:207], v[26:29]
	v_mfma_f32_16x16x32_bf16 v[14:17], v[146:149], v[212:215], v[14:17]
	v_mfma_f32_16x16x32_bf16 v[10:13], v[154:157], v[212:215], v[10:13]
	v_mfma_f32_16x16x32_bf16 v[54:57], v[158:161], v[174:177], v[54:57]
	v_mfma_f32_16x16x32_bf16 v[50:53], v[166:169], v[174:177], v[50:53]
	v_mfma_f32_16x16x32_bf16 v[38:41], v[158:161], v[182:185], v[38:41]
	v_mfma_f32_16x16x32_bf16 v[34:37], v[166:169], v[182:185], v[34:37]
	v_mfma_f32_16x16x32_bf16 v[22:25], v[158:161], v[192:195], v[22:25]
	v_mfma_f32_16x16x32_bf16 v[18:21], v[166:169], v[192:195], v[18:21]
	v_mfma_f32_16x16x32_bf16 v[6:9], v[158:161], v[208:211], v[6:9]
	v_mfma_f32_16x16x32_bf16 v[2:5], v[166:169], v[208:211], v[2:5]
	v_mfma_f32_16x16x32_bf16 v[54:57], v[162:165], v[178:181], v[54:57]
	v_mfma_f32_16x16x32_bf16 v[50:53], v[170:173], v[178:181], v[50:53]
	v_mfma_f32_16x16x32_bf16 v[38:41], v[162:165], v[186:189], v[38:41]
	v_mfma_f32_16x16x32_bf16 v[34:37], v[170:173], v[186:189], v[34:37]
	v_mfma_f32_16x16x32_bf16 v[22:25], v[162:165], v[204:207], v[22:25]
	v_mfma_f32_16x16x32_bf16 v[18:21], v[170:173], v[204:207], v[18:21]
	v_mfma_f32_16x16x32_bf16 v[6:9], v[162:165], v[212:215], v[6:9]
	v_mfma_f32_16x16x32_bf16 v[2:5], v[170:173], v[212:215], v[2:5]
	s_setprio 0
	s_barrier
	s_add_i32 s57, s57, 2
	s_add_u32 s4, s4, 0x100
	s_addc_u32 s5, s5, 0
	s_add_u32 s55, s55, 0x100
	s_addc_u32 s56, s56, 0
	s_cmp_gt_u32 s57, 13
	s_cbranch_scc0 .LBB0_984
	s_and_b64 vcc, exec, s[14:15]
	s_cbranch_vccz .LBB0_987
	s_barrier

.LBB0_1096:
	s_add_u32 s28, s4, 0xfffc0080
	s_addc_u32 s29, s5, -1
	s_add_i32 s53, 0, 0x10000
	s_cmp_eq_u32 s52, 12
	s_cselect_b32 s31, s17, s29
	s_cselect_b32 s30, s19, s28
	s_cselect_b32 s29, s21, s51
	s_cselect_b32 s28, s20, s50
	s_add_i32 s56, 0, 0x14000
	v_add_u32_e32 v134, s53, v1
	v_add_u32_e32 v154, s56, v1
	ds_read_b128 v[110:113], v134
	ds_read_b128 v[118:121], v134 offset:1024
	ds_read_b128 v[122:125], v134 offset:2048
	ds_read_b128 v[134:137], v134 offset:3072
	ds_read_b128 v[138:141], v154
	ds_read_b128 v[142:145], v154 offset:1024
	ds_read_b128 v[146:149], v154 offset:2048
	ds_read_b128 v[154:157], v154 offset:3072
	v_lshl_add_u64 v[196:197], s[4:5], 0, v[206:207]
	s_add_i32 m0, s25, 0xc000
	ds_read_b128 v[162:165], v214
	ds_read_b128 v[166:169], v214 offset:1024
	ds_read_b128 v[170:173], v214 offset:2048
	ds_read_b128 v[174:177], v214 offset:3072
	ds_read_b128 v[178:181], v214 offset:4096
	ds_read_b128 v[182:185], v214 offset:5120
	ds_read_b128 v[186:189], v214 offset:6144
	ds_read_b128 v[210:213], v214 offset:7168
	global_load_lds_dwordx4 v[196:197], off
	s_add_i32 m0, s25, 0xe000
	v_lshl_add_u64 v[196:197], s[4:5], 0, v[208:209]
	global_load_lds_dwordx4 v[196:197], off
	s_waitcnt vmcnt(8)
	s_waitcnt lgkmcnt(0)
	s_barrier
	s_setprio 1
	s_waitcnt lgkmcnt(0)
	v_mfma_f32_16x16x32_bf16 v[158:161], v[110:113], v[162:165], v[158:161]
	v_mfma_f32_16x16x32_bf16 v[150:153], v[122:125], v[162:165], v[150:153]
	v_mfma_f32_16x16x32_bf16 v[114:117], v[110:113], v[170:173], v[114:117]
	v_mfma_f32_16x16x32_bf16 v[106:109], v[122:125], v[170:173], v[106:109]
	v_mfma_f32_16x16x32_bf16 v[94:97], v[110:113], v[178:181], v[94:97]
	v_mfma_f32_16x16x32_bf16 v[90:93], v[122:125], v[178:181], v[90:93]
	v_mfma_f32_16x16x32_bf16 v[78:81], v[110:113], v[186:189], v[78:81]
	v_mfma_f32_16x16x32_bf16 v[74:77], v[122:125], v[186:189], v[74:77]
	v_mfma_f32_16x16x32_bf16 v[158:161], v[118:121], v[166:169], v[158:161]
	v_mfma_f32_16x16x32_bf16 v[150:153], v[134:137], v[166:169], v[150:153]
	v_mfma_f32_16x16x32_bf16 v[114:117], v[118:121], v[174:177], v[114:117]
	v_mfma_f32_16x16x32_bf16 v[106:109], v[134:137], v[174:177], v[106:109]
	v_mfma_f32_16x16x32_bf16 v[94:97], v[118:121], v[182:185], v[94:97]
	v_mfma_f32_16x16x32_bf16 v[90:93], v[134:137], v[182:185], v[90:93]
	v_mfma_f32_16x16x32_bf16 v[78:81], v[118:121], v[210:213], v[78:81]
	v_mfma_f32_16x16x32_bf16 v[74:77], v[134:137], v[210:213], v[74:77]
	v_mfma_f32_16x16x32_bf16 v[130:133], v[138:141], v[162:165], v[130:133]
	v_mfma_f32_16x16x32_bf16 v[126:129], v[146:149], v[162:165], v[126:129]
	v_mfma_f32_16x16x32_bf16 v[102:105], v[138:141], v[170:173], v[102:105]
	v_mfma_f32_16x16x32_bf16 v[98:101], v[146:149], v[170:173], v[98:101]
	v_mfma_f32_16x16x32_bf16 v[86:89], v[138:141], v[178:181], v[86:89]
	v_mfma_f32_16x16x32_bf16 v[82:85], v[146:149], v[178:181], v[82:85]
	v_mfma_f32_16x16x32_bf16 v[70:73], v[138:141], v[186:189], v[70:73]
	v_mfma_f32_16x16x32_bf16 v[66:69], v[146:149], v[186:189], v[66:69]
	v_mfma_f32_16x16x32_bf16 v[130:133], v[142:145], v[166:169], v[130:133]
	v_mfma_f32_16x16x32_bf16 v[126:129], v[154:157], v[166:169], v[126:129]
	v_mfma_f32_16x16x32_bf16 v[102:105], v[142:145], v[174:177], v[102:105]
	v_mfma_f32_16x16x32_bf16 v[98:101], v[154:157], v[174:177], v[98:101]
	v_mfma_f32_16x16x32_bf16 v[86:89], v[142:145], v[182:185], v[86:89]
	v_mfma_f32_16x16x32_bf16 v[82:85], v[154:157], v[182:185], v[82:85]
	v_mfma_f32_16x16x32_bf16 v[70:73], v[142:145], v[210:213], v[70:73]
	v_mfma_f32_16x16x32_bf16 v[66:69], v[154:157], v[210:213], v[66:69]
	s_setprio 0
	s_barrier
	s_add_i32 s53, s53, s40
	v_lshl_add_u64 v[196:197], s[28:29], 0, v[192:193]
	s_mov_b32 m0, s53
	ds_read_b128 v[162:165], v214 offset:16384
	ds_read_b128 v[166:169], v214 offset:17408
	ds_read_b128 v[170:173], v214 offset:18432
	ds_read_b128 v[174:177], v214 offset:19456
	ds_read_b128 v[178:181], v214 offset:20480
	ds_read_b128 v[182:185], v214 offset:21504
	ds_read_b128 v[186:189], v214 offset:22528
	ds_read_b128 v[210:213], v214 offset:23552
	global_load_lds_dwordx4 v[196:197], off
	s_add_i32 m0, s53, 0x2000
	s_add_u32 s54, s28, 0x40000
	v_lshl_add_u64 v[198:199], s[28:29], 0, v[204:205]
	s_addc_u32 s55, s29, 0
	s_add_i32 s53, s56, s40
	global_load_lds_dwordx4 v[198:199], off
	v_lshl_add_u64 v[216:217], s[54:55], 0, v[192:193]
	s_mov_b32 m0, s53
	v_lshl_add_u64 v[220:221], s[30:31], 0, v[194:195]
	global_load_lds_dwordx4 v[216:217], off
	s_add_i32 m0, s53, 0x2000
	v_lshl_add_u64 v[216:217], s[54:55], 0, v[204:205]
	global_load_lds_dwordx4 v[216:217], off
	s_mov_b32 m0, s25
	v_lshl_add_u64 v[216:217], s[30:31], 0, v[190:191]
	global_load_lds_dwordx4 v[216:217], off
	s_mov_b32 m0, s27
	s_nop 0
	global_load_lds_dwordx4 v[220:221], off
	s_waitcnt vmcnt(8)
	s_waitcnt lgkmcnt(0)
	s_barrier
	s_setprio 1
	s_waitcnt lgkmcnt(0)
	v_mfma_f32_16x16x32_bf16 v[62:65], v[110:113], v[162:165], v[62:65]
	v_mfma_f32_16x16x32_bf16 v[58:61], v[122:125], v[162:165], v[58:61]
	v_mfma_f32_16x16x32_bf16 v[46:49], v[110:113], v[170:173], v[46:49]
	v_mfma_f32_16x16x32_bf16 v[42:45], v[122:125], v[170:173], v[42:45]
	v_mfma_f32_16x16x32_bf16 v[30:33], v[110:113], v[178:181], v[30:33]
	v_mfma_f32_16x16x32_bf16 v[26:29], v[122:125], v[178:181], v[26:29]
	v_mfma_f32_16x16x32_bf16 v[14:17], v[110:113], v[186:189], v[14:17]
	v_mfma_f32_16x16x32_bf16 v[10:13], v[122:125], v[186:189], v[10:13]
	v_mfma_f32_16x16x32_bf16 v[62:65], v[118:121], v[166:169], v[62:65]
	v_mfma_f32_16x16x32_bf16 v[58:61], v[134:137], v[166:169], v[58:61]
	v_mfma_f32_16x16x32_bf16 v[46:49], v[118:121], v[174:177], v[46:49]
	v_mfma_f32_16x16x32_bf16 v[42:45], v[134:137], v[174:177], v[42:45]
	v_mfma_f32_16x16x32_bf16 v[30:33], v[118:121], v[182:185], v[30:33]
	v_mfma_f32_16x16x32_bf16 v[26:29], v[134:137], v[182:185], v[26:29]
	v_mfma_f32_16x16x32_bf16 v[14:17], v[118:121], v[210:213], v[14:17]
	v_mfma_f32_16x16x32_bf16 v[10:13], v[134:137], v[210:213], v[10:13]
	v_mfma_f32_16x16x32_bf16 v[54:57], v[138:141], v[162:165], v[54:57]
	v_mfma_f32_16x16x32_bf16 v[50:53], v[146:149], v[162:165], v[50:53]
	v_mfma_f32_16x16x32_bf16 v[38:41], v[138:141], v[170:173], v[38:41]
	v_mfma_f32_16x16x32_bf16 v[34:37], v[146:149], v[170:173], v[34:37]
	v_mfma_f32_16x16x32_bf16 v[22:25], v[138:141], v[178:181], v[22:25]
	v_mfma_f32_16x16x32_bf16 v[18:21], v[146:149], v[178:181], v[18:21]
	v_mfma_f32_16x16x32_bf16 v[6:9], v[138:141], v[186:189], v[6:9]
	v_mfma_f32_16x16x32_bf16 v[2:5], v[146:149], v[186:189], v[2:5]
	v_mfma_f32_16x16x32_bf16 v[54:57], v[142:145], v[166:169], v[54:57]
	v_mfma_f32_16x16x32_bf16 v[50:53], v[154:157], v[166:169], v[50:53]
	v_mfma_f32_16x16x32_bf16 v[38:41], v[142:145], v[174:177], v[38:41]
	v_mfma_f32_16x16x32_bf16 v[34:37], v[154:157], v[174:177], v[34:37]
	v_mfma_f32_16x16x32_bf16 v[22:25], v[142:145], v[182:185], v[22:25]
	v_mfma_f32_16x16x32_bf16 v[18:21], v[154:157], v[182:185], v[18:21]
	v_mfma_f32_16x16x32_bf16 v[6:9], v[142:145], v[210:213], v[6:9]
	v_mfma_f32_16x16x32_bf16 v[2:5], v[154:157], v[210:213], v[2:5]
	s_setprio 0
	s_barrier
	s_add_i32 s53, 0, 0x18000
	s_add_i32 s54, 0, 0x1c000
	v_add_u32_e32 v134, s53, v1
	v_add_u32_e32 v154, s54, v1
	ds_read_b128 v[110:113], v134
	ds_read_b128 v[118:121], v134 offset:1024
	ds_read_b128 v[122:125], v134 offset:2048
	ds_read_b128 v[134:137], v134 offset:3072
	ds_read_b128 v[138:141], v154
	ds_read_b128 v[142:145], v154 offset:1024
	ds_read_b128 v[146:149], v154 offset:2048
	ds_read_b128 v[154:157], v154 offset:3072
	s_add_u32 s30, s30, 0x40000
	s_addc_u32 s31, s31, 0
	s_mov_b32 m0, s41
	v_lshl_add_u64 v[222:223], s[30:31], 0, v[190:191]
	ds_read_b128 v[162:165], v214 offset:32768
	ds_read_b128 v[166:169], v214 offset:33792
	ds_read_b128 v[170:173], v214 offset:34816
	ds_read_b128 v[174:177], v214 offset:35840
	ds_read_b128 v[178:181], v214 offset:36864
	ds_read_b128 v[182:185], v214 offset:37888
	ds_read_b128 v[186:189], v214 offset:38912
	ds_read_b128 v[210:213], v214 offset:39936
	global_load_lds_dwordx4 v[222:223], off
	s_mov_b32 m0, s42
	v_lshl_add_u64 v[222:223], s[30:31], 0, v[194:195]
	global_load_lds_dwordx4 v[222:223], off
	s_waitcnt vmcnt(8)
	s_waitcnt lgkmcnt(0)
	s_barrier
	s_setprio 1
	s_waitcnt lgkmcnt(0)
	v_mfma_f32_16x16x32_bf16 v[158:161], v[110:113], v[162:165], v[158:161]
	v_mfma_f32_16x16x32_bf16 v[150:153], v[122:125], v[162:165], v[150:153]
	v_mfma_f32_16x16x32_bf16 v[114:117], v[110:113], v[170:173], v[114:117]
	v_mfma_f32_16x16x32_bf16 v[106:109], v[122:125], v[170:173], v[106:109]
	v_mfma_f32_16x16x32_bf16 v[94:97], v[110:113], v[178:181], v[94:97]
	v_mfma_f32_16x16x32_bf16 v[90:93], v[122:125], v[178:181], v[90:93]
	v_mfma_f32_16x16x32_bf16 v[78:81], v[110:113], v[186:189], v[78:81]
	v_mfma_f32_16x16x32_bf16 v[74:77], v[122:125], v[186:189], v[74:77]
	v_mfma_f32_16x16x32_bf16 v[158:161], v[118:121], v[166:169], v[158:161]
	v_mfma_f32_16x16x32_bf16 v[150:153], v[134:137], v[166:169], v[150:153]
	v_mfma_f32_16x16x32_bf16 v[114:117], v[118:121], v[174:177], v[114:117]
	v_mfma_f32_16x16x32_bf16 v[106:109], v[134:137], v[174:177], v[106:109]
	v_mfma_f32_16x16x32_bf16 v[94:97], v[118:121], v[182:185], v[94:97]
	v_mfma_f32_16x16x32_bf16 v[90:93], v[134:137], v[182:185], v[90:93]
	v_mfma_f32_16x16x32_bf16 v[78:81], v[118:121], v[210:213], v[78:81]
	v_mfma_f32_16x16x32_bf16 v[74:77], v[134:137], v[210:213], v[74:77]
	v_mfma_f32_16x16x32_bf16 v[130:133], v[138:141], v[162:165], v[130:133]
	v_mfma_f32_16x16x32_bf16 v[126:129], v[146:149], v[162:165], v[126:129]
	v_mfma_f32_16x16x32_bf16 v[102:105], v[138:141], v[170:173], v[102:105]
	v_mfma_f32_16x16x32_bf16 v[98:101], v[146:149], v[170:173], v[98:101]
	v_mfma_f32_16x16x32_bf16 v[86:89], v[138:141], v[178:181], v[86:89]
	v_mfma_f32_16x16x32_bf16 v[82:85], v[146:149], v[178:181], v[82:85]
	v_mfma_f32_16x16x32_bf16 v[70:73], v[138:141], v[186:189], v[70:73]
	v_mfma_f32_16x16x32_bf16 v[66:69], v[146:149], v[186:189], v[66:69]
	v_mfma_f32_16x16x32_bf16 v[130:133], v[142:145], v[166:169], v[130:133]
	v_mfma_f32_16x16x32_bf16 v[126:129], v[154:157], v[166:169], v[126:129]
	v_mfma_f32_16x16x32_bf16 v[102:105], v[142:145], v[174:177], v[102:105]
	v_mfma_f32_16x16x32_bf16 v[98:101], v[154:157], v[174:177], v[98:101]
	v_mfma_f32_16x16x32_bf16 v[86:89], v[142:145], v[182:185], v[86:89]
	v_mfma_f32_16x16x32_bf16 v[82:85], v[154:157], v[182:185], v[82:85]
	v_mfma_f32_16x16x32_bf16 v[70:73], v[142:145], v[210:213], v[70:73]
	v_mfma_f32_16x16x32_bf16 v[66:69], v[154:157], v[210:213], v[66:69]
	s_setprio 0
	s_barrier
	s_add_i32 s30, s53, s40
	v_lshl_add_u64 v[196:197], v[196:197], 0, s[94:95]
	s_mov_b32 m0, s30
	ds_read_b128 v[162:165], v214 offset:49152
	ds_read_b128 v[166:169], v214 offset:50176
	ds_read_b128 v[170:173], v214 offset:51200
	ds_read_b128 v[174:177], v214 offset:52224
	ds_read_b128 v[178:181], v214 offset:53248
	ds_read_b128 v[182:185], v214 offset:54272
	ds_read_b128 v[186:189], v214 offset:55296
	ds_read_b128 v[210:213], v214 offset:56320
	global_load_lds_dwordx4 v[196:197], off
	s_add_i32 m0, s30, 0x2000
	s_add_u32 s28, s28, 0x40080
	v_lshl_add_u64 v[196:197], v[198:199], 0, s[94:95]
	s_addc_u32 s29, s29, 0
	s_add_i32 s30, s54, s40
	global_load_lds_dwordx4 v[196:197], off
	s_mov_b32 m0, s30
	v_lshl_add_u64 v[196:197], s[28:29], 0, v[192:193]
	global_load_lds_dwordx4 v[196:197], off
	s_add_i32 m0, s30, 0x2000
	v_lshl_add_u64 v[196:197], s[28:29], 0, v[204:205]
	global_load_lds_dwordx4 v[196:197], off
	s_mov_b32 m0, s45
	v_lshl_add_u64 v[196:197], v[216:217], 0, s[94:95]
	global_load_lds_dwordx4 v[196:197], off
	s_mov_b32 m0, s46
	v_lshl_add_u64 v[196:197], v[220:221], 0, s[94:95]
	global_load_lds_dwordx4 v[196:197], off
	s_waitcnt vmcnt(8)
	s_waitcnt lgkmcnt(0)
	s_barrier
	s_setprio 1
	s_waitcnt lgkmcnt(0)
	v_mfma_f32_16x16x32_bf16 v[62:65], v[110:113], v[162:165], v[62:65]
	v_mfma_f32_16x16x32_bf16 v[58:61], v[122:125], v[162:165], v[58:61]
	v_mfma_f32_16x16x32_bf16 v[46:49], v[110:113], v[170:173], v[46:49]
	v_mfma_f32_16x16x32_bf16 v[42:45], v[122:125], v[170:173], v[42:45]
	v_mfma_f32_16x16x32_bf16 v[30:33], v[110:113], v[178:181], v[30:33]
	v_mfma_f32_16x16x32_bf16 v[26:29], v[122:125], v[178:181], v[26:29]
	v_mfma_f32_16x16x32_bf16 v[14:17], v[110:113], v[186:189], v[14:17]
	v_mfma_f32_16x16x32_bf16 v[10:13], v[122:125], v[186:189], v[10:13]
	v_mfma_f32_16x16x32_bf16 v[62:65], v[118:121], v[166:169], v[62:65]
	v_mfma_f32_16x16x32_bf16 v[58:61], v[134:137], v[166:169], v[58:61]
	v_mfma_f32_16x16x32_bf16 v[46:49], v[118:121], v[174:177], v[46:49]
	v_mfma_f32_16x16x32_bf16 v[42:45], v[134:137], v[174:177], v[42:45]
	v_mfma_f32_16x16x32_bf16 v[30:33], v[118:121], v[182:185], v[30:33]
	v_mfma_f32_16x16x32_bf16 v[26:29], v[134:137], v[182:185], v[26:29]
	v_mfma_f32_16x16x32_bf16 v[14:17], v[118:121], v[210:213], v[14:17]
	v_mfma_f32_16x16x32_bf16 v[10:13], v[134:137], v[210:213], v[10:13]
	v_mfma_f32_16x16x32_bf16 v[54:57], v[138:141], v[162:165], v[54:57]
	v_mfma_f32_16x16x32_bf16 v[50:53], v[146:149], v[162:165], v[50:53]
	v_mfma_f32_16x16x32_bf16 v[38:41], v[138:141], v[170:173], v[38:41]
	v_mfma_f32_16x16x32_bf16 v[34:37], v[146:149], v[170:173], v[34:37]
	v_mfma_f32_16x16x32_bf16 v[22:25], v[138:141], v[178:181], v[22:25]
	v_mfma_f32_16x16x32_bf16 v[18:21], v[146:149], v[178:181], v[18:21]
	v_mfma_f32_16x16x32_bf16 v[6:9], v[138:141], v[186:189], v[6:9]
	v_mfma_f32_16x16x32_bf16 v[2:5], v[146:149], v[186:189], v[2:5]
	v_mfma_f32_16x16x32_bf16 v[54:57], v[142:145], v[166:169], v[54:57]
	v_mfma_f32_16x16x32_bf16 v[50:53], v[154:157], v[166:169], v[50:53]
	v_mfma_f32_16x16x32_bf16 v[38:41], v[142:145], v[174:177], v[38:41]
	v_mfma_f32_16x16x32_bf16 v[34:37], v[154:157], v[174:177], v[34:37]
	v_mfma_f32_16x16x32_bf16 v[22:25], v[142:145], v[182:185], v[22:25]
	v_mfma_f32_16x16x32_bf16 v[18:21], v[154:157], v[182:185], v[18:21]
	v_mfma_f32_16x16x32_bf16 v[6:9], v[142:145], v[210:213], v[6:9]
	v_mfma_f32_16x16x32_bf16 v[2:5], v[154:157], v[210:213], v[2:5]
	s_setprio 0
	s_barrier
	s_add_i32 s52, s52, 2
	s_add_u32 s4, s4, 0x100
	s_addc_u32 s5, s5, 0
	s_add_u32 s50, s50, 0x100
	s_addc_u32 s51, s51, 0
	s_cmp_gt_u32 s52, 13
	s_cbranch_scc0 .LBB0_1096
	s_and_b64 vcc, exec, s[14:15]
	s_cbranch_vccz .LBB0_1099
	s_barrier

.LBB0_1180:
	s_add_u32 s26, s24, 0xfffc0080
	s_addc_u32 s27, s25, -1
	s_add_i32 s55, 0, 0x10000
	s_cmp_eq_u32 s54, 12
	s_cselect_b32 s29, s17, s27
	s_cselect_b32 s28, s50, s26
	v_add_u32_e32 v150, s55, v1
	s_cselect_b32 s27, s15, s53
	s_cselect_b32 s26, s51, s52
	s_add_i32 s58, 0, 0x14000
	ds_read_b128 v[142:145], v150
	ds_read_b128 v[146:149], v150 offset:1024
	ds_read_b128 v[154:157], v150 offset:2048
	ds_read_b128 v[158:161], v150 offset:3072
	v_add_u32_e32 v150, s58, v1
	ds_read_b128 v[162:165], v150
	ds_read_b128 v[166:169], v150 offset:1024
	ds_read_b128 v[170:173], v150 offset:2048
	ds_read_b128 v[174:177], v150 offset:3072
	v_lshl_add_u64 v[150:151], s[24:25], 0, v[138:139]
	s_add_i32 m0, s40, 0xc000
	ds_read_b128 v[178:181], v152
	ds_read_b128 v[182:185], v152 offset:1024
	ds_read_b128 v[186:189], v152 offset:2048
	ds_read_b128 v[190:193], v152 offset:3072
	ds_read_b128 v[204:207], v152 offset:4096
	ds_read_b128 v[208:211], v152 offset:5120
	ds_read_b128 v[212:215], v152 offset:6144
	ds_read_b128 v[228:231], v152 offset:7168
	global_load_lds_dwordx4 v[150:151], off
	s_add_i32 m0, s40, 0xe000
	v_lshl_add_u64 v[150:151], s[24:25], 0, v[140:141]
	global_load_lds_dwordx4 v[150:151], off
	s_waitcnt vmcnt(8)
	s_waitcnt lgkmcnt(0)
	s_barrier
	s_setprio 1
	s_waitcnt lgkmcnt(0)
	v_mfma_f32_16x16x32_bf16 v[126:129], v[142:145], v[178:181], v[126:129]
	v_mfma_f32_16x16x32_bf16 v[122:125], v[154:157], v[178:181], v[122:125]
	v_mfma_f32_16x16x32_bf16 v[110:113], v[142:145], v[186:189], v[110:113]
	v_mfma_f32_16x16x32_bf16 v[106:109], v[154:157], v[186:189], v[106:109]
	v_mfma_f32_16x16x32_bf16 v[94:97], v[142:145], v[204:207], v[94:97]
	v_mfma_f32_16x16x32_bf16 v[90:93], v[154:157], v[204:207], v[90:93]
	v_mfma_f32_16x16x32_bf16 v[78:81], v[142:145], v[212:215], v[78:81]
	v_mfma_f32_16x16x32_bf16 v[74:77], v[154:157], v[212:215], v[74:77]
	v_mfma_f32_16x16x32_bf16 v[126:129], v[146:149], v[182:185], v[126:129]
	v_mfma_f32_16x16x32_bf16 v[122:125], v[158:161], v[182:185], v[122:125]
	v_mfma_f32_16x16x32_bf16 v[110:113], v[146:149], v[190:193], v[110:113]
	v_mfma_f32_16x16x32_bf16 v[106:109], v[158:161], v[190:193], v[106:109]
	v_mfma_f32_16x16x32_bf16 v[94:97], v[146:149], v[208:211], v[94:97]
	v_mfma_f32_16x16x32_bf16 v[90:93], v[158:161], v[208:211], v[90:93]
	v_mfma_f32_16x16x32_bf16 v[78:81], v[146:149], v[228:231], v[78:81]
	v_mfma_f32_16x16x32_bf16 v[74:77], v[158:161], v[228:231], v[74:77]
	v_mfma_f32_16x16x32_bf16 v[118:121], v[162:165], v[178:181], v[118:121]
	v_mfma_f32_16x16x32_bf16 v[114:117], v[170:173], v[178:181], v[114:117]
	v_mfma_f32_16x16x32_bf16 v[102:105], v[162:165], v[186:189], v[102:105]
	v_mfma_f32_16x16x32_bf16 v[98:101], v[170:173], v[186:189], v[98:101]
	v_mfma_f32_16x16x32_bf16 v[86:89], v[162:165], v[204:207], v[86:89]
	v_mfma_f32_16x16x32_bf16 v[82:85], v[170:173], v[204:207], v[82:85]
	v_mfma_f32_16x16x32_bf16 v[70:73], v[162:165], v[212:215], v[70:73]
	v_mfma_f32_16x16x32_bf16 v[66:69], v[170:173], v[212:215], v[66:69]
	v_mfma_f32_16x16x32_bf16 v[118:121], v[166:169], v[182:185], v[118:121]
	v_mfma_f32_16x16x32_bf16 v[114:117], v[174:177], v[182:185], v[114:117]
	v_mfma_f32_16x16x32_bf16 v[102:105], v[166:169], v[190:193], v[102:105]
	v_mfma_f32_16x16x32_bf16 v[98:101], v[174:177], v[190:193], v[98:101]
	v_mfma_f32_16x16x32_bf16 v[86:89], v[166:169], v[208:211], v[86:89]
	v_mfma_f32_16x16x32_bf16 v[82:85], v[174:177], v[208:211], v[82:85]
	v_mfma_f32_16x16x32_bf16 v[70:73], v[166:169], v[228:231], v[70:73]
	v_mfma_f32_16x16x32_bf16 v[66:69], v[174:177], v[228:231], v[66:69]
	s_setprio 0
	s_barrier
	s_add_i32 s55, s55, s39
	v_lshl_add_u64 v[150:151], s[26:27], 0, v[134:135]
	s_mov_b32 m0, s55
	ds_read_b128 v[178:181], v152 offset:16384
	ds_read_b128 v[182:185], v152 offset:17408
	ds_read_b128 v[186:189], v152 offset:18432
	ds_read_b128 v[190:193], v152 offset:19456
	ds_read_b128 v[204:207], v152 offset:20480
	ds_read_b128 v[208:211], v152 offset:21504
	ds_read_b128 v[212:215], v152 offset:22528
	ds_read_b128 v[228:231], v152 offset:23552
	global_load_lds_dwordx4 v[150:151], off
	s_add_i32 m0, s55, 0x2000
	s_add_u32 s56, s26, 0x40000
	v_lshl_add_u64 v[194:195], s[26:27], 0, v[130:131]
	s_addc_u32 s57, s27, 0
	s_add_i32 s55, s58, s39
	global_load_lds_dwordx4 v[194:195], off
	v_lshl_add_u64 v[196:197], s[56:57], 0, v[134:135]
	s_mov_b32 m0, s55
	v_lshl_add_u64 v[198:199], s[28:29], 0, v[132:133]
	global_load_lds_dwordx4 v[196:197], off
	s_add_i32 m0, s55, 0x2000
	v_lshl_add_u64 v[196:197], s[56:57], 0, v[130:131]
	global_load_lds_dwordx4 v[196:197], off
	s_mov_b32 m0, s40
	v_lshl_add_u64 v[196:197], s[28:29], 0, v[136:137]
	global_load_lds_dwordx4 v[196:197], off
	s_mov_b32 m0, s41
	s_nop 0
	global_load_lds_dwordx4 v[198:199], off
	s_waitcnt vmcnt(8)
	s_waitcnt lgkmcnt(0)
	s_barrier
	s_setprio 1
	s_waitcnt lgkmcnt(0)
	v_mfma_f32_16x16x32_bf16 v[62:65], v[142:145], v[178:181], v[62:65]
	v_mfma_f32_16x16x32_bf16 v[58:61], v[154:157], v[178:181], v[58:61]
	v_mfma_f32_16x16x32_bf16 v[46:49], v[142:145], v[186:189], v[46:49]
	v_mfma_f32_16x16x32_bf16 v[42:45], v[154:157], v[186:189], v[42:45]
	v_mfma_f32_16x16x32_bf16 v[30:33], v[142:145], v[204:207], v[30:33]
	v_mfma_f32_16x16x32_bf16 v[26:29], v[154:157], v[204:207], v[26:29]
	v_mfma_f32_16x16x32_bf16 v[14:17], v[142:145], v[212:215], v[14:17]
	v_mfma_f32_16x16x32_bf16 v[10:13], v[154:157], v[212:215], v[10:13]
	v_mfma_f32_16x16x32_bf16 v[62:65], v[146:149], v[182:185], v[62:65]
	v_mfma_f32_16x16x32_bf16 v[58:61], v[158:161], v[182:185], v[58:61]
	v_mfma_f32_16x16x32_bf16 v[46:49], v[146:149], v[190:193], v[46:49]
	v_mfma_f32_16x16x32_bf16 v[42:45], v[158:161], v[190:193], v[42:45]
	v_mfma_f32_16x16x32_bf16 v[30:33], v[146:149], v[208:211], v[30:33]
	v_mfma_f32_16x16x32_bf16 v[26:29], v[158:161], v[208:211], v[26:29]
	v_mfma_f32_16x16x32_bf16 v[14:17], v[146:149], v[228:231], v[14:17]
	v_mfma_f32_16x16x32_bf16 v[10:13], v[158:161], v[228:231], v[10:13]
	v_mfma_f32_16x16x32_bf16 v[54:57], v[162:165], v[178:181], v[54:57]
	v_mfma_f32_16x16x32_bf16 v[50:53], v[170:173], v[178:181], v[50:53]
	v_mfma_f32_16x16x32_bf16 v[38:41], v[162:165], v[186:189], v[38:41]
	v_mfma_f32_16x16x32_bf16 v[34:37], v[170:173], v[186:189], v[34:37]
	v_mfma_f32_16x16x32_bf16 v[22:25], v[162:165], v[204:207], v[22:25]
	v_mfma_f32_16x16x32_bf16 v[18:21], v[170:173], v[204:207], v[18:21]
	v_mfma_f32_16x16x32_bf16 v[6:9], v[162:165], v[212:215], v[6:9]
	v_mfma_f32_16x16x32_bf16 v[2:5], v[170:173], v[212:215], v[2:5]
	v_mfma_f32_16x16x32_bf16 v[54:57], v[166:169], v[182:185], v[54:57]
	v_mfma_f32_16x16x32_bf16 v[50:53], v[174:177], v[182:185], v[50:53]
	v_mfma_f32_16x16x32_bf16 v[38:41], v[166:169], v[190:193], v[38:41]
	v_mfma_f32_16x16x32_bf16 v[34:37], v[174:177], v[190:193], v[34:37]
	v_mfma_f32_16x16x32_bf16 v[22:25], v[166:169], v[208:211], v[22:25]
	v_mfma_f32_16x16x32_bf16 v[18:21], v[174:177], v[208:211], v[18:21]
	v_mfma_f32_16x16x32_bf16 v[6:9], v[166:169], v[228:231], v[6:9]
	v_mfma_f32_16x16x32_bf16 v[2:5], v[174:177], v[228:231], v[2:5]
	s_setprio 0
	s_barrier
	s_add_i32 s55, 0, 0x18000
	v_add_u32_e32 v153, s55, v1
	s_add_i32 s56, 0, 0x1c000
	ds_read_b128 v[142:145], v153
	ds_read_b128 v[146:149], v153 offset:1024
	ds_read_b128 v[154:157], v153 offset:2048
	ds_read_b128 v[158:161], v153 offset:3072
	v_add_u32_e32 v153, s56, v1
	ds_read_b128 v[162:165], v153
	ds_read_b128 v[166:169], v153 offset:1024
	ds_read_b128 v[170:173], v153 offset:2048
	ds_read_b128 v[174:177], v153 offset:3072
	s_add_u32 s28, s28, 0x40000
	s_addc_u32 s29, s29, 0
	s_mov_b32 m0, s42
	v_lshl_add_u64 v[216:217], s[28:29], 0, v[136:137]
	ds_read_b128 v[178:181], v152 offset:32768
	ds_read_b128 v[182:185], v152 offset:33792
	ds_read_b128 v[186:189], v152 offset:34816
	ds_read_b128 v[190:193], v152 offset:35840
	ds_read_b128 v[204:207], v152 offset:36864
	ds_read_b128 v[208:211], v152 offset:37888
	ds_read_b128 v[212:215], v152 offset:38912
	ds_read_b128 v[228:231], v152 offset:39936
	global_load_lds_dwordx4 v[216:217], off
	s_mov_b32 m0, s43
	v_lshl_add_u64 v[216:217], s[28:29], 0, v[132:133]
	global_load_lds_dwordx4 v[216:217], off
	s_waitcnt vmcnt(8)
	s_waitcnt lgkmcnt(0)
	s_barrier
	s_setprio 1
	s_waitcnt lgkmcnt(0)
	v_mfma_f32_16x16x32_bf16 v[126:129], v[142:145], v[178:181], v[126:129]
	v_mfma_f32_16x16x32_bf16 v[122:125], v[154:157], v[178:181], v[122:125]
	v_mfma_f32_16x16x32_bf16 v[110:113], v[142:145], v[186:189], v[110:113]
	v_mfma_f32_16x16x32_bf16 v[106:109], v[154:157], v[186:189], v[106:109]
	v_mfma_f32_16x16x32_bf16 v[94:97], v[142:145], v[204:207], v[94:97]
	v_mfma_f32_16x16x32_bf16 v[90:93], v[154:157], v[204:207], v[90:93]
	v_mfma_f32_16x16x32_bf16 v[78:81], v[142:145], v[212:215], v[78:81]
	v_mfma_f32_16x16x32_bf16 v[74:77], v[154:157], v[212:215], v[74:77]
	v_mfma_f32_16x16x32_bf16 v[126:129], v[146:149], v[182:185], v[126:129]
	v_mfma_f32_16x16x32_bf16 v[122:125], v[158:161], v[182:185], v[122:125]
	v_mfma_f32_16x16x32_bf16 v[110:113], v[146:149], v[190:193], v[110:113]
	v_mfma_f32_16x16x32_bf16 v[106:109], v[158:161], v[190:193], v[106:109]
	v_mfma_f32_16x16x32_bf16 v[94:97], v[146:149], v[208:211], v[94:97]
	v_mfma_f32_16x16x32_bf16 v[90:93], v[158:161], v[208:211], v[90:93]
	v_mfma_f32_16x16x32_bf16 v[78:81], v[146:149], v[228:231], v[78:81]
	v_mfma_f32_16x16x32_bf16 v[74:77], v[158:161], v[228:231], v[74:77]
	v_mfma_f32_16x16x32_bf16 v[118:121], v[162:165], v[178:181], v[118:121]
	v_mfma_f32_16x16x32_bf16 v[114:117], v[170:173], v[178:181], v[114:117]
	v_mfma_f32_16x16x32_bf16 v[102:105], v[162:165], v[186:189], v[102:105]
	v_mfma_f32_16x16x32_bf16 v[98:101], v[170:173], v[186:189], v[98:101]
	v_mfma_f32_16x16x32_bf16 v[86:89], v[162:165], v[204:207], v[86:89]
	v_mfma_f32_16x16x32_bf16 v[82:85], v[170:173], v[204:207], v[82:85]
	v_mfma_f32_16x16x32_bf16 v[70:73], v[162:165], v[212:215], v[70:73]
	v_mfma_f32_16x16x32_bf16 v[66:69], v[170:173], v[212:215], v[66:69]
	v_mfma_f32_16x16x32_bf16 v[118:121], v[166:169], v[182:185], v[118:121]
	v_mfma_f32_16x16x32_bf16 v[114:117], v[174:177], v[182:185], v[114:117]
	v_mfma_f32_16x16x32_bf16 v[102:105], v[166:169], v[190:193], v[102:105]
	v_mfma_f32_16x16x32_bf16 v[98:101], v[174:177], v[190:193], v[98:101]
	v_mfma_f32_16x16x32_bf16 v[86:89], v[166:169], v[208:211], v[86:89]
	v_mfma_f32_16x16x32_bf16 v[82:85], v[174:177], v[208:211], v[82:85]
	v_mfma_f32_16x16x32_bf16 v[70:73], v[166:169], v[228:231], v[70:73]
	v_mfma_f32_16x16x32_bf16 v[66:69], v[174:177], v[228:231], v[66:69]
	s_setprio 0
	s_barrier
	s_add_i32 s28, s55, s39
	v_lshl_add_u64 v[150:151], v[150:151], 0, s[94:95]
	s_mov_b32 m0, s28
	ds_read_b128 v[178:181], v152 offset:49152
	ds_read_b128 v[182:185], v152 offset:50176
	ds_read_b128 v[186:189], v152 offset:51200
	ds_read_b128 v[190:193], v152 offset:52224
	ds_read_b128 v[204:207], v152 offset:53248
	ds_read_b128 v[208:211], v152 offset:54272
	ds_read_b128 v[212:215], v152 offset:55296
	ds_read_b128 v[228:231], v152 offset:56320
	global_load_lds_dwordx4 v[150:151], off
	s_add_i32 m0, s28, 0x2000
	s_add_u32 s26, s26, 0x40080
	v_lshl_add_u64 v[150:151], v[194:195], 0, s[94:95]
	s_addc_u32 s27, s27, 0
	s_add_i32 s28, s56, s39
	global_load_lds_dwordx4 v[150:151], off
	s_mov_b32 m0, s28
	v_lshl_add_u64 v[150:151], s[26:27], 0, v[134:135]
	global_load_lds_dwordx4 v[150:151], off
	s_add_i32 m0, s28, 0x2000
	v_lshl_add_u64 v[150:151], s[26:27], 0, v[130:131]
	global_load_lds_dwordx4 v[150:151], off
	s_mov_b32 m0, s47
	v_lshl_add_u64 v[150:151], v[196:197], 0, s[94:95]
	global_load_lds_dwordx4 v[150:151], off
	s_mov_b32 m0, s48
	v_lshl_add_u64 v[150:151], v[198:199], 0, s[94:95]
	global_load_lds_dwordx4 v[150:151], off
	s_waitcnt vmcnt(8)
	s_waitcnt lgkmcnt(0)
	s_barrier
	s_setprio 1
	s_waitcnt lgkmcnt(0)
	v_mfma_f32_16x16x32_bf16 v[62:65], v[142:145], v[178:181], v[62:65]
	v_mfma_f32_16x16x32_bf16 v[58:61], v[154:157], v[178:181], v[58:61]
	v_mfma_f32_16x16x32_bf16 v[46:49], v[142:145], v[186:189], v[46:49]
	v_mfma_f32_16x16x32_bf16 v[42:45], v[154:157], v[186:189], v[42:45]
	v_mfma_f32_16x16x32_bf16 v[30:33], v[142:145], v[204:207], v[30:33]
	v_mfma_f32_16x16x32_bf16 v[26:29], v[154:157], v[204:207], v[26:29]
	v_mfma_f32_16x16x32_bf16 v[14:17], v[142:145], v[212:215], v[14:17]
	v_mfma_f32_16x16x32_bf16 v[10:13], v[154:157], v[212:215], v[10:13]
	v_mfma_f32_16x16x32_bf16 v[62:65], v[146:149], v[182:185], v[62:65]
	v_mfma_f32_16x16x32_bf16 v[58:61], v[158:161], v[182:185], v[58:61]
	v_mfma_f32_16x16x32_bf16 v[46:49], v[146:149], v[190:193], v[46:49]
	v_mfma_f32_16x16x32_bf16 v[42:45], v[158:161], v[190:193], v[42:45]
	v_mfma_f32_16x16x32_bf16 v[30:33], v[146:149], v[208:211], v[30:33]
	v_mfma_f32_16x16x32_bf16 v[26:29], v[158:161], v[208:211], v[26:29]
	v_mfma_f32_16x16x32_bf16 v[14:17], v[146:149], v[228:231], v[14:17]
	v_mfma_f32_16x16x32_bf16 v[10:13], v[158:161], v[228:231], v[10:13]
	v_mfma_f32_16x16x32_bf16 v[54:57], v[162:165], v[178:181], v[54:57]
	v_mfma_f32_16x16x32_bf16 v[50:53], v[170:173], v[178:181], v[50:53]
	v_mfma_f32_16x16x32_bf16 v[38:41], v[162:165], v[186:189], v[38:41]
	v_mfma_f32_16x16x32_bf16 v[34:37], v[170:173], v[186:189], v[34:37]
	v_mfma_f32_16x16x32_bf16 v[22:25], v[162:165], v[204:207], v[22:25]
	v_mfma_f32_16x16x32_bf16 v[18:21], v[170:173], v[204:207], v[18:21]
	v_mfma_f32_16x16x32_bf16 v[6:9], v[162:165], v[212:215], v[6:9]
	v_mfma_f32_16x16x32_bf16 v[2:5], v[170:173], v[212:215], v[2:5]
	v_mfma_f32_16x16x32_bf16 v[54:57], v[166:169], v[182:185], v[54:57]
	v_mfma_f32_16x16x32_bf16 v[50:53], v[174:177], v[182:185], v[50:53]
	v_mfma_f32_16x16x32_bf16 v[38:41], v[166:169], v[190:193], v[38:41]
	v_mfma_f32_16x16x32_bf16 v[34:37], v[174:177], v[190:193], v[34:37]
	v_mfma_f32_16x16x32_bf16 v[22:25], v[166:169], v[208:211], v[22:25]
	v_mfma_f32_16x16x32_bf16 v[18:21], v[174:177], v[208:211], v[18:21]
	v_mfma_f32_16x16x32_bf16 v[6:9], v[166:169], v[228:231], v[6:9]
	v_mfma_f32_16x16x32_bf16 v[2:5], v[174:177], v[228:231], v[2:5]
	s_setprio 0
	s_barrier
	s_add_i32 s54, s54, 2
	s_add_u32 s24, s24, 0x100
	s_addc_u32 s25, s25, 0
	s_add_u32 s52, s52, 0x100
	s_addc_u32 s53, s53, 0
	s_cmp_gt_u32 s54, 13
	s_cbranch_scc0 .LBB0_1180
	s_and_b64 vcc, exec, s[12:13]
	s_cbranch_vccz .LBB0_1183
	s_barrier

.LBB0_1263:
	s_add_u32 s20, s18, 0x100
	s_addc_u32 s21, s19, 0
	s_add_i32 s53, 0, 0x10000
	s_cmp_eq_u32 s52, 40
	s_cselect_b32 s25, s5, s21
	s_cselect_b32 s24, s4, s20
	s_cselect_b32 s23, s17, s51
	s_cselect_b32 s22, s16, s50
	s_add_i32 s54, 0, 0x14000
	v_add_u32_e32 v134, s53, v1
	v_add_u32_e32 v154, s54, v1
	ds_read_b128 v[110:113], v134
	ds_read_b128 v[118:121], v134 offset:1024
	ds_read_b128 v[122:125], v134 offset:2048
	ds_read_b128 v[134:137], v134 offset:3072
	ds_read_b128 v[138:141], v154
	ds_read_b128 v[142:145], v154 offset:1024
	ds_read_b128 v[146:149], v154 offset:2048
	ds_read_b128 v[154:157], v154 offset:3072
	v_lshl_add_u64 v[196:197], s[18:19], 0, v[206:207]
	s_add_i32 m0, s35, 0xc000
	ds_read_b128 v[162:165], v214
	ds_read_b128 v[166:169], v214 offset:1024
	ds_read_b128 v[170:173], v214 offset:2048
	ds_read_b128 v[174:177], v214 offset:3072
	ds_read_b128 v[178:181], v214 offset:4096
	ds_read_b128 v[182:185], v214 offset:5120
	ds_read_b128 v[186:189], v214 offset:6144
	ds_read_b128 v[210:213], v214 offset:7168
	global_load_lds_dwordx4 v[196:197], off
	s_add_i32 m0, s35, 0xe000
	v_lshl_add_u64 v[196:197], s[18:19], 0, v[208:209]
	global_load_lds_dwordx4 v[196:197], off
	s_waitcnt vmcnt(8)
	s_waitcnt lgkmcnt(0)
	s_barrier
	s_setprio 1
	s_waitcnt lgkmcnt(0)
	v_mfma_f32_16x16x32_bf16 v[158:161], v[110:113], v[162:165], v[158:161]
	v_mfma_f32_16x16x32_bf16 v[150:153], v[122:125], v[162:165], v[150:153]
	v_mfma_f32_16x16x32_bf16 v[114:117], v[110:113], v[170:173], v[114:117]
	v_mfma_f32_16x16x32_bf16 v[106:109], v[122:125], v[170:173], v[106:109]
	v_mfma_f32_16x16x32_bf16 v[94:97], v[110:113], v[178:181], v[94:97]
	v_mfma_f32_16x16x32_bf16 v[90:93], v[122:125], v[178:181], v[90:93]
	v_mfma_f32_16x16x32_bf16 v[78:81], v[110:113], v[186:189], v[78:81]
	v_mfma_f32_16x16x32_bf16 v[74:77], v[122:125], v[186:189], v[74:77]
	v_mfma_f32_16x16x32_bf16 v[158:161], v[118:121], v[166:169], v[158:161]
	v_mfma_f32_16x16x32_bf16 v[150:153], v[134:137], v[166:169], v[150:153]
	v_mfma_f32_16x16x32_bf16 v[114:117], v[118:121], v[174:177], v[114:117]
	v_mfma_f32_16x16x32_bf16 v[106:109], v[134:137], v[174:177], v[106:109]
	v_mfma_f32_16x16x32_bf16 v[94:97], v[118:121], v[182:185], v[94:97]
	v_mfma_f32_16x16x32_bf16 v[90:93], v[134:137], v[182:185], v[90:93]
	v_mfma_f32_16x16x32_bf16 v[78:81], v[118:121], v[210:213], v[78:81]
	v_mfma_f32_16x16x32_bf16 v[74:77], v[134:137], v[210:213], v[74:77]
	v_mfma_f32_16x16x32_bf16 v[130:133], v[138:141], v[162:165], v[130:133]
	v_mfma_f32_16x16x32_bf16 v[126:129], v[146:149], v[162:165], v[126:129]
	v_mfma_f32_16x16x32_bf16 v[102:105], v[138:141], v[170:173], v[102:105]
	v_mfma_f32_16x16x32_bf16 v[98:101], v[146:149], v[170:173], v[98:101]
	v_mfma_f32_16x16x32_bf16 v[86:89], v[138:141], v[178:181], v[86:89]
	v_mfma_f32_16x16x32_bf16 v[82:85], v[146:149], v[178:181], v[82:85]
	v_mfma_f32_16x16x32_bf16 v[70:73], v[138:141], v[186:189], v[70:73]
	v_mfma_f32_16x16x32_bf16 v[66:69], v[146:149], v[186:189], v[66:69]
	v_mfma_f32_16x16x32_bf16 v[130:133], v[142:145], v[166:169], v[130:133]
	v_mfma_f32_16x16x32_bf16 v[126:129], v[154:157], v[166:169], v[126:129]
	v_mfma_f32_16x16x32_bf16 v[102:105], v[142:145], v[174:177], v[102:105]
	v_mfma_f32_16x16x32_bf16 v[98:101], v[154:157], v[174:177], v[98:101]
	v_mfma_f32_16x16x32_bf16 v[86:89], v[142:145], v[182:185], v[86:89]
	v_mfma_f32_16x16x32_bf16 v[82:85], v[154:157], v[182:185], v[82:85]
	v_mfma_f32_16x16x32_bf16 v[70:73], v[142:145], v[210:213], v[70:73]
	v_mfma_f32_16x16x32_bf16 v[66:69], v[154:157], v[210:213], v[66:69]
	s_setprio 0
	s_barrier
	s_add_i32 s18, s53, s34
	v_lshl_add_u64 v[196:197], s[22:23], 0, v[192:193]
	s_mov_b32 m0, s18
	ds_read_b128 v[162:165], v214 offset:16384
	ds_read_b128 v[166:169], v214 offset:17408
	ds_read_b128 v[170:173], v214 offset:18432
	ds_read_b128 v[174:177], v214 offset:19456
	ds_read_b128 v[178:181], v214 offset:20480
	ds_read_b128 v[182:185], v214 offset:21504
	ds_read_b128 v[186:189], v214 offset:22528
	ds_read_b128 v[210:213], v214 offset:23552
	global_load_lds_dwordx4 v[196:197], off
	s_add_i32 m0, s18, 0x2000
	s_add_u32 s18, s22, 0xb0000
	v_lshl_add_u64 v[198:199], s[22:23], 0, v[204:205]
	s_addc_u32 s19, s23, 0
	s_add_i32 s53, s54, s34
	global_load_lds_dwordx4 v[198:199], off
	v_lshl_add_u64 v[216:217], s[18:19], 0, v[192:193]
	s_mov_b32 m0, s53
	v_lshl_add_u64 v[220:221], s[24:25], 0, v[194:195]
	global_load_lds_dwordx4 v[216:217], off
	s_add_i32 m0, s53, 0x2000
	v_lshl_add_u64 v[216:217], s[18:19], 0, v[204:205]
	global_load_lds_dwordx4 v[216:217], off
	s_mov_b32 m0, s35
	v_lshl_add_u64 v[216:217], s[24:25], 0, v[190:191]
	global_load_lds_dwordx4 v[216:217], off
	s_mov_b32 m0, s36
	s_nop 0
	global_load_lds_dwordx4 v[220:221], off
	s_waitcnt vmcnt(8)
	s_waitcnt lgkmcnt(0)
	s_barrier
	s_setprio 1
	s_waitcnt lgkmcnt(0)
	v_mfma_f32_16x16x32_bf16 v[62:65], v[110:113], v[162:165], v[62:65]
	v_mfma_f32_16x16x32_bf16 v[58:61], v[122:125], v[162:165], v[58:61]
	v_mfma_f32_16x16x32_bf16 v[46:49], v[110:113], v[170:173], v[46:49]
	v_mfma_f32_16x16x32_bf16 v[42:45], v[122:125], v[170:173], v[42:45]
	v_mfma_f32_16x16x32_bf16 v[30:33], v[110:113], v[178:181], v[30:33]
	v_mfma_f32_16x16x32_bf16 v[26:29], v[122:125], v[178:181], v[26:29]
	v_mfma_f32_16x16x32_bf16 v[14:17], v[110:113], v[186:189], v[14:17]
	v_mfma_f32_16x16x32_bf16 v[10:13], v[122:125], v[186:189], v[10:13]
	v_mfma_f32_16x16x32_bf16 v[62:65], v[118:121], v[166:169], v[62:65]
	v_mfma_f32_16x16x32_bf16 v[58:61], v[134:137], v[166:169], v[58:61]
	v_mfma_f32_16x16x32_bf16 v[46:49], v[118:121], v[174:177], v[46:49]
	v_mfma_f32_16x16x32_bf16 v[42:45], v[134:137], v[174:177], v[42:45]
	v_mfma_f32_16x16x32_bf16 v[30:33], v[118:121], v[182:185], v[30:33]
	v_mfma_f32_16x16x32_bf16 v[26:29], v[134:137], v[182:185], v[26:29]
	v_mfma_f32_16x16x32_bf16 v[14:17], v[118:121], v[210:213], v[14:17]
	v_mfma_f32_16x16x32_bf16 v[10:13], v[134:137], v[210:213], v[10:13]
	v_mfma_f32_16x16x32_bf16 v[54:57], v[138:141], v[162:165], v[54:57]
	v_mfma_f32_16x16x32_bf16 v[50:53], v[146:149], v[162:165], v[50:53]
	v_mfma_f32_16x16x32_bf16 v[38:41], v[138:141], v[170:173], v[38:41]
	v_mfma_f32_16x16x32_bf16 v[34:37], v[146:149], v[170:173], v[34:37]
	v_mfma_f32_16x16x32_bf16 v[22:25], v[138:141], v[178:181], v[22:25]
	v_mfma_f32_16x16x32_bf16 v[18:21], v[146:149], v[178:181], v[18:21]
	v_mfma_f32_16x16x32_bf16 v[6:9], v[138:141], v[186:189], v[6:9]
	v_mfma_f32_16x16x32_bf16 v[2:5], v[146:149], v[186:189], v[2:5]
	v_mfma_f32_16x16x32_bf16 v[54:57], v[142:145], v[166:169], v[54:57]
	v_mfma_f32_16x16x32_bf16 v[50:53], v[154:157], v[166:169], v[50:53]
	v_mfma_f32_16x16x32_bf16 v[38:41], v[142:145], v[174:177], v[38:41]
	v_mfma_f32_16x16x32_bf16 v[34:37], v[154:157], v[174:177], v[34:37]
	v_mfma_f32_16x16x32_bf16 v[22:25], v[142:145], v[182:185], v[22:25]
	v_mfma_f32_16x16x32_bf16 v[18:21], v[154:157], v[182:185], v[18:21]
	v_mfma_f32_16x16x32_bf16 v[6:9], v[142:145], v[210:213], v[6:9]
	v_mfma_f32_16x16x32_bf16 v[2:5], v[154:157], v[210:213], v[2:5]
	s_setprio 0
	s_barrier
	s_add_i32 s53, 0, 0x18000
	s_add_i32 s54, 0, 0x1c000
	v_add_u32_e32 v134, s53, v1
	v_add_u32_e32 v154, s54, v1
	ds_read_b128 v[110:113], v134
	ds_read_b128 v[118:121], v134 offset:1024
	ds_read_b128 v[122:125], v134 offset:2048
	ds_read_b128 v[134:137], v134 offset:3072
	ds_read_b128 v[138:141], v154
	ds_read_b128 v[142:145], v154 offset:1024
	ds_read_b128 v[146:149], v154 offset:2048
	ds_read_b128 v[154:157], v154 offset:3072
	s_add_u32 s18, s24, 0xb0000
	s_addc_u32 s19, s25, 0
	s_mov_b32 m0, s37
	v_lshl_add_u64 v[222:223], s[18:19], 0, v[190:191]
	ds_read_b128 v[162:165], v214 offset:32768
	ds_read_b128 v[166:169], v214 offset:33792
	ds_read_b128 v[170:173], v214 offset:34816
	ds_read_b128 v[174:177], v214 offset:35840
	ds_read_b128 v[178:181], v214 offset:36864
	ds_read_b128 v[182:185], v214 offset:37888
	ds_read_b128 v[186:189], v214 offset:38912
	ds_read_b128 v[210:213], v214 offset:39936
	global_load_lds_dwordx4 v[222:223], off
	s_mov_b32 m0, s38
	v_lshl_add_u64 v[222:223], s[18:19], 0, v[194:195]
	global_load_lds_dwordx4 v[222:223], off
	s_waitcnt vmcnt(8)
	s_waitcnt lgkmcnt(0)
	s_barrier
	s_setprio 1
	s_waitcnt lgkmcnt(0)
	v_mfma_f32_16x16x32_bf16 v[158:161], v[110:113], v[162:165], v[158:161]
	v_mfma_f32_16x16x32_bf16 v[150:153], v[122:125], v[162:165], v[150:153]
	v_mfma_f32_16x16x32_bf16 v[114:117], v[110:113], v[170:173], v[114:117]
	v_mfma_f32_16x16x32_bf16 v[106:109], v[122:125], v[170:173], v[106:109]
	v_mfma_f32_16x16x32_bf16 v[94:97], v[110:113], v[178:181], v[94:97]
	v_mfma_f32_16x16x32_bf16 v[90:93], v[122:125], v[178:181], v[90:93]
	v_mfma_f32_16x16x32_bf16 v[78:81], v[110:113], v[186:189], v[78:81]
	v_mfma_f32_16x16x32_bf16 v[74:77], v[122:125], v[186:189], v[74:77]
	v_mfma_f32_16x16x32_bf16 v[158:161], v[118:121], v[166:169], v[158:161]
	v_mfma_f32_16x16x32_bf16 v[150:153], v[134:137], v[166:169], v[150:153]
	v_mfma_f32_16x16x32_bf16 v[114:117], v[118:121], v[174:177], v[114:117]
	v_mfma_f32_16x16x32_bf16 v[106:109], v[134:137], v[174:177], v[106:109]
	v_mfma_f32_16x16x32_bf16 v[94:97], v[118:121], v[182:185], v[94:97]
	v_mfma_f32_16x16x32_bf16 v[90:93], v[134:137], v[182:185], v[90:93]
	v_mfma_f32_16x16x32_bf16 v[78:81], v[118:121], v[210:213], v[78:81]
	v_mfma_f32_16x16x32_bf16 v[74:77], v[134:137], v[210:213], v[74:77]
	v_mfma_f32_16x16x32_bf16 v[130:133], v[138:141], v[162:165], v[130:133]
	v_mfma_f32_16x16x32_bf16 v[126:129], v[146:149], v[162:165], v[126:129]
	v_mfma_f32_16x16x32_bf16 v[102:105], v[138:141], v[170:173], v[102:105]
	v_mfma_f32_16x16x32_bf16 v[98:101], v[146:149], v[170:173], v[98:101]
	v_mfma_f32_16x16x32_bf16 v[86:89], v[138:141], v[178:181], v[86:89]
	v_mfma_f32_16x16x32_bf16 v[82:85], v[146:149], v[178:181], v[82:85]
	v_mfma_f32_16x16x32_bf16 v[70:73], v[138:141], v[186:189], v[70:73]
	v_mfma_f32_16x16x32_bf16 v[66:69], v[146:149], v[186:189], v[66:69]
	v_mfma_f32_16x16x32_bf16 v[130:133], v[142:145], v[166:169], v[130:133]
	v_mfma_f32_16x16x32_bf16 v[126:129], v[154:157], v[166:169], v[126:129]
	v_mfma_f32_16x16x32_bf16 v[102:105], v[142:145], v[174:177], v[102:105]
	v_mfma_f32_16x16x32_bf16 v[98:101], v[154:157], v[174:177], v[98:101]
	v_mfma_f32_16x16x32_bf16 v[86:89], v[142:145], v[182:185], v[86:89]
	v_mfma_f32_16x16x32_bf16 v[82:85], v[154:157], v[182:185], v[82:85]
	v_mfma_f32_16x16x32_bf16 v[70:73], v[142:145], v[210:213], v[70:73]
	v_mfma_f32_16x16x32_bf16 v[66:69], v[154:157], v[210:213], v[66:69]
	s_setprio 0
	s_barrier
	s_add_i32 s18, s53, s34
	v_lshl_add_u64 v[196:197], v[196:197], 0, s[94:95]
	s_mov_b32 m0, s18
	ds_read_b128 v[162:165], v214 offset:49152
	ds_read_b128 v[166:169], v214 offset:50176
	ds_read_b128 v[170:173], v214 offset:51200
	ds_read_b128 v[174:177], v214 offset:52224
	ds_read_b128 v[178:181], v214 offset:53248
	ds_read_b128 v[182:185], v214 offset:54272
	ds_read_b128 v[186:189], v214 offset:55296
	ds_read_b128 v[210:213], v214 offset:56320
	global_load_lds_dwordx4 v[196:197], off
	s_add_i32 m0, s18, 0x2000
	s_add_u32 s18, s22, 0xb0080
	v_lshl_add_u64 v[196:197], v[198:199], 0, s[94:95]
	s_addc_u32 s19, s23, 0
	s_add_i32 s22, s54, s34
	global_load_lds_dwordx4 v[196:197], off
	s_mov_b32 m0, s22
	v_lshl_add_u64 v[196:197], s[18:19], 0, v[192:193]
	global_load_lds_dwordx4 v[196:197], off
	s_add_i32 m0, s22, 0x2000
	v_lshl_add_u64 v[196:197], s[18:19], 0, v[204:205]
	global_load_lds_dwordx4 v[196:197], off
	s_mov_b32 m0, s41
	v_lshl_add_u64 v[196:197], v[216:217], 0, s[94:95]
	global_load_lds_dwordx4 v[196:197], off
	s_mov_b32 m0, s42
	v_lshl_add_u64 v[196:197], v[220:221], 0, s[94:95]
	global_load_lds_dwordx4 v[196:197], off
	s_waitcnt vmcnt(8)
	s_waitcnt lgkmcnt(0)
	s_barrier
	s_setprio 1
	s_waitcnt lgkmcnt(0)
	v_mfma_f32_16x16x32_bf16 v[62:65], v[110:113], v[162:165], v[62:65]
	v_mfma_f32_16x16x32_bf16 v[58:61], v[122:125], v[162:165], v[58:61]
	v_mfma_f32_16x16x32_bf16 v[46:49], v[110:113], v[170:173], v[46:49]
	v_mfma_f32_16x16x32_bf16 v[42:45], v[122:125], v[170:173], v[42:45]
	v_mfma_f32_16x16x32_bf16 v[30:33], v[110:113], v[178:181], v[30:33]
	v_mfma_f32_16x16x32_bf16 v[26:29], v[122:125], v[178:181], v[26:29]
	v_mfma_f32_16x16x32_bf16 v[14:17], v[110:113], v[186:189], v[14:17]
	v_mfma_f32_16x16x32_bf16 v[10:13], v[122:125], v[186:189], v[10:13]
	v_mfma_f32_16x16x32_bf16 v[62:65], v[118:121], v[166:169], v[62:65]
	v_mfma_f32_16x16x32_bf16 v[58:61], v[134:137], v[166:169], v[58:61]
	v_mfma_f32_16x16x32_bf16 v[46:49], v[118:121], v[174:177], v[46:49]
	v_mfma_f32_16x16x32_bf16 v[42:45], v[134:137], v[174:177], v[42:45]
	v_mfma_f32_16x16x32_bf16 v[30:33], v[118:121], v[182:185], v[30:33]
	v_mfma_f32_16x16x32_bf16 v[26:29], v[134:137], v[182:185], v[26:29]
	v_mfma_f32_16x16x32_bf16 v[14:17], v[118:121], v[210:213], v[14:17]
	v_mfma_f32_16x16x32_bf16 v[10:13], v[134:137], v[210:213], v[10:13]
	v_mfma_f32_16x16x32_bf16 v[54:57], v[138:141], v[162:165], v[54:57]
	v_mfma_f32_16x16x32_bf16 v[50:53], v[146:149], v[162:165], v[50:53]
	v_mfma_f32_16x16x32_bf16 v[38:41], v[138:141], v[170:173], v[38:41]
	v_mfma_f32_16x16x32_bf16 v[34:37], v[146:149], v[170:173], v[34:37]
	v_mfma_f32_16x16x32_bf16 v[22:25], v[138:141], v[178:181], v[22:25]
	v_mfma_f32_16x16x32_bf16 v[18:21], v[146:149], v[178:181], v[18:21]
	v_mfma_f32_16x16x32_bf16 v[6:9], v[138:141], v[186:189], v[6:9]
	v_mfma_f32_16x16x32_bf16 v[2:5], v[146:149], v[186:189], v[2:5]
	v_mfma_f32_16x16x32_bf16 v[54:57], v[142:145], v[166:169], v[54:57]
	v_mfma_f32_16x16x32_bf16 v[50:53], v[154:157], v[166:169], v[50:53]
	v_mfma_f32_16x16x32_bf16 v[38:41], v[142:145], v[174:177], v[38:41]
	v_mfma_f32_16x16x32_bf16 v[34:37], v[154:157], v[174:177], v[34:37]
	v_mfma_f32_16x16x32_bf16 v[22:25], v[142:145], v[182:185], v[22:25]
	v_mfma_f32_16x16x32_bf16 v[18:21], v[154:157], v[182:185], v[18:21]
	v_mfma_f32_16x16x32_bf16 v[6:9], v[142:145], v[210:213], v[6:9]
	v_mfma_f32_16x16x32_bf16 v[2:5], v[154:157], v[210:213], v[2:5]
	s_setprio 0
	s_barrier
	s_add_i32 s52, s52, 2
	s_add_u32 s50, s50, 0x100
	s_addc_u32 s51, s51, 0
	s_cmp_gt_u32 s52, 41
	s_mov_b64 s[18:19], s[20:21]
	s_cbranch_scc0 .LBB0_1263
	s_and_b64 vcc, exec, s[14:15]
	s_cbranch_vccz .LBB0_1266
	s_barrier
